# back-edge rotation (7.11) on all 9 GEMM K-loops: loop-counter/pointer SALU moved ahead of the loop-back s_barrier
# baseline (speedup 1.0000x reference)
; #define PG8_STAGE(bufoff, gbase, voff) do { _Pragma("unroll") for (int _i = 0; _i < 2; ++_i) \
;         __builtin_amdgcn_global_load_lds((const unsigned*)((const char*)(gbase) + (voff)[_i]), (PG8_LAS unsigned*)(lds + (bufoff) + ldsw + _i * 8192), 16, 0, 0); } while (0)
; #define PG8_LDA(dst, b, h) do { _Pragma("unroll") for (int m = 0; m < 4; ++m) _Pragma("unroll") for (int k = 0; k < 2; ++k) dst[m][k] = *(const PG8_LAS bf16x8*)(lds + PG8_SA(b, h) + aoff + m * 2048 + k * 1024); } while (0)
; #define PG8_LDB(dst, b, h) do { _Pragma("unroll") for (int n = 0; n < 2; ++n) _Pragma("unroll") for (int k = 0; k < 2; ++k) dst[n][k] = *(const PG8_LAS bf16x8*)(lds + PG8_SB(b, h) + boff + n * 2048 + k * 1024); } while (0)
; #define PG8_MMA(ai, bj, At, Bt) do { __builtin_amdgcn_s_setprio(1); _Pragma("unroll") for (int m = 0; m < 4; ++m) _Pragma("unroll") for (int n = 0; n < 2; ++n) _Pragma("unroll") for (int k = 0; k < 2; ++k) \
;         acc[ai][bj][m][n] = __builtin_amdgcn_mfma_f32_16x16x32_bf16(Bt[n][k], At[m][k], acc[ai][bj][m][n], 0, 0, 0); __builtin_amdgcn_s_setprio(0); } while (0)
; #define PG8_WAIT_V(n) asm volatile("s_waitcnt vmcnt(" #n ")" ::: "memory")
; #define PG8_BAR __builtin_amdgcn_s_barrier()
; template <class Epi, class Sched, bool ALIGN_EPI = false, bool SP2 = false>
; __device__ __forceinline__ void gemm_phase(PG8_LAS unsigned char* lds, const Gemm g, const Sched& S, const Epi& E) {
;     ...
;         for (int t = 0; t < nt; t += 2) {
;             const bool last = (t == nt - 2);
;             const char* a1 = cA + (size_t)(t + 1) * kstep;
;             const char* a2 = last ? nA : cA + (size_t)(t + 2) * kstep; const char* b2 = last ? nB : cB + (size_t)(t + 2) * kstep;
;             const char* a3 = a2 + kstep; const char* b3 = b2 + kstep;
;             if (last && has_next) S.a_ready(nxt);
;             if constexpr (SP2) {
;             PG8_LDB(B0, 0, 0); PG8_LDB(B1, 0, 1); PG8_SCHED; PG8_LDA(At, 0, 0); PG8_STAGE(PG8_SA(1, 1), a1 + hstep, voffA);
;             PG8_WAIT_V(8); PG8_WAIT_L(0); PG8_BAR; PG8_MMA(0, 0, At, B0); PG8_MMA(0, 1, At, B1); PG8_BAR; PG8_SCHED;
;             PG8_LDA(At, 0, 1); PG8_STAGE(PG8_SB(0, 0), b2, voffB); PG8_STAGE(PG8_SB(0, 1), b2 + hstep, voffB); PG8_STAGE(PG8_SA(0, 0), a2, voffA);
;             PG8_WAIT_V(8); PG8_WAIT_L(0); PG8_BAR; PG8_MMA(1, 0, At, B0); PG8_MMA(1, 1, At, B1); PG8_BAR; PG8_SCHED;
.LBB0_116:
	ds_read_b128 v[150:153], v147
	ds_read_b128 v[154:157], v147 offset:1024
	ds_read_b128 v[158:161], v147 offset:2048
	ds_read_b128 v[174:177], v147 offset:3072
	ds_read_b128 v[178:181], v148
	ds_read_b128 v[182:185], v148 offset:1024
	ds_read_b128 v[186:189], v148 offset:2048
	ds_read_b128 v[190:193], v148 offset:3072
	s_add_i32 s55, s54, 2
	s_add_u32 s28, s0, 0xfff80080
	s_addc_u32 s29, s1, -1
	s_cmp_eq_u32 s50, s54
	s_cselect_b32 s31, s21, s29
	s_cselect_b32 s30, s48, s28
	s_cselect_b32 s29, s19, s53
	s_cselect_b32 s28, s49, s51
	v_lshl_add_u64 v[138:139], s[0:1], 0, v[130:131]
	s_add_i32 m0, s27, 0xc000
	ds_read_b128 v[194:197], v149
	ds_read_b128 v[198:201], v149 offset:1024
	ds_read_b128 v[202:205], v149 offset:2048
	ds_read_b128 v[206:209], v149 offset:3072
	ds_read_b128 v[210:213], v149 offset:4096
	ds_read_b128 v[224:227], v149 offset:5120
	ds_read_b128 v[232:235], v149 offset:6144
	ds_read_b128 v[236:239], v149 offset:7168
	global_load_lds_dwordx4 v[138:139], off
	v_lshl_add_u64 v[138:139], s[0:1], 0, v[132:133]
	s_add_i32 m0, s27, 0xe000
	s_nop 0
	global_load_lds_dwordx4 v[138:139], off
	s_waitcnt vmcnt(8)
	s_waitcnt lgkmcnt(0)
	s_barrier
	s_setprio 1
	s_waitcnt lgkmcnt(0)
	v_mfma_f32_16x16x32_bf16 v[126:129], v[150:153], v[194:197], v[126:129]
	v_mfma_f32_16x16x32_bf16 v[122:125], v[158:161], v[194:197], v[122:125]
	v_mfma_f32_16x16x32_bf16 v[110:113], v[150:153], v[202:205], v[110:113]
	v_mfma_f32_16x16x32_bf16 v[106:109], v[158:161], v[202:205], v[106:109]
	v_mfma_f32_16x16x32_bf16 v[94:97], v[150:153], v[210:213], v[94:97]
	v_mfma_f32_16x16x32_bf16 v[90:93], v[158:161], v[210:213], v[90:93]
	v_mfma_f32_16x16x32_bf16 v[78:81], v[150:153], v[232:235], v[78:81]
	v_mfma_f32_16x16x32_bf16 v[74:77], v[158:161], v[232:235], v[74:77]
	v_mfma_f32_16x16x32_bf16 v[126:129], v[154:157], v[198:201], v[126:129]
	v_mfma_f32_16x16x32_bf16 v[122:125], v[174:177], v[198:201], v[122:125]
	v_mfma_f32_16x16x32_bf16 v[110:113], v[154:157], v[206:209], v[110:113]
	v_mfma_f32_16x16x32_bf16 v[106:109], v[174:177], v[206:209], v[106:109]
	v_mfma_f32_16x16x32_bf16 v[94:97], v[154:157], v[224:227], v[94:97]
	v_mfma_f32_16x16x32_bf16 v[90:93], v[174:177], v[224:227], v[90:93]
	v_mfma_f32_16x16x32_bf16 v[78:81], v[154:157], v[236:239], v[78:81]
	v_mfma_f32_16x16x32_bf16 v[74:77], v[174:177], v[236:239], v[74:77]
	s_setprio 0
	s_setprio 1
	v_mfma_f32_16x16x32_bf16 v[118:121], v[178:181], v[194:197], v[118:121]
	v_mfma_f32_16x16x32_bf16 v[114:117], v[186:189], v[194:197], v[114:117]
	v_mfma_f32_16x16x32_bf16 v[102:105], v[178:181], v[202:205], v[102:105]
	v_mfma_f32_16x16x32_bf16 v[98:101], v[186:189], v[202:205], v[98:101]
	v_mfma_f32_16x16x32_bf16 v[86:89], v[178:181], v[210:213], v[86:89]
	v_mfma_f32_16x16x32_bf16 v[82:85], v[186:189], v[210:213], v[82:85]
	v_mfma_f32_16x16x32_bf16 v[70:73], v[178:181], v[232:235], v[70:73]
	v_mfma_f32_16x16x32_bf16 v[66:69], v[186:189], v[232:235], v[66:69]
	v_mfma_f32_16x16x32_bf16 v[118:121], v[182:185], v[198:201], v[118:121]
	v_mfma_f32_16x16x32_bf16 v[114:117], v[190:193], v[198:201], v[114:117]
	v_mfma_f32_16x16x32_bf16 v[102:105], v[182:185], v[206:209], v[102:105]
	v_mfma_f32_16x16x32_bf16 v[98:101], v[190:193], v[206:209], v[98:101]
	v_mfma_f32_16x16x32_bf16 v[86:89], v[182:185], v[224:227], v[86:89]
	v_mfma_f32_16x16x32_bf16 v[82:85], v[190:193], v[224:227], v[82:85]
	v_mfma_f32_16x16x32_bf16 v[70:73], v[182:185], v[236:239], v[70:73]
	v_mfma_f32_16x16x32_bf16 v[66:69], v[190:193], v[236:239], v[66:69]
	s_setprio 0
	s_barrier
	s_add_i32 s54, s42, s2
	v_lshl_add_u64 v[138:139], s[28:29], 0, v[168:169]
	s_mov_b32 m0, s54
	ds_read_b128 v[194:197], v149 offset:16384
	ds_read_b128 v[198:201], v149 offset:17408
	ds_read_b128 v[202:205], v149 offset:18432
	ds_read_b128 v[206:209], v149 offset:19456
	ds_read_b128 v[210:213], v149 offset:20480
	ds_read_b128 v[224:227], v149 offset:21504
	ds_read_b128 v[232:235], v149 offset:22528
	ds_read_b128 v[236:239], v149 offset:23552
	global_load_lds_dwordx4 v[138:139], off
	s_add_i32 m0, s54, 0x2000
	s_add_u32 s56, s28, 0x80000
	v_lshl_add_u64 v[240:241], s[28:29], 0, v[172:173]
	s_addc_u32 s57, s29, 0
	s_add_i32 s54, s43, s2
	global_load_lds_dwordx4 v[240:241], off
	v_lshl_add_u64 v[242:243], s[56:57], 0, v[168:169]
	s_mov_b32 m0, s54
	v_lshl_add_u64 v[244:245], s[30:31], 0, v[170:171]
	global_load_lds_dwordx4 v[242:243], off
	v_lshl_add_u64 v[242:243], s[56:57], 0, v[172:173]
	s_add_i32 m0, s54, 0x2000
	s_nop 0
	global_load_lds_dwordx4 v[242:243], off
	v_lshl_add_u64 v[242:243], s[30:31], 0, v[166:167]
	s_mov_b32 m0, s27
	s_nop 0
	global_load_lds_dwordx4 v[242:243], off
	s_mov_b32 m0, s34
	s_nop 0
	global_load_lds_dwordx4 v[244:245], off
	s_waitcnt vmcnt(8)
	s_waitcnt lgkmcnt(0)
	s_barrier
; #define PG8_STAGE(bufoff, gbase, voff) do { _Pragma("unroll") for (int _i = 0; _i < 2; ++_i) \
;         __builtin_amdgcn_global_load_lds((const unsigned*)((const char*)(gbase) + (voff)[_i]), (PG8_LAS unsigned*)(lds + (bufoff) + ldsw + _i * 8192), 16, 0, 0); } while (0)
; #define PG8_LDA(dst, b, h) do { _Pragma("unroll") for (int m = 0; m < 4; ++m) _Pragma("unroll") for (int k = 0; k < 2; ++k) dst[m][k] = *(const PG8_LAS bf16x8*)(lds + PG8_SA(b, h) + aoff + m * 2048 + k * 1024); } while (0)
; #define PG8_LDB(dst, b, h) do { _Pragma("unroll") for (int n = 0; n < 2; ++n) _Pragma("unroll") for (int k = 0; k < 2; ++k) dst[n][k] = *(const PG8_LAS bf16x8*)(lds + PG8_SB(b, h) + boff + n * 2048 + k * 1024); } while (0)
; #define PG8_MMA(ai, bj, At, Bt) do { __builtin_amdgcn_s_setprio(1); _Pragma("unroll") for (int m = 0; m < 4; ++m) _Pragma("unroll") for (int n = 0; n < 2; ++n) _Pragma("unroll") for (int k = 0; k < 2; ++k) \
;         acc[ai][bj][m][n] = __builtin_amdgcn_mfma_f32_16x16x32_bf16(Bt[n][k], At[m][k], acc[ai][bj][m][n], 0, 0, 0); __builtin_amdgcn_s_setprio(0); } while (0)
; #define PG8_WAIT_V(n) asm volatile("s_waitcnt vmcnt(" #n ")" ::: "memory")
; #define PG8_WAIT_L(n) asm volatile("s_waitcnt lgkmcnt(" #n ")" ::: "memory")
; #define PG8_BAR __builtin_amdgcn_s_barrier()
; #define PG8_SCHED __builtin_amdgcn_sched_barrier(0)
; template <class Epi, class Sched, bool ALIGN_EPI = false, bool SP2 = false>
; __device__ __forceinline__ void gemm_phase(PG8_LAS unsigned char* lds, const Gemm g, const Sched& S, const Epi& E) {
;     ...
;             PG8_WAIT_V(8); PG8_WAIT_L(0); PG8_BAR; PG8_MMA(1, 0, At, B0); PG8_MMA(1, 1, At, B1); PG8_BAR; PG8_SCHED;
;             PG8_LDB(B0, 1, 0); PG8_LDB(B1, 1, 1); PG8_SCHED; PG8_LDA(At, 1, 0); PG8_STAGE(PG8_SA(0, 1), a2 + hstep, voffA);
;             PG8_WAIT_V(8); PG8_WAIT_L(0); PG8_BAR; PG8_MMA(0, 0, At, B0); PG8_MMA(0, 1, At, B1); PG8_BAR; PG8_SCHED;
	s_setprio 1
	s_waitcnt lgkmcnt(0)
	v_mfma_f32_16x16x32_bf16 v[62:65], v[150:153], v[194:197], v[62:65]
	v_mfma_f32_16x16x32_bf16 v[58:61], v[158:161], v[194:197], v[58:61]
	v_mfma_f32_16x16x32_bf16 v[46:49], v[150:153], v[202:205], v[46:49]
	v_mfma_f32_16x16x32_bf16 v[42:45], v[158:161], v[202:205], v[42:45]
	v_mfma_f32_16x16x32_bf16 v[30:33], v[150:153], v[210:213], v[30:33]
	v_mfma_f32_16x16x32_bf16 v[26:29], v[158:161], v[210:213], v[26:29]
	v_mfma_f32_16x16x32_bf16 v[14:17], v[150:153], v[232:235], v[14:17]
	v_mfma_f32_16x16x32_bf16 v[10:13], v[158:161], v[232:235], v[10:13]
	v_mfma_f32_16x16x32_bf16 v[62:65], v[154:157], v[198:201], v[62:65]
	v_mfma_f32_16x16x32_bf16 v[58:61], v[174:177], v[198:201], v[58:61]
	v_mfma_f32_16x16x32_bf16 v[46:49], v[154:157], v[206:209], v[46:49]
	v_mfma_f32_16x16x32_bf16 v[42:45], v[174:177], v[206:209], v[42:45]
	v_mfma_f32_16x16x32_bf16 v[30:33], v[154:157], v[224:227], v[30:33]
	v_mfma_f32_16x16x32_bf16 v[26:29], v[174:177], v[224:227], v[26:29]
	v_mfma_f32_16x16x32_bf16 v[14:17], v[154:157], v[236:239], v[14:17]
	v_mfma_f32_16x16x32_bf16 v[10:13], v[174:177], v[236:239], v[10:13]
	s_setprio 0
	s_setprio 1
	v_mfma_f32_16x16x32_bf16 v[54:57], v[178:181], v[194:197], v[54:57]
	v_mfma_f32_16x16x32_bf16 v[50:53], v[186:189], v[194:197], v[50:53]
	v_mfma_f32_16x16x32_bf16 v[38:41], v[178:181], v[202:205], v[38:41]
	v_mfma_f32_16x16x32_bf16 v[34:37], v[186:189], v[202:205], v[34:37]
	v_mfma_f32_16x16x32_bf16 v[22:25], v[178:181], v[210:213], v[22:25]
	v_mfma_f32_16x16x32_bf16 v[18:21], v[186:189], v[210:213], v[18:21]
	v_mfma_f32_16x16x32_bf16 v[6:9], v[178:181], v[232:235], v[6:9]
	v_mfma_f32_16x16x32_bf16 v[2:5], v[186:189], v[232:235], v[2:5]
	v_mfma_f32_16x16x32_bf16 v[54:57], v[182:185], v[198:201], v[54:57]
	v_mfma_f32_16x16x32_bf16 v[50:53], v[190:193], v[198:201], v[50:53]
	v_mfma_f32_16x16x32_bf16 v[38:41], v[182:185], v[206:209], v[38:41]
	v_mfma_f32_16x16x32_bf16 v[34:37], v[190:193], v[206:209], v[34:37]
	v_mfma_f32_16x16x32_bf16 v[22:25], v[182:185], v[224:227], v[22:25]
	v_mfma_f32_16x16x32_bf16 v[18:21], v[190:193], v[224:227], v[18:21]
	v_mfma_f32_16x16x32_bf16 v[6:9], v[182:185], v[236:239], v[6:9]
	v_mfma_f32_16x16x32_bf16 v[2:5], v[190:193], v[236:239], v[2:5]
	s_setprio 0
	s_barrier
	s_add_i32 s54, 0, 0x18000
	s_add_i32 s56, 0, 0x1c000
	v_add_u32_e32 v174, s54, v145
	v_add_u32_e32 v190, s56, v145
	ds_read_b128 v[150:153], v174
	ds_read_b128 v[154:157], v174 offset:1024
	ds_read_b128 v[158:161], v174 offset:2048
	ds_read_b128 v[174:177], v174 offset:3072
	ds_read_b128 v[178:181], v190
	ds_read_b128 v[182:185], v190 offset:1024
	ds_read_b128 v[186:189], v190 offset:2048
	ds_read_b128 v[190:193], v190 offset:3072
	s_add_u32 s30, s30, 0x80000
	s_addc_u32 s31, s31, 0
	s_mov_b32 m0, s35
	v_lshl_add_u64 v[246:247], s[30:31], 0, v[166:167]
	ds_read_b128 v[194:197], v149 offset:32768
	ds_read_b128 v[198:201], v149 offset:33792
	ds_read_b128 v[202:205], v149 offset:34816
	ds_read_b128 v[206:209], v149 offset:35840
	ds_read_b128 v[210:213], v149 offset:36864
	ds_read_b128 v[224:227], v149 offset:37888
	ds_read_b128 v[232:235], v149 offset:38912
	ds_read_b128 v[236:239], v149 offset:39936
	global_load_lds_dwordx4 v[246:247], off
	v_lshl_add_u64 v[246:247], s[30:31], 0, v[170:171]
	s_mov_b32 m0, s36
	s_nop 0
	global_load_lds_dwordx4 v[246:247], off
	s_waitcnt vmcnt(8)
	s_waitcnt lgkmcnt(0)
	s_barrier
	s_setprio 1
	s_waitcnt lgkmcnt(0)
	v_mfma_f32_16x16x32_bf16 v[126:129], v[150:153], v[194:197], v[126:129]
	v_mfma_f32_16x16x32_bf16 v[122:125], v[158:161], v[194:197], v[122:125]
	v_mfma_f32_16x16x32_bf16 v[110:113], v[150:153], v[202:205], v[110:113]
	v_mfma_f32_16x16x32_bf16 v[106:109], v[158:161], v[202:205], v[106:109]
	v_mfma_f32_16x16x32_bf16 v[94:97], v[150:153], v[210:213], v[94:97]
	v_mfma_f32_16x16x32_bf16 v[90:93], v[158:161], v[210:213], v[90:93]
	v_mfma_f32_16x16x32_bf16 v[78:81], v[150:153], v[232:235], v[78:81]
	v_mfma_f32_16x16x32_bf16 v[74:77], v[158:161], v[232:235], v[74:77]
	v_mfma_f32_16x16x32_bf16 v[126:129], v[154:157], v[198:201], v[126:129]
	v_mfma_f32_16x16x32_bf16 v[122:125], v[174:177], v[198:201], v[122:125]
	v_mfma_f32_16x16x32_bf16 v[110:113], v[154:157], v[206:209], v[110:113]
	v_mfma_f32_16x16x32_bf16 v[106:109], v[174:177], v[206:209], v[106:109]
	v_mfma_f32_16x16x32_bf16 v[94:97], v[154:157], v[224:227], v[94:97]
	v_mfma_f32_16x16x32_bf16 v[90:93], v[174:177], v[224:227], v[90:93]
	v_mfma_f32_16x16x32_bf16 v[78:81], v[154:157], v[236:239], v[78:81]
	v_mfma_f32_16x16x32_bf16 v[74:77], v[174:177], v[236:239], v[74:77]
	s_setprio 0
	s_setprio 1
	v_mfma_f32_16x16x32_bf16 v[118:121], v[178:181], v[194:197], v[118:121]
	v_mfma_f32_16x16x32_bf16 v[114:117], v[186:189], v[194:197], v[114:117]
	v_mfma_f32_16x16x32_bf16 v[102:105], v[178:181], v[202:205], v[102:105]
	v_mfma_f32_16x16x32_bf16 v[98:101], v[186:189], v[202:205], v[98:101]
	v_mfma_f32_16x16x32_bf16 v[86:89], v[178:181], v[210:213], v[86:89]
	v_mfma_f32_16x16x32_bf16 v[82:85], v[186:189], v[210:213], v[82:85]
	v_mfma_f32_16x16x32_bf16 v[70:73], v[178:181], v[232:235], v[70:73]
	v_mfma_f32_16x16x32_bf16 v[66:69], v[186:189], v[232:235], v[66:69]
	v_mfma_f32_16x16x32_bf16 v[118:121], v[182:185], v[198:201], v[118:121]
	v_mfma_f32_16x16x32_bf16 v[114:117], v[190:193], v[198:201], v[114:117]
	v_mfma_f32_16x16x32_bf16 v[102:105], v[182:185], v[206:209], v[102:105]
	v_mfma_f32_16x16x32_bf16 v[98:101], v[190:193], v[206:209], v[98:101]
	v_mfma_f32_16x16x32_bf16 v[86:89], v[182:185], v[224:227], v[86:89]
	v_mfma_f32_16x16x32_bf16 v[82:85], v[190:193], v[224:227], v[82:85]
	v_mfma_f32_16x16x32_bf16 v[70:73], v[182:185], v[236:239], v[70:73]
	v_mfma_f32_16x16x32_bf16 v[66:69], v[190:193], v[236:239], v[66:69]
	s_setprio 0
	s_barrier
; #define PG8_STAGE(bufoff, gbase, voff) do { _Pragma("unroll") for (int _i = 0; _i < 2; ++_i) \
;         __builtin_amdgcn_global_load_lds((const unsigned*)((const char*)(gbase) + (voff)[_i]), (PG8_LAS unsigned*)(lds + (bufoff) + ldsw + _i * 8192), 16, 0, 0); } while (0)
; #define PG8_LDA(dst, b, h) do { _Pragma("unroll") for (int m = 0; m < 4; ++m) _Pragma("unroll") for (int k = 0; k < 2; ++k) dst[m][k] = *(const PG8_LAS bf16x8*)(lds + PG8_SA(b, h) + aoff + m * 2048 + k * 1024); } while (0)
; #define PG8_MMA(ai, bj, At, Bt) do { __builtin_amdgcn_s_setprio(1); _Pragma("unroll") for (int m = 0; m < 4; ++m) _Pragma("unroll") for (int n = 0; n < 2; ++n) _Pragma("unroll") for (int k = 0; k < 2; ++k) \
;         acc[ai][bj][m][n] = __builtin_amdgcn_mfma_f32_16x16x32_bf16(Bt[n][k], At[m][k], acc[ai][bj][m][n], 0, 0, 0); __builtin_amdgcn_s_setprio(0); } while (0)
; #define PG8_WAIT_V(n) asm volatile("s_waitcnt vmcnt(" #n ")" ::: "memory")
; #define PG8_WAIT_L(n) asm volatile("s_waitcnt lgkmcnt(" #n ")" ::: "memory")
; #define PG8_BAR __builtin_amdgcn_s_barrier()
; #define PG8_SCHED __builtin_amdgcn_sched_barrier(0)
; template <class Epi, class Sched, bool ALIGN_EPI = false, bool SP2 = false>
; __device__ __forceinline__ void gemm_phase(PG8_LAS unsigned char* lds, const Gemm g, const Sched& S, const Epi& E) {
;     ...
;         for (int t = 0; t < nt; t += 2) {
;     ...
;             PG8_LDA(At, 1, 1); PG8_STAGE(PG8_SB(1, 0), b3, voffB); PG8_STAGE(PG8_SB(1, 1), b3 + hstep, voffB); PG8_STAGE(PG8_SA(1, 0), a3, voffA);
;             PG8_WAIT_V(8); PG8_WAIT_L(0); PG8_BAR; PG8_MMA(1, 0, At, B0); PG8_MMA(1, 1, At, B1); PG8_BAR; PG8_SCHED;
;     ...
;         if constexpr (ALIGN_EPI) { if (wr == 0) PG8_BAR; }
	s_add_i32 s30, s54, s2
	v_lshl_add_u64 v[138:139], v[138:139], 0, s[14:15]
	s_mov_b32 m0, s30
	ds_read_b128 v[194:197], v149 offset:49152
	ds_read_b128 v[198:201], v149 offset:50176
	ds_read_b128 v[202:205], v149 offset:51200
	ds_read_b128 v[206:209], v149 offset:52224
	ds_read_b128 v[210:213], v149 offset:53248
	ds_read_b128 v[224:227], v149 offset:54272
	ds_read_b128 v[232:235], v149 offset:55296
	ds_read_b128 v[236:239], v149 offset:56320
	global_load_lds_dwordx4 v[138:139], off
	s_add_i32 m0, s30, 0x2000
	s_add_u32 s28, s28, 0x80080
	v_lshl_add_u64 v[138:139], v[240:241], 0, s[14:15]
	s_addc_u32 s29, s29, 0
	s_add_i32 s30, s56, s2
	global_load_lds_dwordx4 v[138:139], off
	v_lshl_add_u64 v[138:139], s[28:29], 0, v[168:169]
	s_mov_b32 m0, s30
	s_nop 0
	global_load_lds_dwordx4 v[138:139], off
	v_lshl_add_u64 v[138:139], s[28:29], 0, v[172:173]
	s_add_i32 m0, s30, 0x2000
	s_nop 0
	global_load_lds_dwordx4 v[138:139], off
	v_lshl_add_u64 v[138:139], v[242:243], 0, s[14:15]
	s_mov_b32 m0, s38
	s_nop 0
	global_load_lds_dwordx4 v[138:139], off
	v_lshl_add_u64 v[138:139], v[244:245], 0, s[14:15]
	s_mov_b32 m0, s39
	s_nop 0
	global_load_lds_dwordx4 v[138:139], off
	s_waitcnt vmcnt(8)
	s_waitcnt lgkmcnt(0)
	s_barrier
	s_setprio 1
	s_waitcnt lgkmcnt(0)
	v_mfma_f32_16x16x32_bf16 v[62:65], v[150:153], v[194:197], v[62:65]
	v_mfma_f32_16x16x32_bf16 v[58:61], v[158:161], v[194:197], v[58:61]
	v_mfma_f32_16x16x32_bf16 v[46:49], v[150:153], v[202:205], v[46:49]
	v_mfma_f32_16x16x32_bf16 v[42:45], v[158:161], v[202:205], v[42:45]
	v_mfma_f32_16x16x32_bf16 v[30:33], v[150:153], v[210:213], v[30:33]
	v_mfma_f32_16x16x32_bf16 v[26:29], v[158:161], v[210:213], v[26:29]
	v_mfma_f32_16x16x32_bf16 v[14:17], v[150:153], v[232:235], v[14:17]
	v_mfma_f32_16x16x32_bf16 v[10:13], v[158:161], v[232:235], v[10:13]
	v_mfma_f32_16x16x32_bf16 v[62:65], v[154:157], v[198:201], v[62:65]
	v_mfma_f32_16x16x32_bf16 v[58:61], v[174:177], v[198:201], v[58:61]
	v_mfma_f32_16x16x32_bf16 v[46:49], v[154:157], v[206:209], v[46:49]
	v_mfma_f32_16x16x32_bf16 v[42:45], v[174:177], v[206:209], v[42:45]
	v_mfma_f32_16x16x32_bf16 v[30:33], v[154:157], v[224:227], v[30:33]
	v_mfma_f32_16x16x32_bf16 v[26:29], v[174:177], v[224:227], v[26:29]
	v_mfma_f32_16x16x32_bf16 v[14:17], v[154:157], v[236:239], v[14:17]
	v_mfma_f32_16x16x32_bf16 v[10:13], v[174:177], v[236:239], v[10:13]
	s_setprio 0
	s_setprio 1
	v_mfma_f32_16x16x32_bf16 v[54:57], v[178:181], v[194:197], v[54:57]
	v_mfma_f32_16x16x32_bf16 v[50:53], v[186:189], v[194:197], v[50:53]
	v_mfma_f32_16x16x32_bf16 v[38:41], v[178:181], v[202:205], v[38:41]
	v_mfma_f32_16x16x32_bf16 v[34:37], v[186:189], v[202:205], v[34:37]
	v_mfma_f32_16x16x32_bf16 v[22:25], v[178:181], v[210:213], v[22:25]
	v_mfma_f32_16x16x32_bf16 v[18:21], v[186:189], v[210:213], v[18:21]
	v_mfma_f32_16x16x32_bf16 v[6:9], v[178:181], v[232:235], v[6:9]
	v_mfma_f32_16x16x32_bf16 v[2:5], v[186:189], v[232:235], v[2:5]
	v_mfma_f32_16x16x32_bf16 v[54:57], v[182:185], v[198:201], v[54:57]
	v_mfma_f32_16x16x32_bf16 v[50:53], v[190:193], v[198:201], v[50:53]
	v_mfma_f32_16x16x32_bf16 v[38:41], v[182:185], v[206:209], v[38:41]
	v_mfma_f32_16x16x32_bf16 v[34:37], v[190:193], v[206:209], v[34:37]
	v_mfma_f32_16x16x32_bf16 v[22:25], v[182:185], v[224:227], v[22:25]
	v_mfma_f32_16x16x32_bf16 v[18:21], v[190:193], v[224:227], v[18:21]
	v_mfma_f32_16x16x32_bf16 v[6:9], v[182:185], v[236:239], v[6:9]
	v_mfma_f32_16x16x32_bf16 v[2:5], v[190:193], v[236:239], v[2:5]
	s_setprio 0
	s_add_u32 s0, s0, 0x100
	s_addc_u32 s1, s1, 0
	s_add_u32 s51, s51, 0x100
	s_addc_u32 s53, s53, 0
	s_cmp_ge_u32 s55, s47
	s_mov_b32 s54, s55
	s_barrier
	s_cbranch_scc0 .LBB0_116
	s_and_b64 vcc, exec, s[16:17]
	s_cbranch_vccz .LBB0_119
	s_barrier

; #define PG8_STAGE(bufoff, gbase, voff) do { _Pragma("unroll") for (int _i = 0; _i < 2; ++_i) \
;         __builtin_amdgcn_global_load_lds((const unsigned*)((const char*)(gbase) + (voff)[_i]), (PG8_LAS unsigned*)(lds + (bufoff) + ldsw + _i * 8192), 16, 0, 0); } while (0)
; #define PG8_LDA(dst, b, h) do { _Pragma("unroll") for (int m = 0; m < 4; ++m) _Pragma("unroll") for (int k = 0; k < 2; ++k) dst[m][k] = *(const PG8_LAS bf16x8*)(lds + PG8_SA(b, h) + aoff + m * 2048 + k * 1024); } while (0)
; #define PG8_LDB(dst, b, h) do { _Pragma("unroll") for (int n = 0; n < 2; ++n) _Pragma("unroll") for (int k = 0; k < 2; ++k) dst[n][k] = *(const PG8_LAS bf16x8*)(lds + PG8_SB(b, h) + boff + n * 2048 + k * 1024); } while (0)
; #define PG8_MMA(ai, bj, At, Bt) do { __builtin_amdgcn_s_setprio(1); _Pragma("unroll") for (int m = 0; m < 4; ++m) _Pragma("unroll") for (int n = 0; n < 2; ++n) _Pragma("unroll") for (int k = 0; k < 2; ++k) \
;         acc[ai][bj][m][n] = __builtin_amdgcn_mfma_f32_16x16x32_bf16(Bt[n][k], At[m][k], acc[ai][bj][m][n], 0, 0, 0); __builtin_amdgcn_s_setprio(0); } while (0)
; #define PG8_WAIT_V(n) asm volatile("s_waitcnt vmcnt(" #n ")" ::: "memory")
; #define PG8_BAR __builtin_amdgcn_s_barrier()
; template <class Epi, class Sched, bool ALIGN_EPI = false, bool SP2 = false>
; __device__ __forceinline__ void gemm_phase(PG8_LAS unsigned char* lds, const Gemm g, const Sched& S, const Epi& E) {
;     ...
;         for (int t = 0; t < nt; t += 2) {
;             const bool last = (t == nt - 2);
;             const char* a1 = cA + (size_t)(t + 1) * kstep;
;             const char* a2 = last ? nA : cA + (size_t)(t + 2) * kstep; const char* b2 = last ? nB : cB + (size_t)(t + 2) * kstep;
;             const char* a3 = a2 + kstep; const char* b3 = b2 + kstep;
;             if (last && has_next) S.a_ready(nxt);
;             if constexpr (SP2) {
;             PG8_LDB(B0, 0, 0); PG8_LDB(B1, 0, 1); PG8_SCHED; PG8_LDA(At, 0, 0); PG8_STAGE(PG8_SA(1, 1), a1 + hstep, voffA);
;             PG8_WAIT_V(8); PG8_WAIT_L(0); PG8_BAR; PG8_MMA(0, 0, At, B0); PG8_MMA(0, 1, At, B1); PG8_BAR; PG8_SCHED;
;             PG8_LDA(At, 0, 1); PG8_STAGE(PG8_SB(0, 0), b2, voffB); PG8_STAGE(PG8_SB(0, 1), b2 + hstep, voffB); PG8_STAGE(PG8_SA(0, 0), a2, voffA);
;             PG8_WAIT_V(8); PG8_WAIT_L(0); PG8_BAR; PG8_MMA(1, 0, At, B0); PG8_MMA(1, 1, At, B1); PG8_BAR; PG8_SCHED;
.LBB0_281:
	ds_read_b128 v[136:139], v146
	ds_read_b128 v[150:153], v146 offset:1024
	ds_read_b128 v[154:157], v146 offset:2048
	ds_read_b128 v[158:161], v146 offset:3072
	ds_read_b128 v[178:181], v147
	ds_read_b128 v[182:185], v147 offset:1024
	ds_read_b128 v[186:189], v147 offset:2048
	ds_read_b128 v[190:193], v147 offset:3072
	s_add_i32 s54, s24, 2
	s_add_u32 s25, s22, 0xffea0080
	s_addc_u32 s26, s23, -1
	s_cmp_eq_u32 s50, s24
	s_cselect_b32 s24, s20, s51
	s_cselect_b32 s27, s19, s26
	s_cselect_b32 s26, s18, s25
	s_cselect_b32 s25, s21, s53
	v_lshl_add_u64 v[244:245], s[22:23], 0, v[130:131]
	s_add_i32 m0, s3, 0xc000
	ds_read_b128 v[194:197], v148
	ds_read_b128 v[198:201], v148 offset:1024
	ds_read_b128 v[202:205], v148 offset:2048
	ds_read_b128 v[206:209], v148 offset:3072
	ds_read_b128 v[210:213], v148 offset:4096
	ds_read_b128 v[232:235], v148 offset:5120
	ds_read_b128 v[236:239], v148 offset:6144
	ds_read_b128 v[240:243], v148 offset:7168
	global_load_lds_dwordx4 v[244:245], off
	v_lshl_add_u64 v[244:245], s[22:23], 0, v[132:133]
	s_add_i32 m0, s3, 0xe000
	s_nop 0
	global_load_lds_dwordx4 v[244:245], off
	s_waitcnt vmcnt(8)
	s_waitcnt lgkmcnt(0)
	s_barrier
	s_setprio 1
	s_waitcnt lgkmcnt(0)
	v_mfma_f32_16x16x32_bf16 v[126:129], v[136:139], v[194:197], v[126:129]
	v_mfma_f32_16x16x32_bf16 v[122:125], v[154:157], v[194:197], v[122:125]
	v_mfma_f32_16x16x32_bf16 v[118:121], v[136:139], v[202:205], v[118:121]
	v_mfma_f32_16x16x32_bf16 v[114:117], v[154:157], v[202:205], v[114:117]
	v_mfma_f32_16x16x32_bf16 v[102:105], v[136:139], v[210:213], v[102:105]
	v_mfma_f32_16x16x32_bf16 v[98:101], v[154:157], v[210:213], v[98:101]
	v_mfma_f32_16x16x32_bf16 v[86:89], v[136:139], v[236:239], v[86:89]
	v_mfma_f32_16x16x32_bf16 v[82:85], v[154:157], v[236:239], v[82:85]
	v_mfma_f32_16x16x32_bf16 v[126:129], v[150:153], v[198:201], v[126:129]
	v_mfma_f32_16x16x32_bf16 v[122:125], v[158:161], v[198:201], v[122:125]
	v_mfma_f32_16x16x32_bf16 v[118:121], v[150:153], v[206:209], v[118:121]
	v_mfma_f32_16x16x32_bf16 v[114:117], v[158:161], v[206:209], v[114:117]
	v_mfma_f32_16x16x32_bf16 v[102:105], v[150:153], v[232:235], v[102:105]
	v_mfma_f32_16x16x32_bf16 v[98:101], v[158:161], v[232:235], v[98:101]
	v_mfma_f32_16x16x32_bf16 v[86:89], v[150:153], v[240:243], v[86:89]
	v_mfma_f32_16x16x32_bf16 v[82:85], v[158:161], v[240:243], v[82:85]
	s_setprio 0
	s_setprio 1
	v_mfma_f32_16x16x32_bf16 v[110:113], v[178:181], v[194:197], v[110:113]
	v_mfma_f32_16x16x32_bf16 v[106:109], v[186:189], v[194:197], v[106:109]
	v_mfma_f32_16x16x32_bf16 v[94:97], v[178:181], v[202:205], v[94:97]
	v_mfma_f32_16x16x32_bf16 v[90:93], v[186:189], v[202:205], v[90:93]
	v_mfma_f32_16x16x32_bf16 v[78:81], v[178:181], v[210:213], v[78:81]
	v_mfma_f32_16x16x32_bf16 v[74:77], v[186:189], v[210:213], v[74:77]
	v_mfma_f32_16x16x32_bf16 v[70:73], v[178:181], v[236:239], v[70:73]
	v_mfma_f32_16x16x32_bf16 v[66:69], v[186:189], v[236:239], v[66:69]
	v_mfma_f32_16x16x32_bf16 v[110:113], v[182:185], v[198:201], v[110:113]
	v_mfma_f32_16x16x32_bf16 v[106:109], v[190:193], v[198:201], v[106:109]
	v_mfma_f32_16x16x32_bf16 v[94:97], v[182:185], v[206:209], v[94:97]
	v_mfma_f32_16x16x32_bf16 v[90:93], v[190:193], v[206:209], v[90:93]
	v_mfma_f32_16x16x32_bf16 v[78:81], v[182:185], v[232:235], v[78:81]
	v_mfma_f32_16x16x32_bf16 v[74:77], v[190:193], v[232:235], v[74:77]
	v_mfma_f32_16x16x32_bf16 v[70:73], v[182:185], v[240:243], v[70:73]
	v_mfma_f32_16x16x32_bf16 v[66:69], v[190:193], v[240:243], v[66:69]
	s_setprio 0
	s_barrier
	s_add_i32 s55, s40, s2
	v_lshl_add_u64 v[244:245], s[24:25], 0, v[174:175]
	s_mov_b32 m0, s55
	ds_read_b128 v[194:197], v148 offset:16384
	ds_read_b128 v[198:201], v148 offset:17408
	ds_read_b128 v[202:205], v148 offset:18432
	ds_read_b128 v[206:209], v148 offset:19456
	ds_read_b128 v[210:213], v148 offset:20480
	ds_read_b128 v[232:235], v148 offset:21504
	ds_read_b128 v[236:239], v148 offset:22528
	ds_read_b128 v[240:243], v148 offset:23552
	global_load_lds_dwordx4 v[244:245], off
	s_add_i32 m0, s55, 0x2000
	s_add_u32 s56, s24, 0x160000
	v_lshl_add_u64 v[246:247], s[24:25], 0, v[176:177]
	s_addc_u32 s57, s25, 0
	s_add_i32 s55, s41, s2
	global_load_lds_dwordx4 v[246:247], off
	v_lshl_add_u64 v[248:249], s[56:57], 0, v[174:175]
	s_mov_b32 m0, s55
	v_lshl_add_u64 v[250:251], s[26:27], 0, v[176:177]
	global_load_lds_dwordx4 v[248:249], off
	v_lshl_add_u64 v[248:249], s[56:57], 0, v[176:177]
	s_add_i32 m0, s55, 0x2000
	s_nop 0
	global_load_lds_dwordx4 v[248:249], off
	v_lshl_add_u64 v[248:249], s[26:27], 0, v[174:175]
	s_mov_b32 m0, s3
	s_nop 0
	global_load_lds_dwordx4 v[248:249], off
	s_mov_b32 m0, s28
	s_nop 0
	global_load_lds_dwordx4 v[250:251], off
	s_waitcnt vmcnt(8)
	s_waitcnt lgkmcnt(0)
	s_barrier
; #define PG8_STAGE(bufoff, gbase, voff) do { _Pragma("unroll") for (int _i = 0; _i < 2; ++_i) \
;         __builtin_amdgcn_global_load_lds((const unsigned*)((const char*)(gbase) + (voff)[_i]), (PG8_LAS unsigned*)(lds + (bufoff) + ldsw + _i * 8192), 16, 0, 0); } while (0)
; #define PG8_LDA(dst, b, h) do { _Pragma("unroll") for (int m = 0; m < 4; ++m) _Pragma("unroll") for (int k = 0; k < 2; ++k) dst[m][k] = *(const PG8_LAS bf16x8*)(lds + PG8_SA(b, h) + aoff + m * 2048 + k * 1024); } while (0)
; #define PG8_LDB(dst, b, h) do { _Pragma("unroll") for (int n = 0; n < 2; ++n) _Pragma("unroll") for (int k = 0; k < 2; ++k) dst[n][k] = *(const PG8_LAS bf16x8*)(lds + PG8_SB(b, h) + boff + n * 2048 + k * 1024); } while (0)
; #define PG8_MMA(ai, bj, At, Bt) do { __builtin_amdgcn_s_setprio(1); _Pragma("unroll") for (int m = 0; m < 4; ++m) _Pragma("unroll") for (int n = 0; n < 2; ++n) _Pragma("unroll") for (int k = 0; k < 2; ++k) \
;         acc[ai][bj][m][n] = __builtin_amdgcn_mfma_f32_16x16x32_bf16(Bt[n][k], At[m][k], acc[ai][bj][m][n], 0, 0, 0); __builtin_amdgcn_s_setprio(0); } while (0)
; #define PG8_WAIT_V(n) asm volatile("s_waitcnt vmcnt(" #n ")" ::: "memory")
; #define PG8_WAIT_L(n) asm volatile("s_waitcnt lgkmcnt(" #n ")" ::: "memory")
; #define PG8_BAR __builtin_amdgcn_s_barrier()
; #define PG8_SCHED __builtin_amdgcn_sched_barrier(0)
; template <class Epi, class Sched, bool ALIGN_EPI = false, bool SP2 = false>
; __device__ __forceinline__ void gemm_phase(PG8_LAS unsigned char* lds, const Gemm g, const Sched& S, const Epi& E) {
;     ...
;             PG8_WAIT_V(8); PG8_WAIT_L(0); PG8_BAR; PG8_MMA(1, 0, At, B0); PG8_MMA(1, 1, At, B1); PG8_BAR; PG8_SCHED;
;             PG8_LDB(B0, 1, 0); PG8_LDB(B1, 1, 1); PG8_SCHED; PG8_LDA(At, 1, 0); PG8_STAGE(PG8_SA(0, 1), a2 + hstep, voffA);
;             PG8_WAIT_V(8); PG8_WAIT_L(0); PG8_BAR; PG8_MMA(0, 0, At, B0); PG8_MMA(0, 1, At, B1); PG8_BAR; PG8_SCHED;
	s_setprio 1
	s_waitcnt lgkmcnt(0)
	v_mfma_f32_16x16x32_bf16 v[62:65], v[136:139], v[194:197], v[62:65]
	v_mfma_f32_16x16x32_bf16 v[58:61], v[154:157], v[194:197], v[58:61]
	v_mfma_f32_16x16x32_bf16 v[54:57], v[136:139], v[202:205], v[54:57]
	v_mfma_f32_16x16x32_bf16 v[50:53], v[154:157], v[202:205], v[50:53]
	v_mfma_f32_16x16x32_bf16 v[38:41], v[136:139], v[210:213], v[38:41]
	v_mfma_f32_16x16x32_bf16 v[34:37], v[154:157], v[210:213], v[34:37]
	v_mfma_f32_16x16x32_bf16 v[22:25], v[136:139], v[236:239], v[22:25]
	v_mfma_f32_16x16x32_bf16 v[18:21], v[154:157], v[236:239], v[18:21]
	v_mfma_f32_16x16x32_bf16 v[62:65], v[150:153], v[198:201], v[62:65]
	v_mfma_f32_16x16x32_bf16 v[58:61], v[158:161], v[198:201], v[58:61]
	v_mfma_f32_16x16x32_bf16 v[54:57], v[150:153], v[206:209], v[54:57]
	v_mfma_f32_16x16x32_bf16 v[50:53], v[158:161], v[206:209], v[50:53]
	v_mfma_f32_16x16x32_bf16 v[38:41], v[150:153], v[232:235], v[38:41]
	v_mfma_f32_16x16x32_bf16 v[34:37], v[158:161], v[232:235], v[34:37]
	v_mfma_f32_16x16x32_bf16 v[22:25], v[150:153], v[240:243], v[22:25]
	v_mfma_f32_16x16x32_bf16 v[18:21], v[158:161], v[240:243], v[18:21]
	s_setprio 0
	s_setprio 1
	v_mfma_f32_16x16x32_bf16 v[46:49], v[178:181], v[194:197], v[46:49]
	v_mfma_f32_16x16x32_bf16 v[42:45], v[186:189], v[194:197], v[42:45]
	v_mfma_f32_16x16x32_bf16 v[30:33], v[178:181], v[202:205], v[30:33]
	v_mfma_f32_16x16x32_bf16 v[26:29], v[186:189], v[202:205], v[26:29]
	v_mfma_f32_16x16x32_bf16 v[14:17], v[178:181], v[210:213], v[14:17]
	v_mfma_f32_16x16x32_bf16 v[10:13], v[186:189], v[210:213], v[10:13]
	v_mfma_f32_16x16x32_bf16 v[6:9], v[178:181], v[236:239], v[6:9]
	v_mfma_f32_16x16x32_bf16 v[2:5], v[186:189], v[236:239], v[2:5]
	v_mfma_f32_16x16x32_bf16 v[46:49], v[182:185], v[198:201], v[46:49]
	v_mfma_f32_16x16x32_bf16 v[42:45], v[190:193], v[198:201], v[42:45]
	v_mfma_f32_16x16x32_bf16 v[30:33], v[182:185], v[206:209], v[30:33]
	v_mfma_f32_16x16x32_bf16 v[26:29], v[190:193], v[206:209], v[26:29]
	v_mfma_f32_16x16x32_bf16 v[14:17], v[182:185], v[232:235], v[14:17]
	v_mfma_f32_16x16x32_bf16 v[10:13], v[190:193], v[232:235], v[10:13]
	v_mfma_f32_16x16x32_bf16 v[6:9], v[182:185], v[240:243], v[6:9]
	v_mfma_f32_16x16x32_bf16 v[2:5], v[190:193], v[240:243], v[2:5]
	s_setprio 0
	s_barrier
	s_add_i32 s55, 0, 0x18000
	v_add_u32_e32 v149, s55, v144
	s_add_i32 s56, 0, 0x1c000
	ds_read_b128 v[136:139], v149
	ds_read_b128 v[150:153], v149 offset:1024
	ds_read_b128 v[154:157], v149 offset:2048
	ds_read_b128 v[158:161], v149 offset:3072
	v_add_u32_e32 v149, s56, v144
	ds_read_b128 v[178:181], v149
	ds_read_b128 v[182:185], v149 offset:1024
	ds_read_b128 v[186:189], v149 offset:2048
	ds_read_b128 v[190:193], v149 offset:3072
	s_add_u32 s26, s26, 0x160000
	s_addc_u32 s27, s27, 0
	s_mov_b32 m0, s29
	v_lshl_add_u64 v[252:253], s[26:27], 0, v[174:175]
	ds_read_b128 v[194:197], v148 offset:32768
	ds_read_b128 v[198:201], v148 offset:33792
	ds_read_b128 v[202:205], v148 offset:34816
	ds_read_b128 v[206:209], v148 offset:35840
	ds_read_b128 v[210:213], v148 offset:36864
	ds_read_b128 v[232:235], v148 offset:37888
	ds_read_b128 v[236:239], v148 offset:38912
	ds_read_b128 v[240:243], v148 offset:39936
	global_load_lds_dwordx4 v[252:253], off
	v_lshl_add_u64 v[252:253], s[26:27], 0, v[176:177]
	s_mov_b32 m0, s30
	s_nop 0
	global_load_lds_dwordx4 v[252:253], off
	s_waitcnt vmcnt(8)
	s_waitcnt lgkmcnt(0)
	s_barrier
	s_setprio 1
	s_waitcnt lgkmcnt(0)
	v_mfma_f32_16x16x32_bf16 v[126:129], v[136:139], v[194:197], v[126:129]
	v_mfma_f32_16x16x32_bf16 v[122:125], v[154:157], v[194:197], v[122:125]
	v_mfma_f32_16x16x32_bf16 v[118:121], v[136:139], v[202:205], v[118:121]
	v_mfma_f32_16x16x32_bf16 v[114:117], v[154:157], v[202:205], v[114:117]
	v_mfma_f32_16x16x32_bf16 v[102:105], v[136:139], v[210:213], v[102:105]
	v_mfma_f32_16x16x32_bf16 v[98:101], v[154:157], v[210:213], v[98:101]
	v_mfma_f32_16x16x32_bf16 v[86:89], v[136:139], v[236:239], v[86:89]
	v_mfma_f32_16x16x32_bf16 v[82:85], v[154:157], v[236:239], v[82:85]
	v_mfma_f32_16x16x32_bf16 v[126:129], v[150:153], v[198:201], v[126:129]
	v_mfma_f32_16x16x32_bf16 v[122:125], v[158:161], v[198:201], v[122:125]
	v_mfma_f32_16x16x32_bf16 v[118:121], v[150:153], v[206:209], v[118:121]
	v_mfma_f32_16x16x32_bf16 v[114:117], v[158:161], v[206:209], v[114:117]
	v_mfma_f32_16x16x32_bf16 v[102:105], v[150:153], v[232:235], v[102:105]
	v_mfma_f32_16x16x32_bf16 v[98:101], v[158:161], v[232:235], v[98:101]
	v_mfma_f32_16x16x32_bf16 v[86:89], v[150:153], v[240:243], v[86:89]
	v_mfma_f32_16x16x32_bf16 v[82:85], v[158:161], v[240:243], v[82:85]
	s_setprio 0
	s_setprio 1
	v_mfma_f32_16x16x32_bf16 v[110:113], v[178:181], v[194:197], v[110:113]
	v_mfma_f32_16x16x32_bf16 v[106:109], v[186:189], v[194:197], v[106:109]
	v_mfma_f32_16x16x32_bf16 v[94:97], v[178:181], v[202:205], v[94:97]
	v_mfma_f32_16x16x32_bf16 v[90:93], v[186:189], v[202:205], v[90:93]
	v_mfma_f32_16x16x32_bf16 v[78:81], v[178:181], v[210:213], v[78:81]
	v_mfma_f32_16x16x32_bf16 v[74:77], v[186:189], v[210:213], v[74:77]
	v_mfma_f32_16x16x32_bf16 v[70:73], v[178:181], v[236:239], v[70:73]
	v_mfma_f32_16x16x32_bf16 v[66:69], v[186:189], v[236:239], v[66:69]
	v_mfma_f32_16x16x32_bf16 v[110:113], v[182:185], v[198:201], v[110:113]
	v_mfma_f32_16x16x32_bf16 v[106:109], v[190:193], v[198:201], v[106:109]
	v_mfma_f32_16x16x32_bf16 v[94:97], v[182:185], v[206:209], v[94:97]
	v_mfma_f32_16x16x32_bf16 v[90:93], v[190:193], v[206:209], v[90:93]
	v_mfma_f32_16x16x32_bf16 v[78:81], v[182:185], v[232:235], v[78:81]
	v_mfma_f32_16x16x32_bf16 v[74:77], v[190:193], v[232:235], v[74:77]
	v_mfma_f32_16x16x32_bf16 v[70:73], v[182:185], v[240:243], v[70:73]
	v_mfma_f32_16x16x32_bf16 v[66:69], v[190:193], v[240:243], v[66:69]
	s_setprio 0
	s_barrier
; #define PG8_STAGE(bufoff, gbase, voff) do { _Pragma("unroll") for (int _i = 0; _i < 2; ++_i) \
;         __builtin_amdgcn_global_load_lds((const unsigned*)((const char*)(gbase) + (voff)[_i]), (PG8_LAS unsigned*)(lds + (bufoff) + ldsw + _i * 8192), 16, 0, 0); } while (0)
; #define PG8_LDA(dst, b, h) do { _Pragma("unroll") for (int m = 0; m < 4; ++m) _Pragma("unroll") for (int k = 0; k < 2; ++k) dst[m][k] = *(const PG8_LAS bf16x8*)(lds + PG8_SA(b, h) + aoff + m * 2048 + k * 1024); } while (0)
; #define PG8_MMA(ai, bj, At, Bt) do { __builtin_amdgcn_s_setprio(1); _Pragma("unroll") for (int m = 0; m < 4; ++m) _Pragma("unroll") for (int n = 0; n < 2; ++n) _Pragma("unroll") for (int k = 0; k < 2; ++k) \
;         acc[ai][bj][m][n] = __builtin_amdgcn_mfma_f32_16x16x32_bf16(Bt[n][k], At[m][k], acc[ai][bj][m][n], 0, 0, 0); __builtin_amdgcn_s_setprio(0); } while (0)
; #define PG8_WAIT_V(n) asm volatile("s_waitcnt vmcnt(" #n ")" ::: "memory")
; #define PG8_WAIT_L(n) asm volatile("s_waitcnt lgkmcnt(" #n ")" ::: "memory")
; #define PG8_BAR __builtin_amdgcn_s_barrier()
; #define PG8_SCHED __builtin_amdgcn_sched_barrier(0)
; template <class Epi, class Sched, bool ALIGN_EPI = false, bool SP2 = false>
; __device__ __forceinline__ void gemm_phase(PG8_LAS unsigned char* lds, const Gemm g, const Sched& S, const Epi& E) {
;     ...
;         for (int t = 0; t < nt; t += 2) {
;     ...
;             PG8_LDA(At, 1, 1); PG8_STAGE(PG8_SB(1, 0), b3, voffB); PG8_STAGE(PG8_SB(1, 1), b3 + hstep, voffB); PG8_STAGE(PG8_SA(1, 0), a3, voffA);
;             PG8_WAIT_V(8); PG8_WAIT_L(0); PG8_BAR; PG8_MMA(1, 0, At, B0); PG8_MMA(1, 1, At, B1); PG8_BAR; PG8_SCHED;
;     ...
;         if constexpr (ALIGN_EPI) { if (wr == 0) PG8_BAR; }
	s_add_i32 s26, s55, s2
	v_lshl_add_u64 v[244:245], v[244:245], 0, s[12:13]
	s_mov_b32 m0, s26
	ds_read_b128 v[194:197], v148 offset:49152
	ds_read_b128 v[198:201], v148 offset:50176
	ds_read_b128 v[202:205], v148 offset:51200
	ds_read_b128 v[206:209], v148 offset:52224
	ds_read_b128 v[210:213], v148 offset:53248
	ds_read_b128 v[232:235], v148 offset:54272
	ds_read_b128 v[236:239], v148 offset:55296
	ds_read_b128 v[240:243], v148 offset:56320
	global_load_lds_dwordx4 v[244:245], off
	s_add_i32 m0, s26, 0x2000
	s_add_u32 s24, s24, 0x160080
	v_lshl_add_u64 v[244:245], v[246:247], 0, s[12:13]
	s_addc_u32 s25, s25, 0
	s_add_i32 s26, s56, s2
	global_load_lds_dwordx4 v[244:245], off
	v_lshl_add_u64 v[244:245], s[24:25], 0, v[174:175]
	s_mov_b32 m0, s26
	s_nop 0
	global_load_lds_dwordx4 v[244:245], off
	v_lshl_add_u64 v[244:245], s[24:25], 0, v[176:177]
	s_add_i32 m0, s26, 0x2000
	s_nop 0
	global_load_lds_dwordx4 v[244:245], off
	v_lshl_add_u64 v[244:245], v[248:249], 0, s[12:13]
	s_mov_b32 m0, s31
	s_nop 0
	global_load_lds_dwordx4 v[244:245], off
	v_lshl_add_u64 v[244:245], v[250:251], 0, s[12:13]
	s_mov_b32 m0, s33
	s_nop 0
	global_load_lds_dwordx4 v[244:245], off
	s_waitcnt vmcnt(8)
	s_waitcnt lgkmcnt(0)
	s_barrier
	s_setprio 1
	s_waitcnt lgkmcnt(0)
	v_mfma_f32_16x16x32_bf16 v[62:65], v[136:139], v[194:197], v[62:65]
	v_mfma_f32_16x16x32_bf16 v[58:61], v[154:157], v[194:197], v[58:61]
	v_mfma_f32_16x16x32_bf16 v[54:57], v[136:139], v[202:205], v[54:57]
	v_mfma_f32_16x16x32_bf16 v[50:53], v[154:157], v[202:205], v[50:53]
	v_mfma_f32_16x16x32_bf16 v[38:41], v[136:139], v[210:213], v[38:41]
	v_mfma_f32_16x16x32_bf16 v[34:37], v[154:157], v[210:213], v[34:37]
	v_mfma_f32_16x16x32_bf16 v[22:25], v[136:139], v[236:239], v[22:25]
	v_mfma_f32_16x16x32_bf16 v[18:21], v[154:157], v[236:239], v[18:21]
	v_mfma_f32_16x16x32_bf16 v[62:65], v[150:153], v[198:201], v[62:65]
	v_mfma_f32_16x16x32_bf16 v[58:61], v[158:161], v[198:201], v[58:61]
	v_mfma_f32_16x16x32_bf16 v[54:57], v[150:153], v[206:209], v[54:57]
	v_mfma_f32_16x16x32_bf16 v[50:53], v[158:161], v[206:209], v[50:53]
	v_mfma_f32_16x16x32_bf16 v[38:41], v[150:153], v[232:235], v[38:41]
	v_mfma_f32_16x16x32_bf16 v[34:37], v[158:161], v[232:235], v[34:37]
	v_mfma_f32_16x16x32_bf16 v[22:25], v[150:153], v[240:243], v[22:25]
	v_mfma_f32_16x16x32_bf16 v[18:21], v[158:161], v[240:243], v[18:21]
	s_setprio 0
	s_setprio 1
	v_mfma_f32_16x16x32_bf16 v[46:49], v[178:181], v[194:197], v[46:49]
	v_mfma_f32_16x16x32_bf16 v[42:45], v[186:189], v[194:197], v[42:45]
	v_mfma_f32_16x16x32_bf16 v[30:33], v[178:181], v[202:205], v[30:33]
	v_mfma_f32_16x16x32_bf16 v[26:29], v[186:189], v[202:205], v[26:29]
	v_mfma_f32_16x16x32_bf16 v[14:17], v[178:181], v[210:213], v[14:17]
	v_mfma_f32_16x16x32_bf16 v[10:13], v[186:189], v[210:213], v[10:13]
	v_mfma_f32_16x16x32_bf16 v[6:9], v[178:181], v[236:239], v[6:9]
	v_mfma_f32_16x16x32_bf16 v[2:5], v[186:189], v[236:239], v[2:5]
	v_mfma_f32_16x16x32_bf16 v[46:49], v[182:185], v[198:201], v[46:49]
	v_mfma_f32_16x16x32_bf16 v[42:45], v[190:193], v[198:201], v[42:45]
	v_mfma_f32_16x16x32_bf16 v[30:33], v[182:185], v[206:209], v[30:33]
	v_mfma_f32_16x16x32_bf16 v[26:29], v[190:193], v[206:209], v[26:29]
	v_mfma_f32_16x16x32_bf16 v[14:17], v[182:185], v[232:235], v[14:17]
	v_mfma_f32_16x16x32_bf16 v[10:13], v[190:193], v[232:235], v[10:13]
	v_mfma_f32_16x16x32_bf16 v[6:9], v[182:185], v[240:243], v[6:9]
	v_mfma_f32_16x16x32_bf16 v[2:5], v[190:193], v[240:243], v[2:5]
	s_setprio 0
	s_add_u32 s22, s22, 0x100
	s_addc_u32 s23, s23, 0
	s_add_u32 s51, s51, 0x100
	s_addc_u32 s53, s53, 0
	s_cmp_ge_u32 s54, s43
	s_mov_b32 s24, s54
	s_barrier
	s_cbranch_scc0 .LBB0_281
	s_and_b64 vcc, exec, s[14:15]
	s_cbranch_vccz .LBB0_284
	s_barrier

; #define PG8_STAGE(bufoff, gbase, voff) do { _Pragma("unroll") for (int _i = 0; _i < 2; ++_i) \
;         __builtin_amdgcn_global_load_lds((const unsigned*)((const char*)(gbase) + (voff)[_i]), (PG8_LAS unsigned*)(lds + (bufoff) + ldsw + _i * 8192), 16, 0, 0); } while (0)
; #define PG8_LDA(dst, b, h) do { _Pragma("unroll") for (int m = 0; m < 4; ++m) _Pragma("unroll") for (int k = 0; k < 2; ++k) dst[m][k] = *(const PG8_LAS bf16x8*)(lds + PG8_SA(b, h) + aoff + m * 2048 + k * 1024); } while (0)
; #define PG8_LDB(dst, b, h) do { _Pragma("unroll") for (int n = 0; n < 2; ++n) _Pragma("unroll") for (int k = 0; k < 2; ++k) dst[n][k] = *(const PG8_LAS bf16x8*)(lds + PG8_SB(b, h) + boff + n * 2048 + k * 1024); } while (0)
; #define PG8_MMA(ai, bj, At, Bt) do { __builtin_amdgcn_s_setprio(1); _Pragma("unroll") for (int m = 0; m < 4; ++m) _Pragma("unroll") for (int n = 0; n < 2; ++n) _Pragma("unroll") for (int k = 0; k < 2; ++k) \
;         acc[ai][bj][m][n] = __builtin_amdgcn_mfma_f32_16x16x32_bf16(Bt[n][k], At[m][k], acc[ai][bj][m][n], 0, 0, 0); __builtin_amdgcn_s_setprio(0); } while (0)
; #define PG8_WAIT_V(n) asm volatile("s_waitcnt vmcnt(" #n ")" ::: "memory")
; #define PG8_BAR __builtin_amdgcn_s_barrier()
; template <class Epi, class Sched, bool ALIGN_EPI = false, bool SP2 = false>
; __device__ __forceinline__ void gemm_phase(PG8_LAS unsigned char* lds, const Gemm g, const Sched& S, const Epi& E) {
;     ...
;         for (int t = 0; t < nt; t += 2) {
;             const bool last = (t == nt - 2);
;             const char* a1 = cA + (size_t)(t + 1) * kstep;
;             const char* a2 = last ? nA : cA + (size_t)(t + 2) * kstep; const char* b2 = last ? nB : cB + (size_t)(t + 2) * kstep;
;             const char* a3 = a2 + kstep; const char* b3 = b2 + kstep;
;             if (last && has_next) S.a_ready(nxt);
;             if constexpr (SP2) {
;             PG8_LDB(B0, 0, 0); PG8_LDB(B1, 0, 1); PG8_SCHED; PG8_LDA(At, 0, 0); PG8_STAGE(PG8_SA(1, 1), a1 + hstep, voffA);
;             PG8_WAIT_V(8); PG8_WAIT_L(0); PG8_BAR; PG8_MMA(0, 0, At, B0); PG8_MMA(0, 1, At, B1); PG8_BAR; PG8_SCHED;
;             PG8_LDA(At, 0, 1); PG8_STAGE(PG8_SB(0, 0), b2, voffB); PG8_STAGE(PG8_SB(0, 1), b2 + hstep, voffB); PG8_STAGE(PG8_SA(0, 0), a2, voffA);
;             PG8_WAIT_V(8); PG8_WAIT_L(0); PG8_BAR; PG8_MMA(1, 0, At, B0); PG8_MMA(1, 1, At, B1); PG8_BAR; PG8_SCHED;
.LBB0_423:
	ds_read_b128 v[146:149], v139
	ds_read_b128 v[150:153], v139 offset:1024
	ds_read_b128 v[154:157], v139 offset:2048
	ds_read_b128 v[158:161], v139 offset:3072
	ds_read_b128 v[180:183], v143
	ds_read_b128 v[184:187], v143 offset:1024
	ds_read_b128 v[188:191], v143 offset:2048
	ds_read_b128 v[192:195], v143 offset:3072
	s_add_i32 s49, s48, 2
	s_add_u32 s24, s4, 0xfff80080
	s_addc_u32 s25, s5, -1
	s_cmp_eq_u32 s45, s48
	s_cselect_b32 s27, s19, s25
	s_cselect_b32 s26, s43, s24
	s_cselect_b32 s25, s17, s47
	s_cselect_b32 s24, s44, s46
	v_lshl_add_u64 v[212:213], s[4:5], 0, v[130:131]
	s_add_i32 m0, s15, 0xc000
	ds_read_b128 v[196:199], v144
	ds_read_b128 v[200:203], v144 offset:1024
	ds_read_b128 v[204:207], v144 offset:2048
	ds_read_b128 v[208:211], v144 offset:3072
	ds_read_b128 v[232:235], v144 offset:4096
	ds_read_b128 v[236:239], v144 offset:5120
	ds_read_b128 v[240:243], v144 offset:6144
	ds_read_b128 v[244:247], v144 offset:7168
	global_load_lds_dwordx4 v[212:213], off
	v_lshl_add_u64 v[212:213], s[4:5], 0, v[132:133]
	s_add_i32 m0, s15, 0xe000
	s_nop 0
	global_load_lds_dwordx4 v[212:213], off
	s_waitcnt vmcnt(8)
	s_waitcnt lgkmcnt(0)
	s_barrier
	s_setprio 1
	s_waitcnt lgkmcnt(0)
	v_mfma_f32_16x16x32_bf16 v[126:129], v[146:149], v[196:199], v[126:129]
	v_mfma_f32_16x16x32_bf16 v[122:125], v[154:157], v[196:199], v[122:125]
	v_mfma_f32_16x16x32_bf16 v[118:121], v[146:149], v[204:207], v[118:121]
	v_mfma_f32_16x16x32_bf16 v[114:117], v[154:157], v[204:207], v[114:117]
	v_mfma_f32_16x16x32_bf16 v[102:105], v[146:149], v[232:235], v[102:105]
	v_mfma_f32_16x16x32_bf16 v[98:101], v[154:157], v[232:235], v[98:101]
	v_mfma_f32_16x16x32_bf16 v[86:89], v[146:149], v[240:243], v[86:89]
	v_mfma_f32_16x16x32_bf16 v[82:85], v[154:157], v[240:243], v[82:85]
	v_mfma_f32_16x16x32_bf16 v[126:129], v[150:153], v[200:203], v[126:129]
	v_mfma_f32_16x16x32_bf16 v[122:125], v[158:161], v[200:203], v[122:125]
	v_mfma_f32_16x16x32_bf16 v[118:121], v[150:153], v[208:211], v[118:121]
	v_mfma_f32_16x16x32_bf16 v[114:117], v[158:161], v[208:211], v[114:117]
	v_mfma_f32_16x16x32_bf16 v[102:105], v[150:153], v[236:239], v[102:105]
	v_mfma_f32_16x16x32_bf16 v[98:101], v[158:161], v[236:239], v[98:101]
	v_mfma_f32_16x16x32_bf16 v[86:89], v[150:153], v[244:247], v[86:89]
	v_mfma_f32_16x16x32_bf16 v[82:85], v[158:161], v[244:247], v[82:85]
	s_setprio 0
	s_setprio 1
	v_mfma_f32_16x16x32_bf16 v[110:113], v[180:183], v[196:199], v[110:113]
	v_mfma_f32_16x16x32_bf16 v[106:109], v[188:191], v[196:199], v[106:109]
	v_mfma_f32_16x16x32_bf16 v[94:97], v[180:183], v[204:207], v[94:97]
	v_mfma_f32_16x16x32_bf16 v[90:93], v[188:191], v[204:207], v[90:93]
	v_mfma_f32_16x16x32_bf16 v[78:81], v[180:183], v[232:235], v[78:81]
	v_mfma_f32_16x16x32_bf16 v[74:77], v[188:191], v[232:235], v[74:77]
	v_mfma_f32_16x16x32_bf16 v[70:73], v[180:183], v[240:243], v[70:73]
	v_mfma_f32_16x16x32_bf16 v[66:69], v[188:191], v[240:243], v[66:69]
	v_mfma_f32_16x16x32_bf16 v[110:113], v[184:187], v[200:203], v[110:113]
	v_mfma_f32_16x16x32_bf16 v[106:109], v[192:195], v[200:203], v[106:109]
	v_mfma_f32_16x16x32_bf16 v[94:97], v[184:187], v[208:211], v[94:97]
	v_mfma_f32_16x16x32_bf16 v[90:93], v[192:195], v[208:211], v[90:93]
	v_mfma_f32_16x16x32_bf16 v[78:81], v[184:187], v[236:239], v[78:81]
	v_mfma_f32_16x16x32_bf16 v[74:77], v[192:195], v[236:239], v[74:77]
	v_mfma_f32_16x16x32_bf16 v[70:73], v[184:187], v[244:247], v[70:73]
	v_mfma_f32_16x16x32_bf16 v[66:69], v[192:195], v[244:247], v[66:69]
	s_setprio 0
	s_barrier
	s_add_i32 s48, s37, s2
	v_lshl_add_u64 v[212:213], s[24:25], 0, v[168:169]
	s_mov_b32 m0, s48
	ds_read_b128 v[196:199], v144 offset:16384
	ds_read_b128 v[200:203], v144 offset:17408
	ds_read_b128 v[204:207], v144 offset:18432
	ds_read_b128 v[208:211], v144 offset:19456
	ds_read_b128 v[232:235], v144 offset:20480
	ds_read_b128 v[236:239], v144 offset:21504
	ds_read_b128 v[240:243], v144 offset:22528
	ds_read_b128 v[244:247], v144 offset:23552
	global_load_lds_dwordx4 v[212:213], off
	s_add_i32 m0, s48, 0x2000
	s_add_u32 s50, s24, 0x80000
	v_lshl_add_u64 v[248:249], s[24:25], 0, v[172:173]
	s_addc_u32 s51, s25, 0
	s_add_i32 s48, s38, s2
	global_load_lds_dwordx4 v[248:249], off
	v_lshl_add_u64 v[250:251], s[50:51], 0, v[168:169]
	s_mov_b32 m0, s48
	v_lshl_add_u64 v[252:253], s[26:27], 0, v[170:171]
	global_load_lds_dwordx4 v[250:251], off
	v_lshl_add_u64 v[250:251], s[50:51], 0, v[172:173]
	s_add_i32 m0, s48, 0x2000
	s_nop 0
	global_load_lds_dwordx4 v[250:251], off
	v_lshl_add_u64 v[250:251], s[26:27], 0, v[166:167]
	s_mov_b32 m0, s15
	s_nop 0
	global_load_lds_dwordx4 v[250:251], off
	s_mov_b32 m0, s29
	s_nop 0
	global_load_lds_dwordx4 v[252:253], off
	s_waitcnt vmcnt(8)
	s_waitcnt lgkmcnt(0)
	s_barrier
; #define PG8_STAGE(bufoff, gbase, voff) do { _Pragma("unroll") for (int _i = 0; _i < 2; ++_i) \
;         __builtin_amdgcn_global_load_lds((const unsigned*)((const char*)(gbase) + (voff)[_i]), (PG8_LAS unsigned*)(lds + (bufoff) + ldsw + _i * 8192), 16, 0, 0); } while (0)
; #define PG8_LDA(dst, b, h) do { _Pragma("unroll") for (int m = 0; m < 4; ++m) _Pragma("unroll") for (int k = 0; k < 2; ++k) dst[m][k] = *(const PG8_LAS bf16x8*)(lds + PG8_SA(b, h) + aoff + m * 2048 + k * 1024); } while (0)
; #define PG8_LDB(dst, b, h) do { _Pragma("unroll") for (int n = 0; n < 2; ++n) _Pragma("unroll") for (int k = 0; k < 2; ++k) dst[n][k] = *(const PG8_LAS bf16x8*)(lds + PG8_SB(b, h) + boff + n * 2048 + k * 1024); } while (0)
; #define PG8_MMA(ai, bj, At, Bt) do { __builtin_amdgcn_s_setprio(1); _Pragma("unroll") for (int m = 0; m < 4; ++m) _Pragma("unroll") for (int n = 0; n < 2; ++n) _Pragma("unroll") for (int k = 0; k < 2; ++k) \
;         acc[ai][bj][m][n] = __builtin_amdgcn_mfma_f32_16x16x32_bf16(Bt[n][k], At[m][k], acc[ai][bj][m][n], 0, 0, 0); __builtin_amdgcn_s_setprio(0); } while (0)
; #define PG8_WAIT_V(n) asm volatile("s_waitcnt vmcnt(" #n ")" ::: "memory")
; #define PG8_WAIT_L(n) asm volatile("s_waitcnt lgkmcnt(" #n ")" ::: "memory")
; #define PG8_BAR __builtin_amdgcn_s_barrier()
; #define PG8_SCHED __builtin_amdgcn_sched_barrier(0)
; template <class Epi, class Sched, bool ALIGN_EPI = false, bool SP2 = false>
; __device__ __forceinline__ void gemm_phase(PG8_LAS unsigned char* lds, const Gemm g, const Sched& S, const Epi& E) {
;     ...
;             PG8_WAIT_V(8); PG8_WAIT_L(0); PG8_BAR; PG8_MMA(1, 0, At, B0); PG8_MMA(1, 1, At, B1); PG8_BAR; PG8_SCHED;
;             PG8_LDB(B0, 1, 0); PG8_LDB(B1, 1, 1); PG8_SCHED; PG8_LDA(At, 1, 0); PG8_STAGE(PG8_SA(0, 1), a2 + hstep, voffA);
;             PG8_WAIT_V(8); PG8_WAIT_L(0); PG8_BAR; PG8_MMA(0, 0, At, B0); PG8_MMA(0, 1, At, B1); PG8_BAR; PG8_SCHED;
;             PG8_LDA(At, 1, 1); PG8_STAGE(PG8_SB(1, 0), b3, voffB); PG8_STAGE(PG8_SB(1, 1), b3 + hstep, voffB); PG8_STAGE(PG8_SA(1, 0), a3, voffA);
	s_setprio 1
	s_waitcnt lgkmcnt(0)
	v_mfma_f32_16x16x32_bf16 v[62:65], v[146:149], v[196:199], v[62:65]
	v_mfma_f32_16x16x32_bf16 v[58:61], v[154:157], v[196:199], v[58:61]
	v_mfma_f32_16x16x32_bf16 v[54:57], v[146:149], v[204:207], v[54:57]
	v_mfma_f32_16x16x32_bf16 v[50:53], v[154:157], v[204:207], v[50:53]
	v_mfma_f32_16x16x32_bf16 v[38:41], v[146:149], v[232:235], v[38:41]
	v_mfma_f32_16x16x32_bf16 v[34:37], v[154:157], v[232:235], v[34:37]
	v_mfma_f32_16x16x32_bf16 v[22:25], v[146:149], v[240:243], v[22:25]
	v_mfma_f32_16x16x32_bf16 v[18:21], v[154:157], v[240:243], v[18:21]
	v_mfma_f32_16x16x32_bf16 v[62:65], v[150:153], v[200:203], v[62:65]
	v_mfma_f32_16x16x32_bf16 v[58:61], v[158:161], v[200:203], v[58:61]
	v_mfma_f32_16x16x32_bf16 v[54:57], v[150:153], v[208:211], v[54:57]
	v_mfma_f32_16x16x32_bf16 v[50:53], v[158:161], v[208:211], v[50:53]
	v_mfma_f32_16x16x32_bf16 v[38:41], v[150:153], v[236:239], v[38:41]
	v_mfma_f32_16x16x32_bf16 v[34:37], v[158:161], v[236:239], v[34:37]
	v_mfma_f32_16x16x32_bf16 v[22:25], v[150:153], v[244:247], v[22:25]
	v_mfma_f32_16x16x32_bf16 v[18:21], v[158:161], v[244:247], v[18:21]
	s_setprio 0
	s_setprio 1
	v_mfma_f32_16x16x32_bf16 v[46:49], v[180:183], v[196:199], v[46:49]
	v_mfma_f32_16x16x32_bf16 v[42:45], v[188:191], v[196:199], v[42:45]
	v_mfma_f32_16x16x32_bf16 v[30:33], v[180:183], v[204:207], v[30:33]
	v_mfma_f32_16x16x32_bf16 v[26:29], v[188:191], v[204:207], v[26:29]
	v_mfma_f32_16x16x32_bf16 v[14:17], v[180:183], v[232:235], v[14:17]
	v_mfma_f32_16x16x32_bf16 v[10:13], v[188:191], v[232:235], v[10:13]
	v_mfma_f32_16x16x32_bf16 v[6:9], v[180:183], v[240:243], v[6:9]
	v_mfma_f32_16x16x32_bf16 v[2:5], v[188:191], v[240:243], v[2:5]
	v_mfma_f32_16x16x32_bf16 v[46:49], v[184:187], v[200:203], v[46:49]
	v_mfma_f32_16x16x32_bf16 v[42:45], v[192:195], v[200:203], v[42:45]
	v_mfma_f32_16x16x32_bf16 v[30:33], v[184:187], v[208:211], v[30:33]
	v_mfma_f32_16x16x32_bf16 v[26:29], v[192:195], v[208:211], v[26:29]
	v_mfma_f32_16x16x32_bf16 v[14:17], v[184:187], v[236:239], v[14:17]
	v_mfma_f32_16x16x32_bf16 v[10:13], v[192:195], v[236:239], v[10:13]
	v_mfma_f32_16x16x32_bf16 v[6:9], v[184:187], v[244:247], v[6:9]
	v_mfma_f32_16x16x32_bf16 v[2:5], v[192:195], v[244:247], v[2:5]
	s_setprio 0
	s_barrier
	s_add_i32 s48, 0, 0x18000
	v_add_u32_e32 v145, s48, v137
	s_add_i32 s50, 0, 0x1c000
	ds_read_b128 v[146:149], v145
	ds_read_b128 v[150:153], v145 offset:1024
	ds_read_b128 v[154:157], v145 offset:2048
	ds_read_b128 v[158:161], v145 offset:3072
	v_add_u32_e32 v145, s50, v137
	ds_read_b128 v[180:183], v145
	ds_read_b128 v[184:187], v145 offset:1024
	ds_read_b128 v[188:191], v145 offset:2048
	ds_read_b128 v[192:195], v145 offset:3072
	s_add_u32 s26, s26, 0x80000
	s_addc_u32 s27, s27, 0
	s_mov_b32 m0, s30
	v_lshl_add_u64 v[222:223], s[26:27], 0, v[166:167]
	ds_read_b128 v[196:199], v144 offset:32768
	ds_read_b128 v[200:203], v144 offset:33792
	ds_read_b128 v[204:207], v144 offset:34816
	ds_read_b128 v[208:211], v144 offset:35840
	ds_read_b128 v[232:235], v144 offset:36864
	ds_read_b128 v[236:239], v144 offset:37888
	ds_read_b128 v[240:243], v144 offset:38912
	ds_read_b128 v[244:247], v144 offset:39936
	global_load_lds_dwordx4 v[222:223], off
	v_lshl_add_u64 v[222:223], s[26:27], 0, v[170:171]
	s_mov_b32 m0, s31
	s_nop 0
	global_load_lds_dwordx4 v[222:223], off
	s_waitcnt vmcnt(8)
	s_waitcnt lgkmcnt(0)
	s_barrier
	s_setprio 1
	s_waitcnt lgkmcnt(0)
	v_mfma_f32_16x16x32_bf16 v[126:129], v[146:149], v[196:199], v[126:129]
	v_mfma_f32_16x16x32_bf16 v[122:125], v[154:157], v[196:199], v[122:125]
	v_mfma_f32_16x16x32_bf16 v[118:121], v[146:149], v[204:207], v[118:121]
	v_mfma_f32_16x16x32_bf16 v[114:117], v[154:157], v[204:207], v[114:117]
	v_mfma_f32_16x16x32_bf16 v[102:105], v[146:149], v[232:235], v[102:105]
	v_mfma_f32_16x16x32_bf16 v[98:101], v[154:157], v[232:235], v[98:101]
	v_mfma_f32_16x16x32_bf16 v[86:89], v[146:149], v[240:243], v[86:89]
	v_mfma_f32_16x16x32_bf16 v[82:85], v[154:157], v[240:243], v[82:85]
	v_mfma_f32_16x16x32_bf16 v[126:129], v[150:153], v[200:203], v[126:129]
	v_mfma_f32_16x16x32_bf16 v[122:125], v[158:161], v[200:203], v[122:125]
	v_mfma_f32_16x16x32_bf16 v[118:121], v[150:153], v[208:211], v[118:121]
	v_mfma_f32_16x16x32_bf16 v[114:117], v[158:161], v[208:211], v[114:117]
	v_mfma_f32_16x16x32_bf16 v[102:105], v[150:153], v[236:239], v[102:105]
	v_mfma_f32_16x16x32_bf16 v[98:101], v[158:161], v[236:239], v[98:101]
	v_mfma_f32_16x16x32_bf16 v[86:89], v[150:153], v[244:247], v[86:89]
	v_mfma_f32_16x16x32_bf16 v[82:85], v[158:161], v[244:247], v[82:85]
	s_setprio 0
	s_setprio 1
	v_mfma_f32_16x16x32_bf16 v[110:113], v[180:183], v[196:199], v[110:113]
	v_mfma_f32_16x16x32_bf16 v[106:109], v[188:191], v[196:199], v[106:109]
	v_mfma_f32_16x16x32_bf16 v[94:97], v[180:183], v[204:207], v[94:97]
	v_mfma_f32_16x16x32_bf16 v[90:93], v[188:191], v[204:207], v[90:93]
	v_mfma_f32_16x16x32_bf16 v[78:81], v[180:183], v[232:235], v[78:81]
	v_mfma_f32_16x16x32_bf16 v[74:77], v[188:191], v[232:235], v[74:77]
	v_mfma_f32_16x16x32_bf16 v[70:73], v[180:183], v[240:243], v[70:73]
	v_mfma_f32_16x16x32_bf16 v[66:69], v[188:191], v[240:243], v[66:69]
	v_mfma_f32_16x16x32_bf16 v[110:113], v[184:187], v[200:203], v[110:113]
	v_mfma_f32_16x16x32_bf16 v[106:109], v[192:195], v[200:203], v[106:109]
	v_mfma_f32_16x16x32_bf16 v[94:97], v[184:187], v[208:211], v[94:97]
	v_mfma_f32_16x16x32_bf16 v[90:93], v[192:195], v[208:211], v[90:93]
	v_mfma_f32_16x16x32_bf16 v[78:81], v[184:187], v[236:239], v[78:81]
	v_mfma_f32_16x16x32_bf16 v[74:77], v[192:195], v[236:239], v[74:77]
	v_mfma_f32_16x16x32_bf16 v[70:73], v[184:187], v[244:247], v[70:73]
	v_mfma_f32_16x16x32_bf16 v[66:69], v[192:195], v[244:247], v[66:69]
	s_setprio 0
	s_barrier
; #define PG8_STAGE(bufoff, gbase, voff) do { _Pragma("unroll") for (int _i = 0; _i < 2; ++_i) \
;         __builtin_amdgcn_global_load_lds((const unsigned*)((const char*)(gbase) + (voff)[_i]), (PG8_LAS unsigned*)(lds + (bufoff) + ldsw + _i * 8192), 16, 0, 0); } while (0)
; #define PG8_LDA(dst, b, h) do { _Pragma("unroll") for (int m = 0; m < 4; ++m) _Pragma("unroll") for (int k = 0; k < 2; ++k) dst[m][k] = *(const PG8_LAS bf16x8*)(lds + PG8_SA(b, h) + aoff + m * 2048 + k * 1024); } while (0)
; #define PG8_MMA(ai, bj, At, Bt) do { __builtin_amdgcn_s_setprio(1); _Pragma("unroll") for (int m = 0; m < 4; ++m) _Pragma("unroll") for (int n = 0; n < 2; ++n) _Pragma("unroll") for (int k = 0; k < 2; ++k) \
;         acc[ai][bj][m][n] = __builtin_amdgcn_mfma_f32_16x16x32_bf16(Bt[n][k], At[m][k], acc[ai][bj][m][n], 0, 0, 0); __builtin_amdgcn_s_setprio(0); } while (0)
; #define PG8_WAIT_V(n) asm volatile("s_waitcnt vmcnt(" #n ")" ::: "memory")
; #define PG8_WAIT_L(n) asm volatile("s_waitcnt lgkmcnt(" #n ")" ::: "memory")
; #define PG8_BAR __builtin_amdgcn_s_barrier()
; #define PG8_SCHED __builtin_amdgcn_sched_barrier(0)
; template <class Epi, class Sched, bool ALIGN_EPI = false, bool SP2 = false>
; __device__ __forceinline__ void gemm_phase(PG8_LAS unsigned char* lds, const Gemm g, const Sched& S, const Epi& E) {
;     ...
;         for (int t = 0; t < nt; t += 2) {
;             const bool last = (t == nt - 2);
;             const char* a1 = cA + (size_t)(t + 1) * kstep;
;             const char* a2 = last ? nA : cA + (size_t)(t + 2) * kstep; const char* b2 = last ? nB : cB + (size_t)(t + 2) * kstep;
;     ...
;             PG8_LDA(At, 1, 1); PG8_STAGE(PG8_SB(1, 0), b3, voffB); PG8_STAGE(PG8_SB(1, 1), b3 + hstep, voffB); PG8_STAGE(PG8_SA(1, 0), a3, voffA);
;             PG8_WAIT_V(8); PG8_WAIT_L(0); PG8_BAR; PG8_MMA(1, 0, At, B0); PG8_MMA(1, 1, At, B1); PG8_BAR; PG8_SCHED;
	s_add_i32 s26, s48, s2
	v_lshl_add_u64 v[212:213], v[212:213], 0, s[10:11]
	s_mov_b32 m0, s26
	ds_read_b128 v[196:199], v144 offset:49152
	ds_read_b128 v[200:203], v144 offset:50176
	ds_read_b128 v[204:207], v144 offset:51200
	ds_read_b128 v[208:211], v144 offset:52224
	ds_read_b128 v[232:235], v144 offset:53248
	ds_read_b128 v[236:239], v144 offset:54272
	ds_read_b128 v[240:243], v144 offset:55296
	ds_read_b128 v[244:247], v144 offset:56320
	global_load_lds_dwordx4 v[212:213], off
	s_add_i32 m0, s26, 0x2000
	s_add_u32 s24, s24, 0x80080
	v_lshl_add_u64 v[212:213], v[248:249], 0, s[10:11]
	s_addc_u32 s25, s25, 0
	s_add_i32 s26, s50, s2
	global_load_lds_dwordx4 v[212:213], off
	v_lshl_add_u64 v[212:213], s[24:25], 0, v[168:169]
	s_mov_b32 m0, s26
	s_nop 0
	global_load_lds_dwordx4 v[212:213], off
	v_lshl_add_u64 v[212:213], s[24:25], 0, v[172:173]
	s_add_i32 m0, s26, 0x2000
	s_nop 0
	global_load_lds_dwordx4 v[212:213], off
	v_lshl_add_u64 v[212:213], v[250:251], 0, s[10:11]
	s_mov_b32 m0, s34
	s_nop 0
	global_load_lds_dwordx4 v[212:213], off
	v_lshl_add_u64 v[212:213], v[252:253], 0, s[10:11]
	s_mov_b32 m0, s35
	s_nop 0
	global_load_lds_dwordx4 v[212:213], off
	s_waitcnt vmcnt(8)
	s_waitcnt lgkmcnt(0)
	s_barrier
	s_setprio 1
	s_waitcnt lgkmcnt(0)
	v_mfma_f32_16x16x32_bf16 v[62:65], v[146:149], v[196:199], v[62:65]
	v_mfma_f32_16x16x32_bf16 v[58:61], v[154:157], v[196:199], v[58:61]
	v_mfma_f32_16x16x32_bf16 v[54:57], v[146:149], v[204:207], v[54:57]
	v_mfma_f32_16x16x32_bf16 v[50:53], v[154:157], v[204:207], v[50:53]
	v_mfma_f32_16x16x32_bf16 v[38:41], v[146:149], v[232:235], v[38:41]
	v_mfma_f32_16x16x32_bf16 v[34:37], v[154:157], v[232:235], v[34:37]
	v_mfma_f32_16x16x32_bf16 v[22:25], v[146:149], v[240:243], v[22:25]
	v_mfma_f32_16x16x32_bf16 v[18:21], v[154:157], v[240:243], v[18:21]
	v_mfma_f32_16x16x32_bf16 v[62:65], v[150:153], v[200:203], v[62:65]
	v_mfma_f32_16x16x32_bf16 v[58:61], v[158:161], v[200:203], v[58:61]
	v_mfma_f32_16x16x32_bf16 v[54:57], v[150:153], v[208:211], v[54:57]
	v_mfma_f32_16x16x32_bf16 v[50:53], v[158:161], v[208:211], v[50:53]
	v_mfma_f32_16x16x32_bf16 v[38:41], v[150:153], v[236:239], v[38:41]
	v_mfma_f32_16x16x32_bf16 v[34:37], v[158:161], v[236:239], v[34:37]
	v_mfma_f32_16x16x32_bf16 v[22:25], v[150:153], v[244:247], v[22:25]
	v_mfma_f32_16x16x32_bf16 v[18:21], v[158:161], v[244:247], v[18:21]
	s_setprio 0
	s_setprio 1
	v_mfma_f32_16x16x32_bf16 v[46:49], v[180:183], v[196:199], v[46:49]
	v_mfma_f32_16x16x32_bf16 v[42:45], v[188:191], v[196:199], v[42:45]
	v_mfma_f32_16x16x32_bf16 v[30:33], v[180:183], v[204:207], v[30:33]
	v_mfma_f32_16x16x32_bf16 v[26:29], v[188:191], v[204:207], v[26:29]
	v_mfma_f32_16x16x32_bf16 v[14:17], v[180:183], v[232:235], v[14:17]
	v_mfma_f32_16x16x32_bf16 v[10:13], v[188:191], v[232:235], v[10:13]
	v_mfma_f32_16x16x32_bf16 v[6:9], v[180:183], v[240:243], v[6:9]
	v_mfma_f32_16x16x32_bf16 v[2:5], v[188:191], v[240:243], v[2:5]
	v_mfma_f32_16x16x32_bf16 v[46:49], v[184:187], v[200:203], v[46:49]
	v_mfma_f32_16x16x32_bf16 v[42:45], v[192:195], v[200:203], v[42:45]
	v_mfma_f32_16x16x32_bf16 v[30:33], v[184:187], v[208:211], v[30:33]
	v_mfma_f32_16x16x32_bf16 v[26:29], v[192:195], v[208:211], v[26:29]
	v_mfma_f32_16x16x32_bf16 v[14:17], v[184:187], v[236:239], v[14:17]
	v_mfma_f32_16x16x32_bf16 v[10:13], v[192:195], v[236:239], v[10:13]
	v_mfma_f32_16x16x32_bf16 v[6:9], v[184:187], v[244:247], v[6:9]
	v_mfma_f32_16x16x32_bf16 v[2:5], v[192:195], v[244:247], v[2:5]
	s_setprio 0
	s_add_u32 s4, s4, 0x100
	s_addc_u32 s5, s5, 0
	s_add_u32 s46, s46, 0x100
	s_addc_u32 s47, s47, 0
	s_cmp_ge_u32 s49, s41
	s_mov_b32 s48, s49
	s_barrier
	s_cbranch_scc0 .LBB0_423
	s_and_b64 vcc, exec, s[12:13]
	s_cbranch_vccz .LBB0_426
	s_barrier

; #define PG8_STAGE(bufoff, gbase, voff) do { _Pragma("unroll") for (int _i = 0; _i < 2; ++_i) \
;         __builtin_amdgcn_global_load_lds((const unsigned*)((const char*)(gbase) + (voff)[_i]), (PG8_LAS unsigned*)(lds + (bufoff) + ldsw + _i * 8192), 16, 0, 0); } while (0)
; #define PG8_LDA(dst, b, h) do { _Pragma("unroll") for (int m = 0; m < 4; ++m) _Pragma("unroll") for (int k = 0; k < 2; ++k) dst[m][k] = *(const PG8_LAS bf16x8*)(lds + PG8_SA(b, h) + aoff + m * 2048 + k * 1024); } while (0)
; #define PG8_LDB(dst, b, h) do { _Pragma("unroll") for (int n = 0; n < 2; ++n) _Pragma("unroll") for (int k = 0; k < 2; ++k) dst[n][k] = *(const PG8_LAS bf16x8*)(lds + PG8_SB(b, h) + boff + n * 2048 + k * 1024); } while (0)
; #define PG8_MMA(ai, bj, At, Bt) do { __builtin_amdgcn_s_setprio(1); _Pragma("unroll") for (int m = 0; m < 4; ++m) _Pragma("unroll") for (int n = 0; n < 2; ++n) _Pragma("unroll") for (int k = 0; k < 2; ++k) \
;         acc[ai][bj][m][n] = __builtin_amdgcn_mfma_f32_16x16x32_bf16(Bt[n][k], At[m][k], acc[ai][bj][m][n], 0, 0, 0); __builtin_amdgcn_s_setprio(0); } while (0)
; #define PG8_WAIT_V(n) asm volatile("s_waitcnt vmcnt(" #n ")" ::: "memory")
; #define PG8_BAR __builtin_amdgcn_s_barrier()
; template <class Epi, class Sched, bool ALIGN_EPI = false, bool SP2 = false>
; __device__ __forceinline__ void gemm_phase(PG8_LAS unsigned char* lds, const Gemm g, const Sched& S, const Epi& E) {
;     ...
;         for (int t = 0; t < nt; t += 2) {
;             const bool last = (t == nt - 2);
;             const char* a1 = cA + (size_t)(t + 1) * kstep;
;             const char* a2 = last ? nA : cA + (size_t)(t + 2) * kstep; const char* b2 = last ? nB : cB + (size_t)(t + 2) * kstep;
;             const char* a3 = a2 + kstep; const char* b3 = b2 + kstep;
;             if (last && has_next) S.a_ready(nxt);
;             if constexpr (SP2) {
;             PG8_LDB(B0, 0, 0); PG8_LDB(B1, 0, 1); PG8_SCHED; PG8_LDA(At, 0, 0); PG8_STAGE(PG8_SA(1, 1), a1 + hstep, voffA);
;             PG8_WAIT_V(8); PG8_WAIT_L(0); PG8_BAR; PG8_MMA(0, 0, At, B0); PG8_MMA(0, 1, At, B1); PG8_BAR; PG8_SCHED;
;             PG8_LDA(At, 0, 1); PG8_STAGE(PG8_SB(0, 0), b2, voffB); PG8_STAGE(PG8_SB(0, 1), b2 + hstep, voffB); PG8_STAGE(PG8_SA(0, 0), a2, voffA);
;             PG8_WAIT_V(8); PG8_WAIT_L(0); PG8_BAR; PG8_MMA(1, 0, At, B0); PG8_MMA(1, 1, At, B1); PG8_BAR; PG8_SCHED;
.LBB0_892:
	ds_read_b128 v[136:139], v143
	ds_read_b128 v[146:149], v143 offset:1024
	ds_read_b128 v[150:153], v143 offset:2048
	ds_read_b128 v[154:157], v143 offset:3072
	ds_read_b128 v[158:161], v144
	ds_read_b128 v[180:183], v144 offset:1024
	ds_read_b128 v[184:187], v144 offset:2048
	ds_read_b128 v[188:191], v144 offset:3072
	s_add_i32 s53, s28, 2
	s_add_u32 s29, s26, 0xfff80080
	s_addc_u32 s30, s27, -1
	s_cmp_eq_u32 s49, s28
	s_cselect_b32 s28, s48, s51
	s_cselect_b32 s31, s13, s30
	s_cselect_b32 s30, s19, s29
	s_cselect_b32 s29, s17, s52
	v_lshl_add_u64 v[212:213], s[26:27], 0, v[130:131]
	s_add_i32 m0, s3, 0xc000
	ds_read_b128 v[192:195], v145
	ds_read_b128 v[196:199], v145 offset:1024
	ds_read_b128 v[200:203], v145 offset:2048
	ds_read_b128 v[204:207], v145 offset:3072
	ds_read_b128 v[208:211], v145 offset:4096
	ds_read_b128 v[232:235], v145 offset:5120
	ds_read_b128 v[236:239], v145 offset:6144
	ds_read_b128 v[240:243], v145 offset:7168
	global_load_lds_dwordx4 v[212:213], off
	v_lshl_add_u64 v[212:213], s[26:27], 0, v[132:133]
	s_add_i32 m0, s3, 0xe000
	s_nop 0
	global_load_lds_dwordx4 v[212:213], off
	s_waitcnt vmcnt(8)
	s_waitcnt lgkmcnt(0)
	s_barrier
	s_setprio 1
	s_waitcnt lgkmcnt(0)
	v_mfma_f32_16x16x32_bf16 v[126:129], v[136:139], v[192:195], v[126:129]
	v_mfma_f32_16x16x32_bf16 v[122:125], v[150:153], v[192:195], v[122:125]
	v_mfma_f32_16x16x32_bf16 v[118:121], v[136:139], v[200:203], v[118:121]
	v_mfma_f32_16x16x32_bf16 v[114:117], v[150:153], v[200:203], v[114:117]
	v_mfma_f32_16x16x32_bf16 v[102:105], v[136:139], v[208:211], v[102:105]
	v_mfma_f32_16x16x32_bf16 v[98:101], v[150:153], v[208:211], v[98:101]
	v_mfma_f32_16x16x32_bf16 v[86:89], v[136:139], v[236:239], v[86:89]
	v_mfma_f32_16x16x32_bf16 v[82:85], v[150:153], v[236:239], v[82:85]
	v_mfma_f32_16x16x32_bf16 v[126:129], v[146:149], v[196:199], v[126:129]
	v_mfma_f32_16x16x32_bf16 v[122:125], v[154:157], v[196:199], v[122:125]
	v_mfma_f32_16x16x32_bf16 v[118:121], v[146:149], v[204:207], v[118:121]
	v_mfma_f32_16x16x32_bf16 v[114:117], v[154:157], v[204:207], v[114:117]
	v_mfma_f32_16x16x32_bf16 v[102:105], v[146:149], v[232:235], v[102:105]
	v_mfma_f32_16x16x32_bf16 v[98:101], v[154:157], v[232:235], v[98:101]
	v_mfma_f32_16x16x32_bf16 v[86:89], v[146:149], v[240:243], v[86:89]
	v_mfma_f32_16x16x32_bf16 v[82:85], v[154:157], v[240:243], v[82:85]
	s_setprio 0
	s_setprio 1
	v_mfma_f32_16x16x32_bf16 v[110:113], v[158:161], v[192:195], v[110:113]
	v_mfma_f32_16x16x32_bf16 v[106:109], v[184:187], v[192:195], v[106:109]
	v_mfma_f32_16x16x32_bf16 v[94:97], v[158:161], v[200:203], v[94:97]
	v_mfma_f32_16x16x32_bf16 v[90:93], v[184:187], v[200:203], v[90:93]
	v_mfma_f32_16x16x32_bf16 v[78:81], v[158:161], v[208:211], v[78:81]
	v_mfma_f32_16x16x32_bf16 v[74:77], v[184:187], v[208:211], v[74:77]
	v_mfma_f32_16x16x32_bf16 v[70:73], v[158:161], v[236:239], v[70:73]
	v_mfma_f32_16x16x32_bf16 v[66:69], v[184:187], v[236:239], v[66:69]
	v_mfma_f32_16x16x32_bf16 v[110:113], v[180:183], v[196:199], v[110:113]
	v_mfma_f32_16x16x32_bf16 v[106:109], v[188:191], v[196:199], v[106:109]
	v_mfma_f32_16x16x32_bf16 v[94:97], v[180:183], v[204:207], v[94:97]
	v_mfma_f32_16x16x32_bf16 v[90:93], v[188:191], v[204:207], v[90:93]
	v_mfma_f32_16x16x32_bf16 v[78:81], v[180:183], v[232:235], v[78:81]
	v_mfma_f32_16x16x32_bf16 v[74:77], v[188:191], v[232:235], v[74:77]
	v_mfma_f32_16x16x32_bf16 v[70:73], v[180:183], v[240:243], v[70:73]
	v_mfma_f32_16x16x32_bf16 v[66:69], v[188:191], v[240:243], v[66:69]
	s_setprio 0
	s_barrier
	s_add_i32 s54, s42, s2
	v_lshl_add_u64 v[212:213], s[28:29], 0, v[166:167]
	s_mov_b32 m0, s54
	ds_read_b128 v[192:195], v145 offset:16384
	ds_read_b128 v[196:199], v145 offset:17408
	ds_read_b128 v[200:203], v145 offset:18432
	ds_read_b128 v[204:207], v145 offset:19456
	ds_read_b128 v[208:211], v145 offset:20480
	ds_read_b128 v[232:235], v145 offset:21504
	ds_read_b128 v[236:239], v145 offset:22528
	ds_read_b128 v[240:243], v145 offset:23552
	global_load_lds_dwordx4 v[212:213], off
	s_add_i32 m0, s54, 0x2000
	s_add_u32 s54, s28, 0x80000
	v_lshl_add_u64 v[222:223], s[28:29], 0, v[170:171]
	s_addc_u32 s55, s29, 0
	s_add_i32 s56, s43, s2
	global_load_lds_dwordx4 v[222:223], off
	v_lshl_add_u64 v[244:245], s[54:55], 0, v[166:167]
	s_mov_b32 m0, s56
	v_lshl_add_u64 v[246:247], s[30:31], 0, v[170:171]
	global_load_lds_dwordx4 v[244:245], off
	v_lshl_add_u64 v[244:245], s[54:55], 0, v[170:171]
	s_add_i32 m0, s56, 0x2000
	s_nop 0
	global_load_lds_dwordx4 v[244:245], off
	v_lshl_add_u64 v[244:245], s[30:31], 0, v[166:167]
	s_mov_b32 m0, s3
	s_nop 0
	global_load_lds_dwordx4 v[244:245], off
	s_mov_b32 m0, s15
	s_nop 0
	global_load_lds_dwordx4 v[246:247], off
	s_waitcnt vmcnt(8)
	s_waitcnt lgkmcnt(0)
	s_barrier
; #define PG8_STAGE(bufoff, gbase, voff) do { _Pragma("unroll") for (int _i = 0; _i < 2; ++_i) \
;         __builtin_amdgcn_global_load_lds((const unsigned*)((const char*)(gbase) + (voff)[_i]), (PG8_LAS unsigned*)(lds + (bufoff) + ldsw + _i * 8192), 16, 0, 0); } while (0)
; #define PG8_LDA(dst, b, h) do { _Pragma("unroll") for (int m = 0; m < 4; ++m) _Pragma("unroll") for (int k = 0; k < 2; ++k) dst[m][k] = *(const PG8_LAS bf16x8*)(lds + PG8_SA(b, h) + aoff + m * 2048 + k * 1024); } while (0)
; #define PG8_LDB(dst, b, h) do { _Pragma("unroll") for (int n = 0; n < 2; ++n) _Pragma("unroll") for (int k = 0; k < 2; ++k) dst[n][k] = *(const PG8_LAS bf16x8*)(lds + PG8_SB(b, h) + boff + n * 2048 + k * 1024); } while (0)
; #define PG8_MMA(ai, bj, At, Bt) do { __builtin_amdgcn_s_setprio(1); _Pragma("unroll") for (int m = 0; m < 4; ++m) _Pragma("unroll") for (int n = 0; n < 2; ++n) _Pragma("unroll") for (int k = 0; k < 2; ++k) \
;         acc[ai][bj][m][n] = __builtin_amdgcn_mfma_f32_16x16x32_bf16(Bt[n][k], At[m][k], acc[ai][bj][m][n], 0, 0, 0); __builtin_amdgcn_s_setprio(0); } while (0)
; #define PG8_WAIT_V(n) asm volatile("s_waitcnt vmcnt(" #n ")" ::: "memory")
; #define PG8_WAIT_L(n) asm volatile("s_waitcnt lgkmcnt(" #n ")" ::: "memory")
; #define PG8_BAR __builtin_amdgcn_s_barrier()
; #define PG8_SCHED __builtin_amdgcn_sched_barrier(0)
; template <class Epi, class Sched, bool ALIGN_EPI = false, bool SP2 = false>
; __device__ __forceinline__ void gemm_phase(PG8_LAS unsigned char* lds, const Gemm g, const Sched& S, const Epi& E) {
;     ...
;             PG8_WAIT_V(8); PG8_WAIT_L(0); PG8_BAR; PG8_MMA(1, 0, At, B0); PG8_MMA(1, 1, At, B1); PG8_BAR; PG8_SCHED;
;             PG8_LDB(B0, 1, 0); PG8_LDB(B1, 1, 1); PG8_SCHED; PG8_LDA(At, 1, 0); PG8_STAGE(PG8_SA(0, 1), a2 + hstep, voffA);
;             PG8_WAIT_V(8); PG8_WAIT_L(0); PG8_BAR; PG8_MMA(0, 0, At, B0); PG8_MMA(0, 1, At, B1); PG8_BAR; PG8_SCHED;
;             PG8_LDA(At, 1, 1); PG8_STAGE(PG8_SB(1, 0), b3, voffB); PG8_STAGE(PG8_SB(1, 1), b3 + hstep, voffB); PG8_STAGE(PG8_SA(1, 0), a3, voffA);
	s_setprio 1
	s_waitcnt lgkmcnt(0)
	v_mfma_f32_16x16x32_bf16 v[62:65], v[136:139], v[192:195], v[62:65]
	v_mfma_f32_16x16x32_bf16 v[58:61], v[150:153], v[192:195], v[58:61]
	v_mfma_f32_16x16x32_bf16 v[54:57], v[136:139], v[200:203], v[54:57]
	v_mfma_f32_16x16x32_bf16 v[50:53], v[150:153], v[200:203], v[50:53]
	v_mfma_f32_16x16x32_bf16 v[38:41], v[136:139], v[208:211], v[38:41]
	v_mfma_f32_16x16x32_bf16 v[34:37], v[150:153], v[208:211], v[34:37]
	v_mfma_f32_16x16x32_bf16 v[22:25], v[136:139], v[236:239], v[22:25]
	v_mfma_f32_16x16x32_bf16 v[18:21], v[150:153], v[236:239], v[18:21]
	v_mfma_f32_16x16x32_bf16 v[62:65], v[146:149], v[196:199], v[62:65]
	v_mfma_f32_16x16x32_bf16 v[58:61], v[154:157], v[196:199], v[58:61]
	v_mfma_f32_16x16x32_bf16 v[54:57], v[146:149], v[204:207], v[54:57]
	v_mfma_f32_16x16x32_bf16 v[50:53], v[154:157], v[204:207], v[50:53]
	v_mfma_f32_16x16x32_bf16 v[38:41], v[146:149], v[232:235], v[38:41]
	v_mfma_f32_16x16x32_bf16 v[34:37], v[154:157], v[232:235], v[34:37]
	v_mfma_f32_16x16x32_bf16 v[22:25], v[146:149], v[240:243], v[22:25]
	v_mfma_f32_16x16x32_bf16 v[18:21], v[154:157], v[240:243], v[18:21]
	s_setprio 0
	s_setprio 1
	v_mfma_f32_16x16x32_bf16 v[46:49], v[158:161], v[192:195], v[46:49]
	v_mfma_f32_16x16x32_bf16 v[42:45], v[184:187], v[192:195], v[42:45]
	v_mfma_f32_16x16x32_bf16 v[30:33], v[158:161], v[200:203], v[30:33]
	v_mfma_f32_16x16x32_bf16 v[26:29], v[184:187], v[200:203], v[26:29]
	v_mfma_f32_16x16x32_bf16 v[14:17], v[158:161], v[208:211], v[14:17]
	v_mfma_f32_16x16x32_bf16 v[10:13], v[184:187], v[208:211], v[10:13]
	v_mfma_f32_16x16x32_bf16 v[6:9], v[158:161], v[236:239], v[6:9]
	v_mfma_f32_16x16x32_bf16 v[2:5], v[184:187], v[236:239], v[2:5]
	v_mfma_f32_16x16x32_bf16 v[46:49], v[180:183], v[196:199], v[46:49]
	v_mfma_f32_16x16x32_bf16 v[42:45], v[188:191], v[196:199], v[42:45]
	v_mfma_f32_16x16x32_bf16 v[30:33], v[180:183], v[204:207], v[30:33]
	v_mfma_f32_16x16x32_bf16 v[26:29], v[188:191], v[204:207], v[26:29]
	v_mfma_f32_16x16x32_bf16 v[14:17], v[180:183], v[232:235], v[14:17]
	v_mfma_f32_16x16x32_bf16 v[10:13], v[188:191], v[232:235], v[10:13]
	v_mfma_f32_16x16x32_bf16 v[6:9], v[180:183], v[240:243], v[6:9]
	v_mfma_f32_16x16x32_bf16 v[2:5], v[188:191], v[240:243], v[2:5]
	s_setprio 0
	s_barrier
	s_add_i32 s54, 0, 0x18000
	s_add_i32 s55, 0, 0x1c000
	v_add_u32_e32 v154, s54, v141
	v_add_u32_e32 v169, s55, v141
	ds_read_b128 v[136:139], v154
	ds_read_b128 v[146:149], v154 offset:1024
	ds_read_b128 v[150:153], v154 offset:2048
	ds_read_b128 v[154:157], v154 offset:3072
	ds_read_b128 v[158:161], v169
	ds_read_b128 v[180:183], v169 offset:1024
	ds_read_b128 v[184:187], v169 offset:2048
	ds_read_b128 v[188:191], v169 offset:3072
	s_add_u32 s30, s30, 0x80000
	s_addc_u32 s31, s31, 0
	s_mov_b32 m0, s33
	v_lshl_add_u64 v[248:249], s[30:31], 0, v[166:167]
	ds_read_b128 v[192:195], v145 offset:32768
	ds_read_b128 v[196:199], v145 offset:33792
	ds_read_b128 v[200:203], v145 offset:34816
	ds_read_b128 v[204:207], v145 offset:35840
	ds_read_b128 v[208:211], v145 offset:36864
	ds_read_b128 v[232:235], v145 offset:37888
	ds_read_b128 v[236:239], v145 offset:38912
	ds_read_b128 v[240:243], v145 offset:39936
	global_load_lds_dwordx4 v[248:249], off
	v_lshl_add_u64 v[248:249], s[30:31], 0, v[170:171]
	s_mov_b32 m0, s34
	s_nop 0
	global_load_lds_dwordx4 v[248:249], off
	s_waitcnt vmcnt(8)
	s_waitcnt lgkmcnt(0)
	s_barrier
	s_setprio 1
	s_waitcnt lgkmcnt(0)
	v_mfma_f32_16x16x32_bf16 v[126:129], v[136:139], v[192:195], v[126:129]
	v_mfma_f32_16x16x32_bf16 v[122:125], v[150:153], v[192:195], v[122:125]
	v_mfma_f32_16x16x32_bf16 v[118:121], v[136:139], v[200:203], v[118:121]
	v_mfma_f32_16x16x32_bf16 v[114:117], v[150:153], v[200:203], v[114:117]
	v_mfma_f32_16x16x32_bf16 v[102:105], v[136:139], v[208:211], v[102:105]
	v_mfma_f32_16x16x32_bf16 v[98:101], v[150:153], v[208:211], v[98:101]
	v_mfma_f32_16x16x32_bf16 v[86:89], v[136:139], v[236:239], v[86:89]
	v_mfma_f32_16x16x32_bf16 v[82:85], v[150:153], v[236:239], v[82:85]
	v_mfma_f32_16x16x32_bf16 v[126:129], v[146:149], v[196:199], v[126:129]
	v_mfma_f32_16x16x32_bf16 v[122:125], v[154:157], v[196:199], v[122:125]
	v_mfma_f32_16x16x32_bf16 v[118:121], v[146:149], v[204:207], v[118:121]
	v_mfma_f32_16x16x32_bf16 v[114:117], v[154:157], v[204:207], v[114:117]
	v_mfma_f32_16x16x32_bf16 v[102:105], v[146:149], v[232:235], v[102:105]
	v_mfma_f32_16x16x32_bf16 v[98:101], v[154:157], v[232:235], v[98:101]
	v_mfma_f32_16x16x32_bf16 v[86:89], v[146:149], v[240:243], v[86:89]
	v_mfma_f32_16x16x32_bf16 v[82:85], v[154:157], v[240:243], v[82:85]
	s_setprio 0
	s_setprio 1
	v_mfma_f32_16x16x32_bf16 v[110:113], v[158:161], v[192:195], v[110:113]
	v_mfma_f32_16x16x32_bf16 v[106:109], v[184:187], v[192:195], v[106:109]
	v_mfma_f32_16x16x32_bf16 v[94:97], v[158:161], v[200:203], v[94:97]
	v_mfma_f32_16x16x32_bf16 v[90:93], v[184:187], v[200:203], v[90:93]
	v_mfma_f32_16x16x32_bf16 v[78:81], v[158:161], v[208:211], v[78:81]
	v_mfma_f32_16x16x32_bf16 v[74:77], v[184:187], v[208:211], v[74:77]
	v_mfma_f32_16x16x32_bf16 v[70:73], v[158:161], v[236:239], v[70:73]
	v_mfma_f32_16x16x32_bf16 v[66:69], v[184:187], v[236:239], v[66:69]
	v_mfma_f32_16x16x32_bf16 v[110:113], v[180:183], v[196:199], v[110:113]
	v_mfma_f32_16x16x32_bf16 v[106:109], v[188:191], v[196:199], v[106:109]
	v_mfma_f32_16x16x32_bf16 v[94:97], v[180:183], v[204:207], v[94:97]
	v_mfma_f32_16x16x32_bf16 v[90:93], v[188:191], v[204:207], v[90:93]
	v_mfma_f32_16x16x32_bf16 v[78:81], v[180:183], v[232:235], v[78:81]
	v_mfma_f32_16x16x32_bf16 v[74:77], v[188:191], v[232:235], v[74:77]
	v_mfma_f32_16x16x32_bf16 v[70:73], v[180:183], v[240:243], v[70:73]
	v_mfma_f32_16x16x32_bf16 v[66:69], v[188:191], v[240:243], v[66:69]
	s_setprio 0
	s_barrier
; #define PG8_STAGE(bufoff, gbase, voff) do { _Pragma("unroll") for (int _i = 0; _i < 2; ++_i) \
;         __builtin_amdgcn_global_load_lds((const unsigned*)((const char*)(gbase) + (voff)[_i]), (PG8_LAS unsigned*)(lds + (bufoff) + ldsw + _i * 8192), 16, 0, 0); } while (0)
; #define PG8_LDA(dst, b, h) do { _Pragma("unroll") for (int m = 0; m < 4; ++m) _Pragma("unroll") for (int k = 0; k < 2; ++k) dst[m][k] = *(const PG8_LAS bf16x8*)(lds + PG8_SA(b, h) + aoff + m * 2048 + k * 1024); } while (0)
; #define PG8_MMA(ai, bj, At, Bt) do { __builtin_amdgcn_s_setprio(1); _Pragma("unroll") for (int m = 0; m < 4; ++m) _Pragma("unroll") for (int n = 0; n < 2; ++n) _Pragma("unroll") for (int k = 0; k < 2; ++k) \
;         acc[ai][bj][m][n] = __builtin_amdgcn_mfma_f32_16x16x32_bf16(Bt[n][k], At[m][k], acc[ai][bj][m][n], 0, 0, 0); __builtin_amdgcn_s_setprio(0); } while (0)
; #define PG8_WAIT_V(n) asm volatile("s_waitcnt vmcnt(" #n ")" ::: "memory")
; #define PG8_WAIT_L(n) asm volatile("s_waitcnt lgkmcnt(" #n ")" ::: "memory")
; #define PG8_BAR __builtin_amdgcn_s_barrier()
; #define PG8_SCHED __builtin_amdgcn_sched_barrier(0)
; template <class Epi, class Sched, bool ALIGN_EPI = false, bool SP2 = false>
; __device__ __forceinline__ void gemm_phase(PG8_LAS unsigned char* lds, const Gemm g, const Sched& S, const Epi& E) {
;     ...
;         for (int t = 0; t < nt; t += 2) {
;             const bool last = (t == nt - 2);
;             const char* a1 = cA + (size_t)(t + 1) * kstep;
;             const char* a2 = last ? nA : cA + (size_t)(t + 2) * kstep; const char* b2 = last ? nB : cB + (size_t)(t + 2) * kstep;
;     ...
;             PG8_LDA(At, 1, 1); PG8_STAGE(PG8_SB(1, 0), b3, voffB); PG8_STAGE(PG8_SB(1, 1), b3 + hstep, voffB); PG8_STAGE(PG8_SA(1, 0), a3, voffA);
;             PG8_WAIT_V(8); PG8_WAIT_L(0); PG8_BAR; PG8_MMA(1, 0, At, B0); PG8_MMA(1, 1, At, B1); PG8_BAR; PG8_SCHED;
	s_add_i32 s30, s54, s2
	v_lshl_add_u64 v[212:213], v[212:213], 0, s[6:7]
	s_mov_b32 m0, s30
	ds_read_b128 v[192:195], v145 offset:49152
	ds_read_b128 v[196:199], v145 offset:50176
	ds_read_b128 v[200:203], v145 offset:51200
	ds_read_b128 v[204:207], v145 offset:52224
	ds_read_b128 v[208:211], v145 offset:53248
	ds_read_b128 v[232:235], v145 offset:54272
	ds_read_b128 v[236:239], v145 offset:55296
	ds_read_b128 v[240:243], v145 offset:56320
	global_load_lds_dwordx4 v[212:213], off
	s_add_i32 m0, s30, 0x2000
	s_add_u32 s28, s28, 0x80080
	v_lshl_add_u64 v[212:213], v[222:223], 0, s[6:7]
	s_addc_u32 s29, s29, 0
	s_add_i32 s30, s55, s2
	global_load_lds_dwordx4 v[212:213], off
	v_lshl_add_u64 v[212:213], s[28:29], 0, v[166:167]
	s_mov_b32 m0, s30
	s_nop 0
	global_load_lds_dwordx4 v[212:213], off
	v_lshl_add_u64 v[212:213], s[28:29], 0, v[170:171]
	s_add_i32 m0, s30, 0x2000
	s_nop 0
	global_load_lds_dwordx4 v[212:213], off
	v_lshl_add_u64 v[212:213], v[244:245], 0, s[6:7]
	s_mov_b32 m0, s35
	s_nop 0
	global_load_lds_dwordx4 v[212:213], off
	v_lshl_add_u64 v[212:213], v[246:247], 0, s[6:7]
	s_mov_b32 m0, s36
	s_nop 0
	global_load_lds_dwordx4 v[212:213], off
	s_waitcnt vmcnt(8)
	s_waitcnt lgkmcnt(0)
	s_barrier
	s_setprio 1
	s_waitcnt lgkmcnt(0)
	v_mfma_f32_16x16x32_bf16 v[62:65], v[136:139], v[192:195], v[62:65]
	v_mfma_f32_16x16x32_bf16 v[58:61], v[150:153], v[192:195], v[58:61]
	v_mfma_f32_16x16x32_bf16 v[54:57], v[136:139], v[200:203], v[54:57]
	v_mfma_f32_16x16x32_bf16 v[50:53], v[150:153], v[200:203], v[50:53]
	v_mfma_f32_16x16x32_bf16 v[38:41], v[136:139], v[208:211], v[38:41]
	v_mfma_f32_16x16x32_bf16 v[34:37], v[150:153], v[208:211], v[34:37]
	v_mfma_f32_16x16x32_bf16 v[22:25], v[136:139], v[236:239], v[22:25]
	v_mfma_f32_16x16x32_bf16 v[18:21], v[150:153], v[236:239], v[18:21]
	v_mfma_f32_16x16x32_bf16 v[62:65], v[146:149], v[196:199], v[62:65]
	v_mfma_f32_16x16x32_bf16 v[58:61], v[154:157], v[196:199], v[58:61]
	v_mfma_f32_16x16x32_bf16 v[54:57], v[146:149], v[204:207], v[54:57]
	v_mfma_f32_16x16x32_bf16 v[50:53], v[154:157], v[204:207], v[50:53]
	v_mfma_f32_16x16x32_bf16 v[38:41], v[146:149], v[232:235], v[38:41]
	v_mfma_f32_16x16x32_bf16 v[34:37], v[154:157], v[232:235], v[34:37]
	v_mfma_f32_16x16x32_bf16 v[22:25], v[146:149], v[240:243], v[22:25]
	v_mfma_f32_16x16x32_bf16 v[18:21], v[154:157], v[240:243], v[18:21]
	s_setprio 0
	s_setprio 1
	v_mfma_f32_16x16x32_bf16 v[46:49], v[158:161], v[192:195], v[46:49]
	v_mfma_f32_16x16x32_bf16 v[42:45], v[184:187], v[192:195], v[42:45]
	v_mfma_f32_16x16x32_bf16 v[30:33], v[158:161], v[200:203], v[30:33]
	v_mfma_f32_16x16x32_bf16 v[26:29], v[184:187], v[200:203], v[26:29]
	v_mfma_f32_16x16x32_bf16 v[14:17], v[158:161], v[208:211], v[14:17]
	v_mfma_f32_16x16x32_bf16 v[10:13], v[184:187], v[208:211], v[10:13]
	v_mfma_f32_16x16x32_bf16 v[6:9], v[158:161], v[236:239], v[6:9]
	v_mfma_f32_16x16x32_bf16 v[2:5], v[184:187], v[236:239], v[2:5]
	v_mfma_f32_16x16x32_bf16 v[46:49], v[180:183], v[196:199], v[46:49]
	v_mfma_f32_16x16x32_bf16 v[42:45], v[188:191], v[196:199], v[42:45]
	v_mfma_f32_16x16x32_bf16 v[30:33], v[180:183], v[204:207], v[30:33]
	v_mfma_f32_16x16x32_bf16 v[26:29], v[188:191], v[204:207], v[26:29]
	v_mfma_f32_16x16x32_bf16 v[14:17], v[180:183], v[232:235], v[14:17]
	v_mfma_f32_16x16x32_bf16 v[10:13], v[188:191], v[232:235], v[10:13]
	v_mfma_f32_16x16x32_bf16 v[6:9], v[180:183], v[240:243], v[6:9]
	v_mfma_f32_16x16x32_bf16 v[2:5], v[188:191], v[240:243], v[2:5]
	s_setprio 0
	s_add_u32 s26, s26, 0x100
	s_addc_u32 s27, s27, 0
	s_add_u32 s51, s51, 0x100
	s_addc_u32 s52, s52, 0
	s_cmp_ge_u32 s53, s45
	s_mov_b32 s28, s53
	s_barrier
	s_cbranch_scc0 .LBB0_892
	s_and_b64 vcc, exec, s[8:9]
	s_cbranch_vccz .LBB0_895
	s_barrier

; #define PG8_STAGE(bufoff, gbase, voff) do { _Pragma("unroll") for (int _i = 0; _i < 2; ++_i) \
;         __builtin_amdgcn_global_load_lds((const unsigned*)((const char*)(gbase) + (voff)[_i]), (PG8_LAS unsigned*)(lds + (bufoff) + ldsw + _i * 8192), 16, 0, 0); } while (0)
; #define PG8_LDA(dst, b, h) do { _Pragma("unroll") for (int m = 0; m < 4; ++m) _Pragma("unroll") for (int k = 0; k < 2; ++k) dst[m][k] = *(const PG8_LAS bf16x8*)(lds + PG8_SA(b, h) + aoff + m * 2048 + k * 1024); } while (0)
; #define PG8_LDB(dst, b, h) do { _Pragma("unroll") for (int n = 0; n < 2; ++n) _Pragma("unroll") for (int k = 0; k < 2; ++k) dst[n][k] = *(const PG8_LAS bf16x8*)(lds + PG8_SB(b, h) + boff + n * 2048 + k * 1024); } while (0)
; #define PG8_MMA(ai, bj, At, Bt) do { __builtin_amdgcn_s_setprio(1); _Pragma("unroll") for (int m = 0; m < 4; ++m) _Pragma("unroll") for (int n = 0; n < 2; ++n) _Pragma("unroll") for (int k = 0; k < 2; ++k) \
;         acc[ai][bj][m][n] = __builtin_amdgcn_mfma_f32_16x16x32_bf16(Bt[n][k], At[m][k], acc[ai][bj][m][n], 0, 0, 0); __builtin_amdgcn_s_setprio(0); } while (0)
; #define PG8_WAIT_V(n) asm volatile("s_waitcnt vmcnt(" #n ")" ::: "memory")
; #define PG8_BAR __builtin_amdgcn_s_barrier()
; template <class Epi, class Sched, bool ALIGN_EPI = false, bool SP2 = false>
; __device__ __forceinline__ void gemm_phase(PG8_LAS unsigned char* lds, const Gemm g, const Sched& S, const Epi& E) {
;     ...
;         for (int t = 0; t < nt; t += 2) {
;             const bool last = (t == nt - 2);
;             const char* a1 = cA + (size_t)(t + 1) * kstep;
;             const char* a2 = last ? nA : cA + (size_t)(t + 2) * kstep; const char* b2 = last ? nB : cB + (size_t)(t + 2) * kstep;
;             const char* a3 = a2 + kstep; const char* b3 = b2 + kstep;
;             if (last && has_next) S.a_ready(nxt);
;             if constexpr (SP2) {
;             PG8_LDB(B0, 0, 0); PG8_LDB(B1, 0, 1); PG8_SCHED; PG8_LDA(At, 0, 0); PG8_STAGE(PG8_SA(1, 1), a1 + hstep, voffA);
;             PG8_WAIT_V(8); PG8_WAIT_L(0); PG8_BAR; PG8_MMA(0, 0, At, B0); PG8_MMA(0, 1, At, B1); PG8_BAR; PG8_SCHED;
;             PG8_LDA(At, 0, 1); PG8_STAGE(PG8_SB(0, 0), b2, voffB); PG8_STAGE(PG8_SB(0, 1), b2 + hstep, voffB); PG8_STAGE(PG8_SA(0, 0), a2, voffA);
;             PG8_WAIT_V(8); PG8_WAIT_L(0); PG8_BAR; PG8_MMA(1, 0, At, B0); PG8_MMA(1, 1, At, B1); PG8_BAR; PG8_SCHED;
.LBB0_1029:
	ds_read_b128 v[144:147], v141
	ds_read_b128 v[148:151], v141 offset:1024
	ds_read_b128 v[152:155], v141 offset:2048
	ds_read_b128 v[156:159], v141 offset:3072
	ds_read_b128 v[180:183], v142
	ds_read_b128 v[184:187], v142 offset:1024
	ds_read_b128 v[188:191], v142 offset:2048
	ds_read_b128 v[192:195], v142 offset:3072
	s_add_i32 s45, s44, 2
	s_add_u32 s22, s6, 0xfff80080
	s_addc_u32 s23, s7, -1
	s_cmp_eq_u32 s41, s44
	s_cselect_b32 s25, s17, s23
	s_cselect_b32 s24, s39, s22
	s_cselect_b32 s23, s15, s43
	s_cselect_b32 s22, s40, s42
	v_lshl_add_u64 v[160:161], s[6:7], 0, v[130:131]
	s_add_i32 m0, s13, 0xc000
	ds_read_b128 v[196:199], v143
	ds_read_b128 v[200:203], v143 offset:1024
	ds_read_b128 v[204:207], v143 offset:2048
	ds_read_b128 v[208:211], v143 offset:3072
	ds_read_b128 v[232:235], v143 offset:4096
	ds_read_b128 v[236:239], v143 offset:5120
	ds_read_b128 v[240:243], v143 offset:6144
	ds_read_b128 v[244:247], v143 offset:7168
	global_load_lds_dwordx4 v[160:161], off
	v_lshl_add_u64 v[160:161], s[6:7], 0, v[132:133]
	s_add_i32 m0, s13, 0xe000
	s_nop 0
	global_load_lds_dwordx4 v[160:161], off
	s_waitcnt vmcnt(8)
	s_waitcnt lgkmcnt(0)
	s_barrier
	s_setprio 1
	s_waitcnt lgkmcnt(0)
	v_mfma_f32_16x16x32_bf16 v[126:129], v[144:147], v[196:199], v[126:129]
	v_mfma_f32_16x16x32_bf16 v[122:125], v[152:155], v[196:199], v[122:125]
	v_mfma_f32_16x16x32_bf16 v[118:121], v[144:147], v[204:207], v[118:121]
	v_mfma_f32_16x16x32_bf16 v[114:117], v[152:155], v[204:207], v[114:117]
	v_mfma_f32_16x16x32_bf16 v[102:105], v[144:147], v[232:235], v[102:105]
	v_mfma_f32_16x16x32_bf16 v[98:101], v[152:155], v[232:235], v[98:101]
	v_mfma_f32_16x16x32_bf16 v[86:89], v[144:147], v[240:243], v[86:89]
	v_mfma_f32_16x16x32_bf16 v[82:85], v[152:155], v[240:243], v[82:85]
	v_mfma_f32_16x16x32_bf16 v[126:129], v[148:151], v[200:203], v[126:129]
	v_mfma_f32_16x16x32_bf16 v[122:125], v[156:159], v[200:203], v[122:125]
	v_mfma_f32_16x16x32_bf16 v[118:121], v[148:151], v[208:211], v[118:121]
	v_mfma_f32_16x16x32_bf16 v[114:117], v[156:159], v[208:211], v[114:117]
	v_mfma_f32_16x16x32_bf16 v[102:105], v[148:151], v[236:239], v[102:105]
	v_mfma_f32_16x16x32_bf16 v[98:101], v[156:159], v[236:239], v[98:101]
	v_mfma_f32_16x16x32_bf16 v[86:89], v[148:151], v[244:247], v[86:89]
	v_mfma_f32_16x16x32_bf16 v[82:85], v[156:159], v[244:247], v[82:85]
	s_setprio 0
	s_setprio 1
	v_mfma_f32_16x16x32_bf16 v[110:113], v[180:183], v[196:199], v[110:113]
	v_mfma_f32_16x16x32_bf16 v[106:109], v[188:191], v[196:199], v[106:109]
	v_mfma_f32_16x16x32_bf16 v[94:97], v[180:183], v[204:207], v[94:97]
	v_mfma_f32_16x16x32_bf16 v[90:93], v[188:191], v[204:207], v[90:93]
	v_mfma_f32_16x16x32_bf16 v[78:81], v[180:183], v[232:235], v[78:81]
	v_mfma_f32_16x16x32_bf16 v[74:77], v[188:191], v[232:235], v[74:77]
	v_mfma_f32_16x16x32_bf16 v[70:73], v[180:183], v[240:243], v[70:73]
	v_mfma_f32_16x16x32_bf16 v[66:69], v[188:191], v[240:243], v[66:69]
	v_mfma_f32_16x16x32_bf16 v[110:113], v[184:187], v[200:203], v[110:113]
	v_mfma_f32_16x16x32_bf16 v[106:109], v[192:195], v[200:203], v[106:109]
	v_mfma_f32_16x16x32_bf16 v[94:97], v[184:187], v[208:211], v[94:97]
	v_mfma_f32_16x16x32_bf16 v[90:93], v[192:195], v[208:211], v[90:93]
	v_mfma_f32_16x16x32_bf16 v[78:81], v[184:187], v[236:239], v[78:81]
	v_mfma_f32_16x16x32_bf16 v[74:77], v[192:195], v[236:239], v[74:77]
	v_mfma_f32_16x16x32_bf16 v[70:73], v[184:187], v[244:247], v[70:73]
	v_mfma_f32_16x16x32_bf16 v[66:69], v[192:195], v[244:247], v[66:69]
	s_setprio 0
	s_barrier
	s_add_i32 s44, s34, s2
	v_lshl_add_u64 v[160:161], s[22:23], 0, v[168:169]
	s_mov_b32 m0, s44
	ds_read_b128 v[196:199], v143 offset:16384
	ds_read_b128 v[200:203], v143 offset:17408
	ds_read_b128 v[204:207], v143 offset:18432
	ds_read_b128 v[208:211], v143 offset:19456
	ds_read_b128 v[232:235], v143 offset:20480
	ds_read_b128 v[236:239], v143 offset:21504
	ds_read_b128 v[240:243], v143 offset:22528
	ds_read_b128 v[244:247], v143 offset:23552
	global_load_lds_dwordx4 v[160:161], off
	s_add_i32 m0, s44, 0x2000
	s_add_u32 s46, s22, 0x80000
	v_lshl_add_u64 v[212:213], s[22:23], 0, v[172:173]
	s_addc_u32 s47, s23, 0
	s_add_i32 s44, s35, s2
	global_load_lds_dwordx4 v[212:213], off
	v_lshl_add_u64 v[222:223], s[46:47], 0, v[168:169]
	s_mov_b32 m0, s44
	v_lshl_add_u64 v[248:249], s[24:25], 0, v[170:171]
	global_load_lds_dwordx4 v[222:223], off
	v_lshl_add_u64 v[222:223], s[46:47], 0, v[172:173]
	s_add_i32 m0, s44, 0x2000
	s_nop 0
	global_load_lds_dwordx4 v[222:223], off
	v_lshl_add_u64 v[222:223], s[24:25], 0, v[166:167]
	s_mov_b32 m0, s13
	s_nop 0
	global_load_lds_dwordx4 v[222:223], off
	s_mov_b32 m0, s26
	s_nop 0
	global_load_lds_dwordx4 v[248:249], off
	s_waitcnt vmcnt(8)
	s_waitcnt lgkmcnt(0)
	s_barrier
; #define PG8_STAGE(bufoff, gbase, voff) do { _Pragma("unroll") for (int _i = 0; _i < 2; ++_i) \
;         __builtin_amdgcn_global_load_lds((const unsigned*)((const char*)(gbase) + (voff)[_i]), (PG8_LAS unsigned*)(lds + (bufoff) + ldsw + _i * 8192), 16, 0, 0); } while (0)
; #define PG8_LDA(dst, b, h) do { _Pragma("unroll") for (int m = 0; m < 4; ++m) _Pragma("unroll") for (int k = 0; k < 2; ++k) dst[m][k] = *(const PG8_LAS bf16x8*)(lds + PG8_SA(b, h) + aoff + m * 2048 + k * 1024); } while (0)
; #define PG8_LDB(dst, b, h) do { _Pragma("unroll") for (int n = 0; n < 2; ++n) _Pragma("unroll") for (int k = 0; k < 2; ++k) dst[n][k] = *(const PG8_LAS bf16x8*)(lds + PG8_SB(b, h) + boff + n * 2048 + k * 1024); } while (0)
; #define PG8_MMA(ai, bj, At, Bt) do { __builtin_amdgcn_s_setprio(1); _Pragma("unroll") for (int m = 0; m < 4; ++m) _Pragma("unroll") for (int n = 0; n < 2; ++n) _Pragma("unroll") for (int k = 0; k < 2; ++k) \
;         acc[ai][bj][m][n] = __builtin_amdgcn_mfma_f32_16x16x32_bf16(Bt[n][k], At[m][k], acc[ai][bj][m][n], 0, 0, 0); __builtin_amdgcn_s_setprio(0); } while (0)
; #define PG8_WAIT_V(n) asm volatile("s_waitcnt vmcnt(" #n ")" ::: "memory")
; #define PG8_WAIT_L(n) asm volatile("s_waitcnt lgkmcnt(" #n ")" ::: "memory")
; #define PG8_BAR __builtin_amdgcn_s_barrier()
; #define PG8_SCHED __builtin_amdgcn_sched_barrier(0)
; template <class Epi, class Sched, bool ALIGN_EPI = false, bool SP2 = false>
; __device__ __forceinline__ void gemm_phase(PG8_LAS unsigned char* lds, const Gemm g, const Sched& S, const Epi& E) {
;     ...
;             PG8_WAIT_V(8); PG8_WAIT_L(0); PG8_BAR; PG8_MMA(1, 0, At, B0); PG8_MMA(1, 1, At, B1); PG8_BAR; PG8_SCHED;
;             PG8_LDB(B0, 1, 0); PG8_LDB(B1, 1, 1); PG8_SCHED; PG8_LDA(At, 1, 0); PG8_STAGE(PG8_SA(0, 1), a2 + hstep, voffA);
;             PG8_WAIT_V(8); PG8_WAIT_L(0); PG8_BAR; PG8_MMA(0, 0, At, B0); PG8_MMA(0, 1, At, B1); PG8_BAR; PG8_SCHED;
;             PG8_LDA(At, 1, 1); PG8_STAGE(PG8_SB(1, 0), b3, voffB); PG8_STAGE(PG8_SB(1, 1), b3 + hstep, voffB); PG8_STAGE(PG8_SA(1, 0), a3, voffA);
	s_setprio 1
	s_waitcnt lgkmcnt(0)
	v_mfma_f32_16x16x32_bf16 v[62:65], v[144:147], v[196:199], v[62:65]
	v_mfma_f32_16x16x32_bf16 v[58:61], v[152:155], v[196:199], v[58:61]
	v_mfma_f32_16x16x32_bf16 v[54:57], v[144:147], v[204:207], v[54:57]
	v_mfma_f32_16x16x32_bf16 v[50:53], v[152:155], v[204:207], v[50:53]
	v_mfma_f32_16x16x32_bf16 v[38:41], v[144:147], v[232:235], v[38:41]
	v_mfma_f32_16x16x32_bf16 v[34:37], v[152:155], v[232:235], v[34:37]
	v_mfma_f32_16x16x32_bf16 v[22:25], v[144:147], v[240:243], v[22:25]
	v_mfma_f32_16x16x32_bf16 v[18:21], v[152:155], v[240:243], v[18:21]
	v_mfma_f32_16x16x32_bf16 v[62:65], v[148:151], v[200:203], v[62:65]
	v_mfma_f32_16x16x32_bf16 v[58:61], v[156:159], v[200:203], v[58:61]
	v_mfma_f32_16x16x32_bf16 v[54:57], v[148:151], v[208:211], v[54:57]
	v_mfma_f32_16x16x32_bf16 v[50:53], v[156:159], v[208:211], v[50:53]
	v_mfma_f32_16x16x32_bf16 v[38:41], v[148:151], v[236:239], v[38:41]
	v_mfma_f32_16x16x32_bf16 v[34:37], v[156:159], v[236:239], v[34:37]
	v_mfma_f32_16x16x32_bf16 v[22:25], v[148:151], v[244:247], v[22:25]
	v_mfma_f32_16x16x32_bf16 v[18:21], v[156:159], v[244:247], v[18:21]
	s_setprio 0
	s_setprio 1
	v_mfma_f32_16x16x32_bf16 v[46:49], v[180:183], v[196:199], v[46:49]
	v_mfma_f32_16x16x32_bf16 v[42:45], v[188:191], v[196:199], v[42:45]
	v_mfma_f32_16x16x32_bf16 v[30:33], v[180:183], v[204:207], v[30:33]
	v_mfma_f32_16x16x32_bf16 v[26:29], v[188:191], v[204:207], v[26:29]
	v_mfma_f32_16x16x32_bf16 v[14:17], v[180:183], v[232:235], v[14:17]
	v_mfma_f32_16x16x32_bf16 v[10:13], v[188:191], v[232:235], v[10:13]
	v_mfma_f32_16x16x32_bf16 v[6:9], v[180:183], v[240:243], v[6:9]
	v_mfma_f32_16x16x32_bf16 v[2:5], v[188:191], v[240:243], v[2:5]
	v_mfma_f32_16x16x32_bf16 v[46:49], v[184:187], v[200:203], v[46:49]
	v_mfma_f32_16x16x32_bf16 v[42:45], v[192:195], v[200:203], v[42:45]
	v_mfma_f32_16x16x32_bf16 v[30:33], v[184:187], v[208:211], v[30:33]
	v_mfma_f32_16x16x32_bf16 v[26:29], v[192:195], v[208:211], v[26:29]
	v_mfma_f32_16x16x32_bf16 v[14:17], v[184:187], v[236:239], v[14:17]
	v_mfma_f32_16x16x32_bf16 v[10:13], v[192:195], v[236:239], v[10:13]
	v_mfma_f32_16x16x32_bf16 v[6:9], v[184:187], v[244:247], v[6:9]
	v_mfma_f32_16x16x32_bf16 v[2:5], v[192:195], v[244:247], v[2:5]
	s_setprio 0
	s_barrier
	s_add_i32 s44, 0, 0x18000
	s_add_i32 s46, 0, 0x1c000
	v_add_u32_e32 v156, s44, v139
	v_add_u32_e32 v192, s46, v139
	ds_read_b128 v[144:147], v156
	ds_read_b128 v[148:151], v156 offset:1024
	ds_read_b128 v[152:155], v156 offset:2048
	ds_read_b128 v[156:159], v156 offset:3072
	ds_read_b128 v[180:183], v192
	ds_read_b128 v[184:187], v192 offset:1024
	ds_read_b128 v[188:191], v192 offset:2048
	ds_read_b128 v[192:195], v192 offset:3072
	s_add_u32 s24, s24, 0x80000
	s_addc_u32 s25, s25, 0
	s_mov_b32 m0, s27
	v_lshl_add_u64 v[250:251], s[24:25], 0, v[166:167]
	ds_read_b128 v[196:199], v143 offset:32768
	ds_read_b128 v[200:203], v143 offset:33792
	ds_read_b128 v[204:207], v143 offset:34816
	ds_read_b128 v[208:211], v143 offset:35840
	ds_read_b128 v[232:235], v143 offset:36864
	ds_read_b128 v[236:239], v143 offset:37888
	ds_read_b128 v[240:243], v143 offset:38912
	ds_read_b128 v[244:247], v143 offset:39936
	global_load_lds_dwordx4 v[250:251], off
	v_lshl_add_u64 v[250:251], s[24:25], 0, v[170:171]
	s_mov_b32 m0, s28
	s_nop 0
	global_load_lds_dwordx4 v[250:251], off
	s_waitcnt vmcnt(8)
	s_waitcnt lgkmcnt(0)
	s_barrier
	s_setprio 1
	s_waitcnt lgkmcnt(0)
	v_mfma_f32_16x16x32_bf16 v[126:129], v[144:147], v[196:199], v[126:129]
	v_mfma_f32_16x16x32_bf16 v[122:125], v[152:155], v[196:199], v[122:125]
	v_mfma_f32_16x16x32_bf16 v[118:121], v[144:147], v[204:207], v[118:121]
	v_mfma_f32_16x16x32_bf16 v[114:117], v[152:155], v[204:207], v[114:117]
	v_mfma_f32_16x16x32_bf16 v[102:105], v[144:147], v[232:235], v[102:105]
	v_mfma_f32_16x16x32_bf16 v[98:101], v[152:155], v[232:235], v[98:101]
	v_mfma_f32_16x16x32_bf16 v[86:89], v[144:147], v[240:243], v[86:89]
	v_mfma_f32_16x16x32_bf16 v[82:85], v[152:155], v[240:243], v[82:85]
	v_mfma_f32_16x16x32_bf16 v[126:129], v[148:151], v[200:203], v[126:129]
	v_mfma_f32_16x16x32_bf16 v[122:125], v[156:159], v[200:203], v[122:125]
	v_mfma_f32_16x16x32_bf16 v[118:121], v[148:151], v[208:211], v[118:121]
	v_mfma_f32_16x16x32_bf16 v[114:117], v[156:159], v[208:211], v[114:117]
	v_mfma_f32_16x16x32_bf16 v[102:105], v[148:151], v[236:239], v[102:105]
	v_mfma_f32_16x16x32_bf16 v[98:101], v[156:159], v[236:239], v[98:101]
	v_mfma_f32_16x16x32_bf16 v[86:89], v[148:151], v[244:247], v[86:89]
	v_mfma_f32_16x16x32_bf16 v[82:85], v[156:159], v[244:247], v[82:85]
	s_setprio 0
	s_setprio 1
	v_mfma_f32_16x16x32_bf16 v[110:113], v[180:183], v[196:199], v[110:113]
	v_mfma_f32_16x16x32_bf16 v[106:109], v[188:191], v[196:199], v[106:109]
	v_mfma_f32_16x16x32_bf16 v[94:97], v[180:183], v[204:207], v[94:97]
	v_mfma_f32_16x16x32_bf16 v[90:93], v[188:191], v[204:207], v[90:93]
	v_mfma_f32_16x16x32_bf16 v[78:81], v[180:183], v[232:235], v[78:81]
	v_mfma_f32_16x16x32_bf16 v[74:77], v[188:191], v[232:235], v[74:77]
	v_mfma_f32_16x16x32_bf16 v[70:73], v[180:183], v[240:243], v[70:73]
	v_mfma_f32_16x16x32_bf16 v[66:69], v[188:191], v[240:243], v[66:69]
	v_mfma_f32_16x16x32_bf16 v[110:113], v[184:187], v[200:203], v[110:113]
	v_mfma_f32_16x16x32_bf16 v[106:109], v[192:195], v[200:203], v[106:109]
	v_mfma_f32_16x16x32_bf16 v[94:97], v[184:187], v[208:211], v[94:97]
	v_mfma_f32_16x16x32_bf16 v[90:93], v[192:195], v[208:211], v[90:93]
	v_mfma_f32_16x16x32_bf16 v[78:81], v[184:187], v[236:239], v[78:81]
	v_mfma_f32_16x16x32_bf16 v[74:77], v[192:195], v[236:239], v[74:77]
	v_mfma_f32_16x16x32_bf16 v[70:73], v[184:187], v[244:247], v[70:73]
	v_mfma_f32_16x16x32_bf16 v[66:69], v[192:195], v[244:247], v[66:69]
	s_setprio 0
	s_barrier
; #define PG8_STAGE(bufoff, gbase, voff) do { _Pragma("unroll") for (int _i = 0; _i < 2; ++_i) \
;         __builtin_amdgcn_global_load_lds((const unsigned*)((const char*)(gbase) + (voff)[_i]), (PG8_LAS unsigned*)(lds + (bufoff) + ldsw + _i * 8192), 16, 0, 0); } while (0)
; #define PG8_LDA(dst, b, h) do { _Pragma("unroll") for (int m = 0; m < 4; ++m) _Pragma("unroll") for (int k = 0; k < 2; ++k) dst[m][k] = *(const PG8_LAS bf16x8*)(lds + PG8_SA(b, h) + aoff + m * 2048 + k * 1024); } while (0)
; #define PG8_MMA(ai, bj, At, Bt) do { __builtin_amdgcn_s_setprio(1); _Pragma("unroll") for (int m = 0; m < 4; ++m) _Pragma("unroll") for (int n = 0; n < 2; ++n) _Pragma("unroll") for (int k = 0; k < 2; ++k) \
;         acc[ai][bj][m][n] = __builtin_amdgcn_mfma_f32_16x16x32_bf16(Bt[n][k], At[m][k], acc[ai][bj][m][n], 0, 0, 0); __builtin_amdgcn_s_setprio(0); } while (0)
; #define PG8_WAIT_V(n) asm volatile("s_waitcnt vmcnt(" #n ")" ::: "memory")
; #define PG8_WAIT_L(n) asm volatile("s_waitcnt lgkmcnt(" #n ")" ::: "memory")
; #define PG8_BAR __builtin_amdgcn_s_barrier()
; #define PG8_SCHED __builtin_amdgcn_sched_barrier(0)
; template <class Epi, class Sched, bool ALIGN_EPI = false, bool SP2 = false>
; __device__ __forceinline__ void gemm_phase(PG8_LAS unsigned char* lds, const Gemm g, const Sched& S, const Epi& E) {
;     ...
;         for (int t = 0; t < nt; t += 2) {
;             const bool last = (t == nt - 2);
;             const char* a1 = cA + (size_t)(t + 1) * kstep;
;             const char* a2 = last ? nA : cA + (size_t)(t + 2) * kstep; const char* b2 = last ? nB : cB + (size_t)(t + 2) * kstep;
;     ...
;             PG8_LDA(At, 1, 1); PG8_STAGE(PG8_SB(1, 0), b3, voffB); PG8_STAGE(PG8_SB(1, 1), b3 + hstep, voffB); PG8_STAGE(PG8_SA(1, 0), a3, voffA);
;             PG8_WAIT_V(8); PG8_WAIT_L(0); PG8_BAR; PG8_MMA(1, 0, At, B0); PG8_MMA(1, 1, At, B1); PG8_BAR; PG8_SCHED;
	s_add_i32 s24, s44, s2
	v_lshl_add_u64 v[160:161], v[160:161], 0, s[8:9]
	s_mov_b32 m0, s24
	ds_read_b128 v[196:199], v143 offset:49152
	ds_read_b128 v[200:203], v143 offset:50176
	ds_read_b128 v[204:207], v143 offset:51200
	ds_read_b128 v[208:211], v143 offset:52224
	ds_read_b128 v[232:235], v143 offset:53248
	ds_read_b128 v[236:239], v143 offset:54272
	ds_read_b128 v[240:243], v143 offset:55296
	ds_read_b128 v[244:247], v143 offset:56320
	global_load_lds_dwordx4 v[160:161], off
	s_add_i32 m0, s24, 0x2000
	s_add_u32 s22, s22, 0x80080
	v_lshl_add_u64 v[160:161], v[212:213], 0, s[8:9]
	s_addc_u32 s23, s23, 0
	s_add_i32 s24, s46, s2
	global_load_lds_dwordx4 v[160:161], off
	v_lshl_add_u64 v[160:161], s[22:23], 0, v[168:169]
	s_mov_b32 m0, s24
	s_nop 0
	global_load_lds_dwordx4 v[160:161], off
	v_lshl_add_u64 v[160:161], s[22:23], 0, v[172:173]
	s_add_i32 m0, s24, 0x2000
	s_nop 0
	global_load_lds_dwordx4 v[160:161], off
	v_lshl_add_u64 v[160:161], v[222:223], 0, s[8:9]
	s_mov_b32 m0, s30
	s_nop 0
	global_load_lds_dwordx4 v[160:161], off
	v_lshl_add_u64 v[160:161], v[248:249], 0, s[8:9]
	s_mov_b32 m0, s31
	s_nop 0
	global_load_lds_dwordx4 v[160:161], off
	s_waitcnt vmcnt(8)
	s_waitcnt lgkmcnt(0)
	s_barrier
	s_setprio 1
	s_waitcnt lgkmcnt(0)
	v_mfma_f32_16x16x32_bf16 v[62:65], v[144:147], v[196:199], v[62:65]
	v_mfma_f32_16x16x32_bf16 v[58:61], v[152:155], v[196:199], v[58:61]
	v_mfma_f32_16x16x32_bf16 v[54:57], v[144:147], v[204:207], v[54:57]
	v_mfma_f32_16x16x32_bf16 v[50:53], v[152:155], v[204:207], v[50:53]
	v_mfma_f32_16x16x32_bf16 v[38:41], v[144:147], v[232:235], v[38:41]
	v_mfma_f32_16x16x32_bf16 v[34:37], v[152:155], v[232:235], v[34:37]
	v_mfma_f32_16x16x32_bf16 v[22:25], v[144:147], v[240:243], v[22:25]
	v_mfma_f32_16x16x32_bf16 v[18:21], v[152:155], v[240:243], v[18:21]
	v_mfma_f32_16x16x32_bf16 v[62:65], v[148:151], v[200:203], v[62:65]
	v_mfma_f32_16x16x32_bf16 v[58:61], v[156:159], v[200:203], v[58:61]
	v_mfma_f32_16x16x32_bf16 v[54:57], v[148:151], v[208:211], v[54:57]
	v_mfma_f32_16x16x32_bf16 v[50:53], v[156:159], v[208:211], v[50:53]
	v_mfma_f32_16x16x32_bf16 v[38:41], v[148:151], v[236:239], v[38:41]
	v_mfma_f32_16x16x32_bf16 v[34:37], v[156:159], v[236:239], v[34:37]
	v_mfma_f32_16x16x32_bf16 v[22:25], v[148:151], v[244:247], v[22:25]
	v_mfma_f32_16x16x32_bf16 v[18:21], v[156:159], v[244:247], v[18:21]
	s_setprio 0
	s_setprio 1
	v_mfma_f32_16x16x32_bf16 v[46:49], v[180:183], v[196:199], v[46:49]
	v_mfma_f32_16x16x32_bf16 v[42:45], v[188:191], v[196:199], v[42:45]
	v_mfma_f32_16x16x32_bf16 v[30:33], v[180:183], v[204:207], v[30:33]
	v_mfma_f32_16x16x32_bf16 v[26:29], v[188:191], v[204:207], v[26:29]
	v_mfma_f32_16x16x32_bf16 v[14:17], v[180:183], v[232:235], v[14:17]
	v_mfma_f32_16x16x32_bf16 v[10:13], v[188:191], v[232:235], v[10:13]
	v_mfma_f32_16x16x32_bf16 v[6:9], v[180:183], v[240:243], v[6:9]
	v_mfma_f32_16x16x32_bf16 v[2:5], v[188:191], v[240:243], v[2:5]
	v_mfma_f32_16x16x32_bf16 v[46:49], v[184:187], v[200:203], v[46:49]
	v_mfma_f32_16x16x32_bf16 v[42:45], v[192:195], v[200:203], v[42:45]
	v_mfma_f32_16x16x32_bf16 v[30:33], v[184:187], v[208:211], v[30:33]
	v_mfma_f32_16x16x32_bf16 v[26:29], v[192:195], v[208:211], v[26:29]
	v_mfma_f32_16x16x32_bf16 v[14:17], v[184:187], v[236:239], v[14:17]
	v_mfma_f32_16x16x32_bf16 v[10:13], v[192:195], v[236:239], v[10:13]
	v_mfma_f32_16x16x32_bf16 v[6:9], v[184:187], v[244:247], v[6:9]
	v_mfma_f32_16x16x32_bf16 v[2:5], v[192:195], v[244:247], v[2:5]
	s_setprio 0
	s_add_u32 s6, s6, 0x100
	s_addc_u32 s7, s7, 0
	s_add_u32 s42, s42, 0x100
	s_addc_u32 s43, s43, 0
	s_cmp_ge_u32 s45, s38
	s_mov_b32 s44, s45
	s_barrier
	s_cbranch_scc0 .LBB0_1029
	s_and_b64 vcc, exec, s[10:11]
	s_cbranch_vccz .LBB0_1032
	s_barrier

; #define PG8_STAGE(bufoff, gbase, voff) do { _Pragma("unroll") for (int _i = 0; _i < 2; ++_i) \
;         __builtin_amdgcn_global_load_lds((const unsigned*)((const char*)(gbase) + (voff)[_i]), (PG8_LAS unsigned*)(lds + (bufoff) + ldsw + _i * 8192), 16, 0, 0); } while (0)
; #define PG8_LDA(dst, b, h) do { _Pragma("unroll") for (int m = 0; m < 4; ++m) _Pragma("unroll") for (int k = 0; k < 2; ++k) dst[m][k] = *(const PG8_LAS bf16x8*)(lds + PG8_SA(b, h) + aoff + m * 2048 + k * 1024); } while (0)
; #define PG8_LDB(dst, b, h) do { _Pragma("unroll") for (int n = 0; n < 2; ++n) _Pragma("unroll") for (int k = 0; k < 2; ++k) dst[n][k] = *(const PG8_LAS bf16x8*)(lds + PG8_SB(b, h) + boff + n * 2048 + k * 1024); } while (0)
; #define PG8_MMA(ai, bj, At, Bt) do { __builtin_amdgcn_s_setprio(1); _Pragma("unroll") for (int m = 0; m < 4; ++m) _Pragma("unroll") for (int n = 0; n < 2; ++n) _Pragma("unroll") for (int k = 0; k < 2; ++k) \
;         acc[ai][bj][m][n] = __builtin_amdgcn_mfma_f32_16x16x32_bf16(Bt[n][k], At[m][k], acc[ai][bj][m][n], 0, 0, 0); __builtin_amdgcn_s_setprio(0); } while (0)
; #define PG8_WAIT_V(n) asm volatile("s_waitcnt vmcnt(" #n ")" ::: "memory")
; #define PG8_BAR __builtin_amdgcn_s_barrier()
; template <class Epi, class Sched, bool ALIGN_EPI = false, bool SP2 = false>
; __device__ __forceinline__ void gemm_phase(PG8_LAS unsigned char* lds, const Gemm g, const Sched& S, const Epi& E) {
;     ...
;         for (int t = 0; t < nt; t += 2) {
;             const bool last = (t == nt - 2);
;             const char* a1 = cA + (size_t)(t + 1) * kstep;
;             const char* a2 = last ? nA : cA + (size_t)(t + 2) * kstep; const char* b2 = last ? nB : cB + (size_t)(t + 2) * kstep;
;             const char* a3 = a2 + kstep; const char* b3 = b2 + kstep;
;             if (last && has_next) S.a_ready(nxt);
;             if constexpr (SP2) {
;             PG8_LDB(B0, 0, 0); PG8_LDB(B1, 0, 1); PG8_SCHED; PG8_LDA(At, 0, 0); PG8_STAGE(PG8_SA(1, 1), a1 + hstep, voffA);
;             PG8_WAIT_V(8); PG8_WAIT_L(0); PG8_BAR; PG8_MMA(0, 0, At, B0); PG8_MMA(0, 1, At, B1); PG8_BAR; PG8_SCHED;
;             PG8_LDA(At, 0, 1); PG8_STAGE(PG8_SB(0, 0), b2, voffB); PG8_STAGE(PG8_SB(0, 1), b2 + hstep, voffB); PG8_STAGE(PG8_SA(0, 0), a2, voffA);
;             PG8_WAIT_V(8); PG8_WAIT_L(0); PG8_BAR; PG8_MMA(1, 0, At, B0); PG8_MMA(1, 1, At, B1); PG8_BAR; PG8_SCHED;
.LBB0_1053:
	ds_read_b128 v[140:143], v137
	ds_read_b128 v[144:147], v137 offset:1024
	ds_read_b128 v[148:151], v137 offset:2048
	ds_read_b128 v[152:155], v137 offset:3072
	ds_read_b128 v[156:159], v138
	ds_read_b128 v[180:183], v138 offset:1024
	ds_read_b128 v[184:187], v138 offset:2048
	ds_read_b128 v[188:191], v138 offset:3072
	s_add_i32 s54, s26, 2
	s_add_u32 s27, s24, 0xfff80080
	s_addc_u32 s28, s25, -1
	s_cmp_eq_u32 s48, s26
	s_cselect_b32 s26, s47, s49
	s_cselect_b32 s29, s19, s28
	s_cselect_b32 s28, s46, s27
	s_cselect_b32 s27, s17, s53
	v_lshl_add_u64 v[160:161], s[24:25], 0, v[130:131]
	s_add_i32 m0, s34, 0xc000
	ds_read_b128 v[192:195], v139
	ds_read_b128 v[196:199], v139 offset:1024
	ds_read_b128 v[200:203], v139 offset:2048
	ds_read_b128 v[204:207], v139 offset:3072
	ds_read_b128 v[208:211], v139 offset:4096
	ds_read_b128 v[232:235], v139 offset:5120
	ds_read_b128 v[236:239], v139 offset:6144
	ds_read_b128 v[240:243], v139 offset:7168
	global_load_lds_dwordx4 v[160:161], off
	v_lshl_add_u64 v[160:161], s[24:25], 0, v[132:133]
	s_add_i32 m0, s34, 0xe000
	s_nop 0
	global_load_lds_dwordx4 v[160:161], off
	s_waitcnt vmcnt(8)
	s_waitcnt lgkmcnt(0)
	s_barrier
	s_setprio 1
	s_waitcnt lgkmcnt(0)
	v_mfma_f32_16x16x32_bf16 v[126:129], v[140:143], v[192:195], v[126:129]
	v_mfma_f32_16x16x32_bf16 v[122:125], v[148:151], v[192:195], v[122:125]
	v_mfma_f32_16x16x32_bf16 v[118:121], v[140:143], v[200:203], v[118:121]
	v_mfma_f32_16x16x32_bf16 v[110:113], v[148:151], v[200:203], v[110:113]
	v_mfma_f32_16x16x32_bf16 v[102:105], v[140:143], v[208:211], v[102:105]
	v_mfma_f32_16x16x32_bf16 v[94:97], v[148:151], v[208:211], v[94:97]
	v_mfma_f32_16x16x32_bf16 v[86:89], v[140:143], v[236:239], v[86:89]
	v_mfma_f32_16x16x32_bf16 v[78:81], v[148:151], v[236:239], v[78:81]
	v_mfma_f32_16x16x32_bf16 v[126:129], v[144:147], v[196:199], v[126:129]
	v_mfma_f32_16x16x32_bf16 v[122:125], v[152:155], v[196:199], v[122:125]
	v_mfma_f32_16x16x32_bf16 v[118:121], v[144:147], v[204:207], v[118:121]
	v_mfma_f32_16x16x32_bf16 v[110:113], v[152:155], v[204:207], v[110:113]
	v_mfma_f32_16x16x32_bf16 v[102:105], v[144:147], v[232:235], v[102:105]
	v_mfma_f32_16x16x32_bf16 v[94:97], v[152:155], v[232:235], v[94:97]
	v_mfma_f32_16x16x32_bf16 v[86:89], v[144:147], v[240:243], v[86:89]
	v_mfma_f32_16x16x32_bf16 v[78:81], v[152:155], v[240:243], v[78:81]
	s_setprio 0
	s_setprio 1
	v_mfma_f32_16x16x32_bf16 v[114:117], v[156:159], v[192:195], v[114:117]
	v_mfma_f32_16x16x32_bf16 v[106:109], v[184:187], v[192:195], v[106:109]
	v_mfma_f32_16x16x32_bf16 v[98:101], v[156:159], v[200:203], v[98:101]
	v_mfma_f32_16x16x32_bf16 v[90:93], v[184:187], v[200:203], v[90:93]
	v_mfma_f32_16x16x32_bf16 v[82:85], v[156:159], v[208:211], v[82:85]
	v_mfma_f32_16x16x32_bf16 v[74:77], v[184:187], v[208:211], v[74:77]
	v_mfma_f32_16x16x32_bf16 v[70:73], v[156:159], v[236:239], v[70:73]
	v_mfma_f32_16x16x32_bf16 v[66:69], v[184:187], v[236:239], v[66:69]
	v_mfma_f32_16x16x32_bf16 v[114:117], v[180:183], v[196:199], v[114:117]
	v_mfma_f32_16x16x32_bf16 v[106:109], v[188:191], v[196:199], v[106:109]
	v_mfma_f32_16x16x32_bf16 v[98:101], v[180:183], v[204:207], v[98:101]
	v_mfma_f32_16x16x32_bf16 v[90:93], v[188:191], v[204:207], v[90:93]
	v_mfma_f32_16x16x32_bf16 v[82:85], v[180:183], v[232:235], v[82:85]
	v_mfma_f32_16x16x32_bf16 v[74:77], v[188:191], v[232:235], v[74:77]
	v_mfma_f32_16x16x32_bf16 v[70:73], v[180:183], v[240:243], v[70:73]
	v_mfma_f32_16x16x32_bf16 v[66:69], v[188:191], v[240:243], v[66:69]
	s_setprio 0
	s_barrier
	s_add_i32 s55, s42, s30
	v_lshl_add_u64 v[160:161], s[26:27], 0, v[166:167]
	s_mov_b32 m0, s55
	ds_read_b128 v[192:195], v139 offset:16384
	ds_read_b128 v[196:199], v139 offset:17408
	ds_read_b128 v[200:203], v139 offset:18432
	ds_read_b128 v[204:207], v139 offset:19456
	ds_read_b128 v[208:211], v139 offset:20480
	ds_read_b128 v[232:235], v139 offset:21504
	ds_read_b128 v[236:239], v139 offset:22528
	ds_read_b128 v[240:243], v139 offset:23552
	global_load_lds_dwordx4 v[160:161], off
	s_add_i32 m0, s55, 0x2000
	s_add_u32 s56, s26, 0x80000
	v_lshl_add_u64 v[212:213], s[26:27], 0, v[170:171]
	s_addc_u32 s57, s27, 0
	s_add_i32 s55, s43, s30
	global_load_lds_dwordx4 v[212:213], off
	v_lshl_add_u64 v[222:223], s[56:57], 0, v[166:167]
	s_mov_b32 m0, s55
	v_lshl_add_u64 v[244:245], s[28:29], 0, v[170:171]
	global_load_lds_dwordx4 v[222:223], off
	v_lshl_add_u64 v[222:223], s[56:57], 0, v[170:171]
	s_add_i32 m0, s55, 0x2000
	s_nop 0
	global_load_lds_dwordx4 v[222:223], off
	v_lshl_add_u64 v[222:223], s[28:29], 0, v[166:167]
	s_mov_b32 m0, s34
	s_nop 0
	global_load_lds_dwordx4 v[222:223], off
	s_mov_b32 m0, s35
	s_nop 0
	global_load_lds_dwordx4 v[244:245], off
	s_waitcnt vmcnt(8)
	s_waitcnt lgkmcnt(0)
	s_barrier
; #define PG8_STAGE(bufoff, gbase, voff) do { _Pragma("unroll") for (int _i = 0; _i < 2; ++_i) \
;         __builtin_amdgcn_global_load_lds((const unsigned*)((const char*)(gbase) + (voff)[_i]), (PG8_LAS unsigned*)(lds + (bufoff) + ldsw + _i * 8192), 16, 0, 0); } while (0)
; #define PG8_LDA(dst, b, h) do { _Pragma("unroll") for (int m = 0; m < 4; ++m) _Pragma("unroll") for (int k = 0; k < 2; ++k) dst[m][k] = *(const PG8_LAS bf16x8*)(lds + PG8_SA(b, h) + aoff + m * 2048 + k * 1024); } while (0)
; #define PG8_LDB(dst, b, h) do { _Pragma("unroll") for (int n = 0; n < 2; ++n) _Pragma("unroll") for (int k = 0; k < 2; ++k) dst[n][k] = *(const PG8_LAS bf16x8*)(lds + PG8_SB(b, h) + boff + n * 2048 + k * 1024); } while (0)
; #define PG8_MMA(ai, bj, At, Bt) do { __builtin_amdgcn_s_setprio(1); _Pragma("unroll") for (int m = 0; m < 4; ++m) _Pragma("unroll") for (int n = 0; n < 2; ++n) _Pragma("unroll") for (int k = 0; k < 2; ++k) \
;         acc[ai][bj][m][n] = __builtin_amdgcn_mfma_f32_16x16x32_bf16(Bt[n][k], At[m][k], acc[ai][bj][m][n], 0, 0, 0); __builtin_amdgcn_s_setprio(0); } while (0)
; #define PG8_WAIT_V(n) asm volatile("s_waitcnt vmcnt(" #n ")" ::: "memory")
; #define PG8_WAIT_L(n) asm volatile("s_waitcnt lgkmcnt(" #n ")" ::: "memory")
; #define PG8_BAR __builtin_amdgcn_s_barrier()
; #define PG8_SCHED __builtin_amdgcn_sched_barrier(0)
; template <class Epi, class Sched, bool ALIGN_EPI = false, bool SP2 = false>
; __device__ __forceinline__ void gemm_phase(PG8_LAS unsigned char* lds, const Gemm g, const Sched& S, const Epi& E) {
;     ...
;             PG8_WAIT_V(8); PG8_WAIT_L(0); PG8_BAR; PG8_MMA(1, 0, At, B0); PG8_MMA(1, 1, At, B1); PG8_BAR; PG8_SCHED;
;             PG8_LDB(B0, 1, 0); PG8_LDB(B1, 1, 1); PG8_SCHED; PG8_LDA(At, 1, 0); PG8_STAGE(PG8_SA(0, 1), a2 + hstep, voffA);
;             PG8_WAIT_V(8); PG8_WAIT_L(0); PG8_BAR; PG8_MMA(0, 0, At, B0); PG8_MMA(0, 1, At, B1); PG8_BAR; PG8_SCHED;
;             PG8_LDA(At, 1, 1); PG8_STAGE(PG8_SB(1, 0), b3, voffB); PG8_STAGE(PG8_SB(1, 1), b3 + hstep, voffB); PG8_STAGE(PG8_SA(1, 0), a3, voffA);
	s_setprio 1
	s_waitcnt lgkmcnt(0)
	v_mfma_f32_16x16x32_bf16 v[62:65], v[140:143], v[192:195], v[62:65]
	v_mfma_f32_16x16x32_bf16 v[58:61], v[148:151], v[192:195], v[58:61]
	v_mfma_f32_16x16x32_bf16 v[54:57], v[140:143], v[200:203], v[54:57]
	v_mfma_f32_16x16x32_bf16 v[46:49], v[148:151], v[200:203], v[46:49]
	v_mfma_f32_16x16x32_bf16 v[38:41], v[140:143], v[208:211], v[38:41]
	v_mfma_f32_16x16x32_bf16 v[30:33], v[148:151], v[208:211], v[30:33]
	v_mfma_f32_16x16x32_bf16 v[22:25], v[140:143], v[236:239], v[22:25]
	v_mfma_f32_16x16x32_bf16 v[14:17], v[148:151], v[236:239], v[14:17]
	v_mfma_f32_16x16x32_bf16 v[62:65], v[144:147], v[196:199], v[62:65]
	v_mfma_f32_16x16x32_bf16 v[58:61], v[152:155], v[196:199], v[58:61]
	v_mfma_f32_16x16x32_bf16 v[54:57], v[144:147], v[204:207], v[54:57]
	v_mfma_f32_16x16x32_bf16 v[46:49], v[152:155], v[204:207], v[46:49]
	v_mfma_f32_16x16x32_bf16 v[38:41], v[144:147], v[232:235], v[38:41]
	v_mfma_f32_16x16x32_bf16 v[30:33], v[152:155], v[232:235], v[30:33]
	v_mfma_f32_16x16x32_bf16 v[22:25], v[144:147], v[240:243], v[22:25]
	v_mfma_f32_16x16x32_bf16 v[14:17], v[152:155], v[240:243], v[14:17]
	s_setprio 0
	s_setprio 1
	v_mfma_f32_16x16x32_bf16 v[50:53], v[156:159], v[192:195], v[50:53]
	v_mfma_f32_16x16x32_bf16 v[42:45], v[184:187], v[192:195], v[42:45]
	v_mfma_f32_16x16x32_bf16 v[34:37], v[156:159], v[200:203], v[34:37]
	v_mfma_f32_16x16x32_bf16 v[26:29], v[184:187], v[200:203], v[26:29]
	v_mfma_f32_16x16x32_bf16 v[18:21], v[156:159], v[208:211], v[18:21]
	v_mfma_f32_16x16x32_bf16 v[10:13], v[184:187], v[208:211], v[10:13]
	v_mfma_f32_16x16x32_bf16 v[6:9], v[156:159], v[236:239], v[6:9]
	v_mfma_f32_16x16x32_bf16 v[2:5], v[184:187], v[236:239], v[2:5]
	v_mfma_f32_16x16x32_bf16 v[50:53], v[180:183], v[196:199], v[50:53]
	v_mfma_f32_16x16x32_bf16 v[42:45], v[188:191], v[196:199], v[42:45]
	v_mfma_f32_16x16x32_bf16 v[34:37], v[180:183], v[204:207], v[34:37]
	v_mfma_f32_16x16x32_bf16 v[26:29], v[188:191], v[204:207], v[26:29]
	v_mfma_f32_16x16x32_bf16 v[18:21], v[180:183], v[232:235], v[18:21]
	v_mfma_f32_16x16x32_bf16 v[10:13], v[188:191], v[232:235], v[10:13]
	v_mfma_f32_16x16x32_bf16 v[6:9], v[180:183], v[240:243], v[6:9]
	v_mfma_f32_16x16x32_bf16 v[2:5], v[188:191], v[240:243], v[2:5]
	s_setprio 0
	s_barrier
	s_add_i32 s55, 0, 0x18000
	s_add_i32 s56, 0, 0x1c000
	v_add_u32_e32 v152, s55, v135
	v_add_u32_e32 v169, s56, v135
	ds_read_b128 v[140:143], v152
	ds_read_b128 v[144:147], v152 offset:1024
	ds_read_b128 v[148:151], v152 offset:2048
	ds_read_b128 v[152:155], v152 offset:3072
	ds_read_b128 v[156:159], v169
	ds_read_b128 v[180:183], v169 offset:1024
	ds_read_b128 v[184:187], v169 offset:2048
	ds_read_b128 v[188:191], v169 offset:3072
	s_add_u32 s28, s28, 0x80000
	s_addc_u32 s29, s29, 0
	s_mov_b32 m0, s36
	v_lshl_add_u64 v[246:247], s[28:29], 0, v[166:167]
	ds_read_b128 v[192:195], v139 offset:32768
	ds_read_b128 v[196:199], v139 offset:33792
	ds_read_b128 v[200:203], v139 offset:34816
	ds_read_b128 v[204:207], v139 offset:35840
	ds_read_b128 v[208:211], v139 offset:36864
	ds_read_b128 v[232:235], v139 offset:37888
	ds_read_b128 v[236:239], v139 offset:38912
	ds_read_b128 v[240:243], v139 offset:39936
	global_load_lds_dwordx4 v[246:247], off
	v_lshl_add_u64 v[246:247], s[28:29], 0, v[170:171]
	s_mov_b32 m0, s37
	s_nop 0
	global_load_lds_dwordx4 v[246:247], off
	s_waitcnt vmcnt(8)
	s_waitcnt lgkmcnt(0)
	s_barrier
	s_setprio 1
	s_waitcnt lgkmcnt(0)
	v_mfma_f32_16x16x32_bf16 v[126:129], v[140:143], v[192:195], v[126:129]
	v_mfma_f32_16x16x32_bf16 v[122:125], v[148:151], v[192:195], v[122:125]
	v_mfma_f32_16x16x32_bf16 v[118:121], v[140:143], v[200:203], v[118:121]
	v_mfma_f32_16x16x32_bf16 v[110:113], v[148:151], v[200:203], v[110:113]
	v_mfma_f32_16x16x32_bf16 v[102:105], v[140:143], v[208:211], v[102:105]
	v_mfma_f32_16x16x32_bf16 v[94:97], v[148:151], v[208:211], v[94:97]
	v_mfma_f32_16x16x32_bf16 v[86:89], v[140:143], v[236:239], v[86:89]
	v_mfma_f32_16x16x32_bf16 v[78:81], v[148:151], v[236:239], v[78:81]
	v_mfma_f32_16x16x32_bf16 v[126:129], v[144:147], v[196:199], v[126:129]
	v_mfma_f32_16x16x32_bf16 v[122:125], v[152:155], v[196:199], v[122:125]
	v_mfma_f32_16x16x32_bf16 v[118:121], v[144:147], v[204:207], v[118:121]
	v_mfma_f32_16x16x32_bf16 v[110:113], v[152:155], v[204:207], v[110:113]
	v_mfma_f32_16x16x32_bf16 v[102:105], v[144:147], v[232:235], v[102:105]
	v_mfma_f32_16x16x32_bf16 v[94:97], v[152:155], v[232:235], v[94:97]
	v_mfma_f32_16x16x32_bf16 v[86:89], v[144:147], v[240:243], v[86:89]
	v_mfma_f32_16x16x32_bf16 v[78:81], v[152:155], v[240:243], v[78:81]
	s_setprio 0
	s_setprio 1
	v_mfma_f32_16x16x32_bf16 v[114:117], v[156:159], v[192:195], v[114:117]
	v_mfma_f32_16x16x32_bf16 v[106:109], v[184:187], v[192:195], v[106:109]
	v_mfma_f32_16x16x32_bf16 v[98:101], v[156:159], v[200:203], v[98:101]
	v_mfma_f32_16x16x32_bf16 v[90:93], v[184:187], v[200:203], v[90:93]
	v_mfma_f32_16x16x32_bf16 v[82:85], v[156:159], v[208:211], v[82:85]
	v_mfma_f32_16x16x32_bf16 v[74:77], v[184:187], v[208:211], v[74:77]
	v_mfma_f32_16x16x32_bf16 v[70:73], v[156:159], v[236:239], v[70:73]
	v_mfma_f32_16x16x32_bf16 v[66:69], v[184:187], v[236:239], v[66:69]
	v_mfma_f32_16x16x32_bf16 v[114:117], v[180:183], v[196:199], v[114:117]
	v_mfma_f32_16x16x32_bf16 v[106:109], v[188:191], v[196:199], v[106:109]
	v_mfma_f32_16x16x32_bf16 v[98:101], v[180:183], v[204:207], v[98:101]
	v_mfma_f32_16x16x32_bf16 v[90:93], v[188:191], v[204:207], v[90:93]
	v_mfma_f32_16x16x32_bf16 v[82:85], v[180:183], v[232:235], v[82:85]
	v_mfma_f32_16x16x32_bf16 v[74:77], v[188:191], v[232:235], v[74:77]
	v_mfma_f32_16x16x32_bf16 v[70:73], v[180:183], v[240:243], v[70:73]
	v_mfma_f32_16x16x32_bf16 v[66:69], v[188:191], v[240:243], v[66:69]
	s_setprio 0
	s_barrier
; #define PG8_STAGE(bufoff, gbase, voff) do { _Pragma("unroll") for (int _i = 0; _i < 2; ++_i) \
;         __builtin_amdgcn_global_load_lds((const unsigned*)((const char*)(gbase) + (voff)[_i]), (PG8_LAS unsigned*)(lds + (bufoff) + ldsw + _i * 8192), 16, 0, 0); } while (0)
; #define PG8_LDA(dst, b, h) do { _Pragma("unroll") for (int m = 0; m < 4; ++m) _Pragma("unroll") for (int k = 0; k < 2; ++k) dst[m][k] = *(const PG8_LAS bf16x8*)(lds + PG8_SA(b, h) + aoff + m * 2048 + k * 1024); } while (0)
; #define PG8_MMA(ai, bj, At, Bt) do { __builtin_amdgcn_s_setprio(1); _Pragma("unroll") for (int m = 0; m < 4; ++m) _Pragma("unroll") for (int n = 0; n < 2; ++n) _Pragma("unroll") for (int k = 0; k < 2; ++k) \
;         acc[ai][bj][m][n] = __builtin_amdgcn_mfma_f32_16x16x32_bf16(Bt[n][k], At[m][k], acc[ai][bj][m][n], 0, 0, 0); __builtin_amdgcn_s_setprio(0); } while (0)
; #define PG8_WAIT_V(n) asm volatile("s_waitcnt vmcnt(" #n ")" ::: "memory")
; #define PG8_WAIT_L(n) asm volatile("s_waitcnt lgkmcnt(" #n ")" ::: "memory")
; #define PG8_BAR __builtin_amdgcn_s_barrier()
; #define PG8_SCHED __builtin_amdgcn_sched_barrier(0)
; template <class Epi, class Sched, bool ALIGN_EPI = false, bool SP2 = false>
; __device__ __forceinline__ void gemm_phase(PG8_LAS unsigned char* lds, const Gemm g, const Sched& S, const Epi& E) {
;     ...
;         for (int t = 0; t < nt; t += 2) {
;             const bool last = (t == nt - 2);
;             const char* a1 = cA + (size_t)(t + 1) * kstep;
;             const char* a2 = last ? nA : cA + (size_t)(t + 2) * kstep; const char* b2 = last ? nB : cB + (size_t)(t + 2) * kstep;
;     ...
;             PG8_LDA(At, 1, 1); PG8_STAGE(PG8_SB(1, 0), b3, voffB); PG8_STAGE(PG8_SB(1, 1), b3 + hstep, voffB); PG8_STAGE(PG8_SA(1, 0), a3, voffA);
;             PG8_WAIT_V(8); PG8_WAIT_L(0); PG8_BAR; PG8_MMA(1, 0, At, B0); PG8_MMA(1, 1, At, B1); PG8_BAR; PG8_SCHED;
	s_add_i32 s28, s55, s30
	v_lshl_add_u64 v[160:161], v[160:161], 0, s[4:5]
	s_mov_b32 m0, s28
	ds_read_b128 v[192:195], v139 offset:49152
	ds_read_b128 v[196:199], v139 offset:50176
	ds_read_b128 v[200:203], v139 offset:51200
	ds_read_b128 v[204:207], v139 offset:52224
	ds_read_b128 v[208:211], v139 offset:53248
	ds_read_b128 v[232:235], v139 offset:54272
	ds_read_b128 v[236:239], v139 offset:55296
	ds_read_b128 v[240:243], v139 offset:56320
	global_load_lds_dwordx4 v[160:161], off
	s_add_i32 m0, s28, 0x2000
	s_add_u32 s26, s26, 0x80080
	v_lshl_add_u64 v[160:161], v[212:213], 0, s[4:5]
	s_addc_u32 s27, s27, 0
	s_add_i32 s28, s56, s30
	global_load_lds_dwordx4 v[160:161], off
	v_lshl_add_u64 v[160:161], s[26:27], 0, v[166:167]
	s_mov_b32 m0, s28
	s_nop 0
	global_load_lds_dwordx4 v[160:161], off
	v_lshl_add_u64 v[160:161], s[26:27], 0, v[170:171]
	s_add_i32 m0, s28, 0x2000
	s_nop 0
	global_load_lds_dwordx4 v[160:161], off
	v_lshl_add_u64 v[160:161], v[222:223], 0, s[4:5]
	s_mov_b32 m0, s39
	s_nop 0
	global_load_lds_dwordx4 v[160:161], off
	v_lshl_add_u64 v[160:161], v[244:245], 0, s[4:5]
	s_mov_b32 m0, s40
	s_nop 0
	global_load_lds_dwordx4 v[160:161], off
	s_waitcnt vmcnt(8)
	s_waitcnt lgkmcnt(0)
	s_barrier
	s_setprio 1
	s_waitcnt lgkmcnt(0)
	v_mfma_f32_16x16x32_bf16 v[62:65], v[140:143], v[192:195], v[62:65]
	v_mfma_f32_16x16x32_bf16 v[58:61], v[148:151], v[192:195], v[58:61]
	v_mfma_f32_16x16x32_bf16 v[54:57], v[140:143], v[200:203], v[54:57]
	v_mfma_f32_16x16x32_bf16 v[46:49], v[148:151], v[200:203], v[46:49]
	v_mfma_f32_16x16x32_bf16 v[38:41], v[140:143], v[208:211], v[38:41]
	v_mfma_f32_16x16x32_bf16 v[30:33], v[148:151], v[208:211], v[30:33]
	v_mfma_f32_16x16x32_bf16 v[22:25], v[140:143], v[236:239], v[22:25]
	v_mfma_f32_16x16x32_bf16 v[14:17], v[148:151], v[236:239], v[14:17]
	v_mfma_f32_16x16x32_bf16 v[62:65], v[144:147], v[196:199], v[62:65]
	v_mfma_f32_16x16x32_bf16 v[58:61], v[152:155], v[196:199], v[58:61]
	v_mfma_f32_16x16x32_bf16 v[54:57], v[144:147], v[204:207], v[54:57]
	v_mfma_f32_16x16x32_bf16 v[46:49], v[152:155], v[204:207], v[46:49]
	v_mfma_f32_16x16x32_bf16 v[38:41], v[144:147], v[232:235], v[38:41]
	v_mfma_f32_16x16x32_bf16 v[30:33], v[152:155], v[232:235], v[30:33]
	v_mfma_f32_16x16x32_bf16 v[22:25], v[144:147], v[240:243], v[22:25]
	v_mfma_f32_16x16x32_bf16 v[14:17], v[152:155], v[240:243], v[14:17]
	s_setprio 0
	s_setprio 1
	v_mfma_f32_16x16x32_bf16 v[50:53], v[156:159], v[192:195], v[50:53]
	v_mfma_f32_16x16x32_bf16 v[42:45], v[184:187], v[192:195], v[42:45]
	v_mfma_f32_16x16x32_bf16 v[34:37], v[156:159], v[200:203], v[34:37]
	v_mfma_f32_16x16x32_bf16 v[26:29], v[184:187], v[200:203], v[26:29]
	v_mfma_f32_16x16x32_bf16 v[18:21], v[156:159], v[208:211], v[18:21]
	v_mfma_f32_16x16x32_bf16 v[10:13], v[184:187], v[208:211], v[10:13]
	v_mfma_f32_16x16x32_bf16 v[6:9], v[156:159], v[236:239], v[6:9]
	v_mfma_f32_16x16x32_bf16 v[2:5], v[184:187], v[236:239], v[2:5]
	v_mfma_f32_16x16x32_bf16 v[50:53], v[180:183], v[196:199], v[50:53]
	v_mfma_f32_16x16x32_bf16 v[42:45], v[188:191], v[196:199], v[42:45]
	v_mfma_f32_16x16x32_bf16 v[34:37], v[180:183], v[204:207], v[34:37]
	v_mfma_f32_16x16x32_bf16 v[26:29], v[188:191], v[204:207], v[26:29]
	v_mfma_f32_16x16x32_bf16 v[18:21], v[180:183], v[232:235], v[18:21]
	v_mfma_f32_16x16x32_bf16 v[10:13], v[188:191], v[232:235], v[10:13]
	v_mfma_f32_16x16x32_bf16 v[6:9], v[180:183], v[240:243], v[6:9]
	v_mfma_f32_16x16x32_bf16 v[2:5], v[188:191], v[240:243], v[2:5]
	s_setprio 0
	s_add_u32 s24, s24, 0x100
	s_addc_u32 s25, s25, 0
	s_add_u32 s49, s49, 0x100
	s_addc_u32 s53, s53, 0
	s_cmp_ge_u32 s54, s45
	s_mov_b32 s26, s54
	s_barrier
	s_cbranch_scc0 .LBB0_1053
	s_and_b64 vcc, exec, s[6:7]
	s_cbranch_vccz .LBB0_1056
	s_barrier

; #define PG8_STAGE(bufoff, gbase, voff) do { _Pragma("unroll") for (int _i = 0; _i < 2; ++_i) \
;         __builtin_amdgcn_global_load_lds((const unsigned*)((const char*)(gbase) + (voff)[_i]), (PG8_LAS unsigned*)(lds + (bufoff) + ldsw + _i * 8192), 16, 0, 0); } while (0)
; #define PG8_LDA(dst, b, h) do { _Pragma("unroll") for (int m = 0; m < 4; ++m) _Pragma("unroll") for (int k = 0; k < 2; ++k) dst[m][k] = *(const PG8_LAS bf16x8*)(lds + PG8_SA(b, h) + aoff + m * 2048 + k * 1024); } while (0)
; #define PG8_LDB(dst, b, h) do { _Pragma("unroll") for (int n = 0; n < 2; ++n) _Pragma("unroll") for (int k = 0; k < 2; ++k) dst[n][k] = *(const PG8_LAS bf16x8*)(lds + PG8_SB(b, h) + boff + n * 2048 + k * 1024); } while (0)
; #define PG8_MMA(ai, bj, At, Bt) do { __builtin_amdgcn_s_setprio(1); _Pragma("unroll") for (int m = 0; m < 4; ++m) _Pragma("unroll") for (int n = 0; n < 2; ++n) _Pragma("unroll") for (int k = 0; k < 2; ++k) \
;         acc[ai][bj][m][n] = __builtin_amdgcn_mfma_f32_16x16x32_bf16(Bt[n][k], At[m][k], acc[ai][bj][m][n], 0, 0, 0); __builtin_amdgcn_s_setprio(0); } while (0)
; #define PG8_WAIT_V(n) asm volatile("s_waitcnt vmcnt(" #n ")" ::: "memory")
; #define PG8_BAR __builtin_amdgcn_s_barrier()
; template <class Epi, class Sched, bool ALIGN_EPI = false, bool SP2 = false>
; __device__ __forceinline__ void gemm_phase(PG8_LAS unsigned char* lds, const Gemm g, const Sched& S, const Epi& E) {
;     ...
;         for (int t = 0; t < nt; t += 2) {
;             const bool last = (t == nt - 2);
;             const char* a1 = cA + (size_t)(t + 1) * kstep;
;             const char* a2 = last ? nA : cA + (size_t)(t + 2) * kstep; const char* b2 = last ? nB : cB + (size_t)(t + 2) * kstep;
;             const char* a3 = a2 + kstep; const char* b3 = b2 + kstep;
;             if (last && has_next) S.a_ready(nxt);
;             if constexpr (SP2) {
;             PG8_LDB(B0, 0, 0); PG8_LDB(B1, 0, 1); PG8_SCHED; PG8_LDA(At, 0, 0); PG8_STAGE(PG8_SA(1, 1), a1 + hstep, voffA);
;             PG8_WAIT_V(8); PG8_WAIT_L(0); PG8_BAR; PG8_MMA(0, 0, At, B0); PG8_MMA(0, 1, At, B1); PG8_BAR; PG8_SCHED;
;             PG8_LDA(At, 0, 1); PG8_STAGE(PG8_SB(0, 0), b2, voffB); PG8_STAGE(PG8_SB(0, 1), b2 + hstep, voffB); PG8_STAGE(PG8_SA(0, 0), a2, voffA);
;             PG8_WAIT_V(8); PG8_WAIT_L(0); PG8_BAR; PG8_MMA(1, 0, At, B0); PG8_MMA(1, 1, At, B1); PG8_BAR; PG8_SCHED;
.LBB0_1228:
	ds_read_b128 v[148:151], v145
	ds_read_b128 v[152:155], v145 offset:1024
	ds_read_b128 v[156:159], v145 offset:2048
	ds_read_b128 v[180:183], v145 offset:3072
	ds_read_b128 v[184:187], v146
	ds_read_b128 v[188:191], v146 offset:1024
	ds_read_b128 v[192:195], v146 offset:2048
	ds_read_b128 v[196:199], v146 offset:3072
	s_add_i32 s48, s47, 2
	s_add_u32 s24, s6, 0xfffe0080
	s_addc_u32 s25, s7, -1
	s_cmp_eq_u32 s44, s47
	s_cselect_b32 s27, s19, s25
	s_cselect_b32 s26, s42, s24
	s_cselect_b32 s25, s17, s46
	s_cselect_b32 s24, s43, s45
	v_lshl_add_u64 v[160:161], s[6:7], 0, v[134:135]
	s_add_i32 m0, s15, 0xc000
	ds_read_b128 v[200:203], v147
	ds_read_b128 v[204:207], v147 offset:1024
	ds_read_b128 v[208:211], v147 offset:2048
	ds_read_b128 v[228:231], v147 offset:3072
	ds_read_b128 v[232:235], v147 offset:4096
	ds_read_b128 v[236:239], v147 offset:5120
	ds_read_b128 v[240:243], v147 offset:6144
	ds_read_b128 v[244:247], v147 offset:7168
	global_load_lds_dwordx4 v[160:161], off
	v_lshl_add_u64 v[160:161], s[6:7], 0, v[136:137]
	s_add_i32 m0, s15, 0xe000
	s_nop 0
	global_load_lds_dwordx4 v[160:161], off
	s_waitcnt vmcnt(8)
	s_waitcnt lgkmcnt(0)
	s_barrier
	s_setprio 1
	s_waitcnt lgkmcnt(0)
	v_mfma_f32_16x16x32_bf16 v[126:129], v[148:151], v[200:203], v[126:129]
	v_mfma_f32_16x16x32_bf16 v[122:125], v[156:159], v[200:203], v[122:125]
	v_mfma_f32_16x16x32_bf16 v[118:121], v[148:151], v[208:211], v[118:121]
	v_mfma_f32_16x16x32_bf16 v[110:113], v[156:159], v[208:211], v[110:113]
	v_mfma_f32_16x16x32_bf16 v[102:105], v[148:151], v[232:235], v[102:105]
	v_mfma_f32_16x16x32_bf16 v[94:97], v[156:159], v[232:235], v[94:97]
	v_mfma_f32_16x16x32_bf16 v[86:89], v[148:151], v[240:243], v[86:89]
	v_mfma_f32_16x16x32_bf16 v[78:81], v[156:159], v[240:243], v[78:81]
	v_mfma_f32_16x16x32_bf16 v[126:129], v[152:155], v[204:207], v[126:129]
	v_mfma_f32_16x16x32_bf16 v[122:125], v[180:183], v[204:207], v[122:125]
	v_mfma_f32_16x16x32_bf16 v[118:121], v[152:155], v[228:231], v[118:121]
	v_mfma_f32_16x16x32_bf16 v[110:113], v[180:183], v[228:231], v[110:113]
	v_mfma_f32_16x16x32_bf16 v[102:105], v[152:155], v[236:239], v[102:105]
	v_mfma_f32_16x16x32_bf16 v[94:97], v[180:183], v[236:239], v[94:97]
	v_mfma_f32_16x16x32_bf16 v[86:89], v[152:155], v[244:247], v[86:89]
	v_mfma_f32_16x16x32_bf16 v[78:81], v[180:183], v[244:247], v[78:81]
	s_setprio 0
	s_setprio 1
	v_mfma_f32_16x16x32_bf16 v[114:117], v[184:187], v[200:203], v[114:117]
	v_mfma_f32_16x16x32_bf16 v[106:109], v[192:195], v[200:203], v[106:109]
	v_mfma_f32_16x16x32_bf16 v[98:101], v[184:187], v[208:211], v[98:101]
	v_mfma_f32_16x16x32_bf16 v[90:93], v[192:195], v[208:211], v[90:93]
	v_mfma_f32_16x16x32_bf16 v[82:85], v[184:187], v[232:235], v[82:85]
	v_mfma_f32_16x16x32_bf16 v[74:77], v[192:195], v[232:235], v[74:77]
	v_mfma_f32_16x16x32_bf16 v[70:73], v[184:187], v[240:243], v[70:73]
	v_mfma_f32_16x16x32_bf16 v[66:69], v[192:195], v[240:243], v[66:69]
	v_mfma_f32_16x16x32_bf16 v[114:117], v[188:191], v[204:207], v[114:117]
	v_mfma_f32_16x16x32_bf16 v[106:109], v[196:199], v[204:207], v[106:109]
	v_mfma_f32_16x16x32_bf16 v[98:101], v[188:191], v[228:231], v[98:101]
	v_mfma_f32_16x16x32_bf16 v[90:93], v[196:199], v[228:231], v[90:93]
	v_mfma_f32_16x16x32_bf16 v[82:85], v[188:191], v[236:239], v[82:85]
	v_mfma_f32_16x16x32_bf16 v[74:77], v[196:199], v[236:239], v[74:77]
	v_mfma_f32_16x16x32_bf16 v[70:73], v[188:191], v[244:247], v[70:73]
	v_mfma_f32_16x16x32_bf16 v[66:69], v[196:199], v[244:247], v[66:69]
	s_setprio 0
	s_barrier
	s_add_i32 s47, s37, s2
	v_lshl_add_u64 v[160:161], s[24:25], 0, v[132:133]
	s_mov_b32 m0, s47
	ds_read_b128 v[200:203], v147 offset:16384
	ds_read_b128 v[204:207], v147 offset:17408
	ds_read_b128 v[208:211], v147 offset:18432
	ds_read_b128 v[228:231], v147 offset:19456
	ds_read_b128 v[232:235], v147 offset:20480
	ds_read_b128 v[236:239], v147 offset:21504
	ds_read_b128 v[240:243], v147 offset:22528
	ds_read_b128 v[244:247], v147 offset:23552
	global_load_lds_dwordx4 v[160:161], off
	s_add_i32 m0, s47, 0x2000
	s_add_u32 s54, s24, 0x20000
	v_lshl_add_u64 v[212:213], s[24:25], 0, v[130:131]
	s_addc_u32 s55, s25, 0
	s_add_i32 s47, s38, s2
	global_load_lds_dwordx4 v[212:213], off
	v_lshl_add_u64 v[222:223], s[54:55], 0, v[132:133]
	s_mov_b32 m0, s47
	v_lshl_add_u64 v[248:249], s[26:27], 0, v[130:131]
	global_load_lds_dwordx4 v[222:223], off
	v_lshl_add_u64 v[222:223], s[54:55], 0, v[130:131]
	s_add_i32 m0, s47, 0x2000
	s_nop 0
	global_load_lds_dwordx4 v[222:223], off
	v_lshl_add_u64 v[222:223], s[26:27], 0, v[132:133]
	s_mov_b32 m0, s15
	s_nop 0
	global_load_lds_dwordx4 v[222:223], off
	s_mov_b32 m0, s29
	s_nop 0
	global_load_lds_dwordx4 v[248:249], off
	s_waitcnt vmcnt(8)
	s_waitcnt lgkmcnt(0)
	s_barrier
; #define PG8_STAGE(bufoff, gbase, voff) do { _Pragma("unroll") for (int _i = 0; _i < 2; ++_i) \
;         __builtin_amdgcn_global_load_lds((const unsigned*)((const char*)(gbase) + (voff)[_i]), (PG8_LAS unsigned*)(lds + (bufoff) + ldsw + _i * 8192), 16, 0, 0); } while (0)
; #define PG8_LDA(dst, b, h) do { _Pragma("unroll") for (int m = 0; m < 4; ++m) _Pragma("unroll") for (int k = 0; k < 2; ++k) dst[m][k] = *(const PG8_LAS bf16x8*)(lds + PG8_SA(b, h) + aoff + m * 2048 + k * 1024); } while (0)
; #define PG8_LDB(dst, b, h) do { _Pragma("unroll") for (int n = 0; n < 2; ++n) _Pragma("unroll") for (int k = 0; k < 2; ++k) dst[n][k] = *(const PG8_LAS bf16x8*)(lds + PG8_SB(b, h) + boff + n * 2048 + k * 1024); } while (0)
; #define PG8_MMA(ai, bj, At, Bt) do { __builtin_amdgcn_s_setprio(1); _Pragma("unroll") for (int m = 0; m < 4; ++m) _Pragma("unroll") for (int n = 0; n < 2; ++n) _Pragma("unroll") for (int k = 0; k < 2; ++k) \
;         acc[ai][bj][m][n] = __builtin_amdgcn_mfma_f32_16x16x32_bf16(Bt[n][k], At[m][k], acc[ai][bj][m][n], 0, 0, 0); __builtin_amdgcn_s_setprio(0); } while (0)
; #define PG8_WAIT_V(n) asm volatile("s_waitcnt vmcnt(" #n ")" ::: "memory")
; #define PG8_WAIT_L(n) asm volatile("s_waitcnt lgkmcnt(" #n ")" ::: "memory")
; #define PG8_BAR __builtin_amdgcn_s_barrier()
; #define PG8_SCHED __builtin_amdgcn_sched_barrier(0)
; template <class Epi, class Sched, bool ALIGN_EPI = false, bool SP2 = false>
; __device__ __forceinline__ void gemm_phase(PG8_LAS unsigned char* lds, const Gemm g, const Sched& S, const Epi& E) {
;     ...
;             PG8_WAIT_V(8); PG8_WAIT_L(0); PG8_BAR; PG8_MMA(1, 0, At, B0); PG8_MMA(1, 1, At, B1); PG8_BAR; PG8_SCHED;
;             PG8_LDB(B0, 1, 0); PG8_LDB(B1, 1, 1); PG8_SCHED; PG8_LDA(At, 1, 0); PG8_STAGE(PG8_SA(0, 1), a2 + hstep, voffA);
;             PG8_WAIT_V(8); PG8_WAIT_L(0); PG8_BAR; PG8_MMA(0, 0, At, B0); PG8_MMA(0, 1, At, B1); PG8_BAR; PG8_SCHED;
;             PG8_LDA(At, 1, 1); PG8_STAGE(PG8_SB(1, 0), b3, voffB); PG8_STAGE(PG8_SB(1, 1), b3 + hstep, voffB); PG8_STAGE(PG8_SA(1, 0), a3, voffA);
	s_setprio 1
	s_waitcnt lgkmcnt(0)
	v_mfma_f32_16x16x32_bf16 v[62:65], v[148:151], v[200:203], v[62:65]
	v_mfma_f32_16x16x32_bf16 v[58:61], v[156:159], v[200:203], v[58:61]
	v_mfma_f32_16x16x32_bf16 v[54:57], v[148:151], v[208:211], v[54:57]
	v_mfma_f32_16x16x32_bf16 v[46:49], v[156:159], v[208:211], v[46:49]
	v_mfma_f32_16x16x32_bf16 v[38:41], v[148:151], v[232:235], v[38:41]
	v_mfma_f32_16x16x32_bf16 v[30:33], v[156:159], v[232:235], v[30:33]
	v_mfma_f32_16x16x32_bf16 v[22:25], v[148:151], v[240:243], v[22:25]
	v_mfma_f32_16x16x32_bf16 v[14:17], v[156:159], v[240:243], v[14:17]
	v_mfma_f32_16x16x32_bf16 v[62:65], v[152:155], v[204:207], v[62:65]
	v_mfma_f32_16x16x32_bf16 v[58:61], v[180:183], v[204:207], v[58:61]
	v_mfma_f32_16x16x32_bf16 v[54:57], v[152:155], v[228:231], v[54:57]
	v_mfma_f32_16x16x32_bf16 v[46:49], v[180:183], v[228:231], v[46:49]
	v_mfma_f32_16x16x32_bf16 v[38:41], v[152:155], v[236:239], v[38:41]
	v_mfma_f32_16x16x32_bf16 v[30:33], v[180:183], v[236:239], v[30:33]
	v_mfma_f32_16x16x32_bf16 v[22:25], v[152:155], v[244:247], v[22:25]
	v_mfma_f32_16x16x32_bf16 v[14:17], v[180:183], v[244:247], v[14:17]
	s_setprio 0
	s_setprio 1
	v_mfma_f32_16x16x32_bf16 v[50:53], v[184:187], v[200:203], v[50:53]
	v_mfma_f32_16x16x32_bf16 v[42:45], v[192:195], v[200:203], v[42:45]
	v_mfma_f32_16x16x32_bf16 v[34:37], v[184:187], v[208:211], v[34:37]
	v_mfma_f32_16x16x32_bf16 v[26:29], v[192:195], v[208:211], v[26:29]
	v_mfma_f32_16x16x32_bf16 v[18:21], v[184:187], v[232:235], v[18:21]
	v_mfma_f32_16x16x32_bf16 v[10:13], v[192:195], v[232:235], v[10:13]
	v_mfma_f32_16x16x32_bf16 v[6:9], v[184:187], v[240:243], v[6:9]
	v_mfma_f32_16x16x32_bf16 v[2:5], v[192:195], v[240:243], v[2:5]
	v_mfma_f32_16x16x32_bf16 v[50:53], v[188:191], v[204:207], v[50:53]
	v_mfma_f32_16x16x32_bf16 v[42:45], v[196:199], v[204:207], v[42:45]
	v_mfma_f32_16x16x32_bf16 v[34:37], v[188:191], v[228:231], v[34:37]
	v_mfma_f32_16x16x32_bf16 v[26:29], v[196:199], v[228:231], v[26:29]
	v_mfma_f32_16x16x32_bf16 v[18:21], v[188:191], v[236:239], v[18:21]
	v_mfma_f32_16x16x32_bf16 v[10:13], v[196:199], v[236:239], v[10:13]
	v_mfma_f32_16x16x32_bf16 v[6:9], v[188:191], v[244:247], v[6:9]
	v_mfma_f32_16x16x32_bf16 v[2:5], v[196:199], v[244:247], v[2:5]
	s_setprio 0
	s_barrier
	s_add_i32 s47, 0, 0x18000
	v_add_u32_e32 v167, s47, v143
	s_add_i32 s49, 0, 0x1c000
	ds_read_b128 v[148:151], v167
	ds_read_b128 v[152:155], v167 offset:1024
	ds_read_b128 v[156:159], v167 offset:2048
	ds_read_b128 v[180:183], v167 offset:3072
	v_add_u32_e32 v167, s49, v143
	ds_read_b128 v[184:187], v167
	ds_read_b128 v[188:191], v167 offset:1024
	ds_read_b128 v[192:195], v167 offset:2048
	ds_read_b128 v[196:199], v167 offset:3072
	s_add_u32 s26, s26, 0x20000
	s_addc_u32 s27, s27, 0
	s_mov_b32 m0, s30
	v_lshl_add_u64 v[250:251], s[26:27], 0, v[132:133]
	ds_read_b128 v[200:203], v147 offset:32768
	ds_read_b128 v[204:207], v147 offset:33792
	ds_read_b128 v[208:211], v147 offset:34816
	ds_read_b128 v[228:231], v147 offset:35840
	ds_read_b128 v[232:235], v147 offset:36864
	ds_read_b128 v[236:239], v147 offset:37888
	ds_read_b128 v[240:243], v147 offset:38912
	ds_read_b128 v[244:247], v147 offset:39936
	global_load_lds_dwordx4 v[250:251], off
	v_lshl_add_u64 v[250:251], s[26:27], 0, v[130:131]
	s_mov_b32 m0, s31
	s_nop 0
	global_load_lds_dwordx4 v[250:251], off
	s_waitcnt vmcnt(8)
	s_waitcnt lgkmcnt(0)
	s_barrier
	s_setprio 1
	s_waitcnt lgkmcnt(0)
	v_mfma_f32_16x16x32_bf16 v[126:129], v[148:151], v[200:203], v[126:129]
	v_mfma_f32_16x16x32_bf16 v[122:125], v[156:159], v[200:203], v[122:125]
	v_mfma_f32_16x16x32_bf16 v[118:121], v[148:151], v[208:211], v[118:121]
	v_mfma_f32_16x16x32_bf16 v[110:113], v[156:159], v[208:211], v[110:113]
	v_mfma_f32_16x16x32_bf16 v[102:105], v[148:151], v[232:235], v[102:105]
	v_mfma_f32_16x16x32_bf16 v[94:97], v[156:159], v[232:235], v[94:97]
	v_mfma_f32_16x16x32_bf16 v[86:89], v[148:151], v[240:243], v[86:89]
	v_mfma_f32_16x16x32_bf16 v[78:81], v[156:159], v[240:243], v[78:81]
	v_mfma_f32_16x16x32_bf16 v[126:129], v[152:155], v[204:207], v[126:129]
	v_mfma_f32_16x16x32_bf16 v[122:125], v[180:183], v[204:207], v[122:125]
	v_mfma_f32_16x16x32_bf16 v[118:121], v[152:155], v[228:231], v[118:121]
	v_mfma_f32_16x16x32_bf16 v[110:113], v[180:183], v[228:231], v[110:113]
	v_mfma_f32_16x16x32_bf16 v[102:105], v[152:155], v[236:239], v[102:105]
	v_mfma_f32_16x16x32_bf16 v[94:97], v[180:183], v[236:239], v[94:97]
	v_mfma_f32_16x16x32_bf16 v[86:89], v[152:155], v[244:247], v[86:89]
	v_mfma_f32_16x16x32_bf16 v[78:81], v[180:183], v[244:247], v[78:81]
	s_setprio 0
	s_setprio 1
	v_mfma_f32_16x16x32_bf16 v[114:117], v[184:187], v[200:203], v[114:117]
	v_mfma_f32_16x16x32_bf16 v[106:109], v[192:195], v[200:203], v[106:109]
	v_mfma_f32_16x16x32_bf16 v[98:101], v[184:187], v[208:211], v[98:101]
	v_mfma_f32_16x16x32_bf16 v[90:93], v[192:195], v[208:211], v[90:93]
	v_mfma_f32_16x16x32_bf16 v[82:85], v[184:187], v[232:235], v[82:85]
	v_mfma_f32_16x16x32_bf16 v[74:77], v[192:195], v[232:235], v[74:77]
	v_mfma_f32_16x16x32_bf16 v[70:73], v[184:187], v[240:243], v[70:73]
	v_mfma_f32_16x16x32_bf16 v[66:69], v[192:195], v[240:243], v[66:69]
	v_mfma_f32_16x16x32_bf16 v[114:117], v[188:191], v[204:207], v[114:117]
	v_mfma_f32_16x16x32_bf16 v[106:109], v[196:199], v[204:207], v[106:109]
	v_mfma_f32_16x16x32_bf16 v[98:101], v[188:191], v[228:231], v[98:101]
	v_mfma_f32_16x16x32_bf16 v[90:93], v[196:199], v[228:231], v[90:93]
	v_mfma_f32_16x16x32_bf16 v[82:85], v[188:191], v[236:239], v[82:85]
	v_mfma_f32_16x16x32_bf16 v[74:77], v[196:199], v[236:239], v[74:77]
	v_mfma_f32_16x16x32_bf16 v[70:73], v[188:191], v[244:247], v[70:73]
	v_mfma_f32_16x16x32_bf16 v[66:69], v[196:199], v[244:247], v[66:69]
	s_setprio 0
	s_barrier
; #define PG8_STAGE(bufoff, gbase, voff) do { _Pragma("unroll") for (int _i = 0; _i < 2; ++_i) \
;         __builtin_amdgcn_global_load_lds((const unsigned*)((const char*)(gbase) + (voff)[_i]), (PG8_LAS unsigned*)(lds + (bufoff) + ldsw + _i * 8192), 16, 0, 0); } while (0)
; #define PG8_LDA(dst, b, h) do { _Pragma("unroll") for (int m = 0; m < 4; ++m) _Pragma("unroll") for (int k = 0; k < 2; ++k) dst[m][k] = *(const PG8_LAS bf16x8*)(lds + PG8_SA(b, h) + aoff + m * 2048 + k * 1024); } while (0)
; #define PG8_MMA(ai, bj, At, Bt) do { __builtin_amdgcn_s_setprio(1); _Pragma("unroll") for (int m = 0; m < 4; ++m) _Pragma("unroll") for (int n = 0; n < 2; ++n) _Pragma("unroll") for (int k = 0; k < 2; ++k) \
;         acc[ai][bj][m][n] = __builtin_amdgcn_mfma_f32_16x16x32_bf16(Bt[n][k], At[m][k], acc[ai][bj][m][n], 0, 0, 0); __builtin_amdgcn_s_setprio(0); } while (0)
; #define PG8_WAIT_V(n) asm volatile("s_waitcnt vmcnt(" #n ")" ::: "memory")
; #define PG8_WAIT_L(n) asm volatile("s_waitcnt lgkmcnt(" #n ")" ::: "memory")
; #define PG8_BAR __builtin_amdgcn_s_barrier()
; #define PG8_SCHED __builtin_amdgcn_sched_barrier(0)
; template <class Epi, class Sched, bool ALIGN_EPI = false, bool SP2 = false>
; __device__ __forceinline__ void gemm_phase(PG8_LAS unsigned char* lds, const Gemm g, const Sched& S, const Epi& E) {
;     ...
;         for (int t = 0; t < nt; t += 2) {
;             const bool last = (t == nt - 2);
;             const char* a1 = cA + (size_t)(t + 1) * kstep;
;             const char* a2 = last ? nA : cA + (size_t)(t + 2) * kstep; const char* b2 = last ? nB : cB + (size_t)(t + 2) * kstep;
;     ...
;             PG8_LDA(At, 1, 1); PG8_STAGE(PG8_SB(1, 0), b3, voffB); PG8_STAGE(PG8_SB(1, 1), b3 + hstep, voffB); PG8_STAGE(PG8_SA(1, 0), a3, voffA);
;             PG8_WAIT_V(8); PG8_WAIT_L(0); PG8_BAR; PG8_MMA(1, 0, At, B0); PG8_MMA(1, 1, At, B1); PG8_BAR; PG8_SCHED;
	s_add_i32 s26, s47, s2
	v_lshl_add_u64 v[160:161], v[160:161], 0, s[8:9]
	s_mov_b32 m0, s26
	ds_read_b128 v[200:203], v147 offset:49152
	ds_read_b128 v[204:207], v147 offset:50176
	ds_read_b128 v[208:211], v147 offset:51200
	ds_read_b128 v[228:231], v147 offset:52224
	ds_read_b128 v[232:235], v147 offset:53248
	ds_read_b128 v[236:239], v147 offset:54272
	ds_read_b128 v[240:243], v147 offset:55296
	ds_read_b128 v[244:247], v147 offset:56320
	global_load_lds_dwordx4 v[160:161], off
	s_add_i32 m0, s26, 0x2000
	s_add_u32 s24, s24, 0x20080
	v_lshl_add_u64 v[160:161], v[212:213], 0, s[8:9]
	s_addc_u32 s25, s25, 0
	s_add_i32 s26, s49, s2
	global_load_lds_dwordx4 v[160:161], off
	v_lshl_add_u64 v[160:161], s[24:25], 0, v[132:133]
	s_mov_b32 m0, s26
	s_nop 0
	global_load_lds_dwordx4 v[160:161], off
	v_lshl_add_u64 v[160:161], s[24:25], 0, v[130:131]
	s_add_i32 m0, s26, 0x2000
	s_nop 0
	global_load_lds_dwordx4 v[160:161], off
	v_lshl_add_u64 v[160:161], v[222:223], 0, s[8:9]
	s_mov_b32 m0, s34
	s_nop 0
	global_load_lds_dwordx4 v[160:161], off
	v_lshl_add_u64 v[160:161], v[248:249], 0, s[8:9]
	s_mov_b32 m0, s35
	s_nop 0
	global_load_lds_dwordx4 v[160:161], off
	s_waitcnt vmcnt(8)
	s_waitcnt lgkmcnt(0)
	s_barrier
	s_setprio 1
	s_waitcnt lgkmcnt(0)
	v_mfma_f32_16x16x32_bf16 v[62:65], v[148:151], v[200:203], v[62:65]
	v_mfma_f32_16x16x32_bf16 v[58:61], v[156:159], v[200:203], v[58:61]
	v_mfma_f32_16x16x32_bf16 v[54:57], v[148:151], v[208:211], v[54:57]
	v_mfma_f32_16x16x32_bf16 v[46:49], v[156:159], v[208:211], v[46:49]
	v_mfma_f32_16x16x32_bf16 v[38:41], v[148:151], v[232:235], v[38:41]
	v_mfma_f32_16x16x32_bf16 v[30:33], v[156:159], v[232:235], v[30:33]
	v_mfma_f32_16x16x32_bf16 v[22:25], v[148:151], v[240:243], v[22:25]
	v_mfma_f32_16x16x32_bf16 v[14:17], v[156:159], v[240:243], v[14:17]
	v_mfma_f32_16x16x32_bf16 v[62:65], v[152:155], v[204:207], v[62:65]
	v_mfma_f32_16x16x32_bf16 v[58:61], v[180:183], v[204:207], v[58:61]
	v_mfma_f32_16x16x32_bf16 v[54:57], v[152:155], v[228:231], v[54:57]
	v_mfma_f32_16x16x32_bf16 v[46:49], v[180:183], v[228:231], v[46:49]
	v_mfma_f32_16x16x32_bf16 v[38:41], v[152:155], v[236:239], v[38:41]
	v_mfma_f32_16x16x32_bf16 v[30:33], v[180:183], v[236:239], v[30:33]
	v_mfma_f32_16x16x32_bf16 v[22:25], v[152:155], v[244:247], v[22:25]
	v_mfma_f32_16x16x32_bf16 v[14:17], v[180:183], v[244:247], v[14:17]
	s_setprio 0
	s_setprio 1
	v_mfma_f32_16x16x32_bf16 v[50:53], v[184:187], v[200:203], v[50:53]
	v_mfma_f32_16x16x32_bf16 v[42:45], v[192:195], v[200:203], v[42:45]
	v_mfma_f32_16x16x32_bf16 v[34:37], v[184:187], v[208:211], v[34:37]
	v_mfma_f32_16x16x32_bf16 v[26:29], v[192:195], v[208:211], v[26:29]
	v_mfma_f32_16x16x32_bf16 v[18:21], v[184:187], v[232:235], v[18:21]
	v_mfma_f32_16x16x32_bf16 v[10:13], v[192:195], v[232:235], v[10:13]
	v_mfma_f32_16x16x32_bf16 v[6:9], v[184:187], v[240:243], v[6:9]
	v_mfma_f32_16x16x32_bf16 v[2:5], v[192:195], v[240:243], v[2:5]
	v_mfma_f32_16x16x32_bf16 v[50:53], v[188:191], v[204:207], v[50:53]
	v_mfma_f32_16x16x32_bf16 v[42:45], v[196:199], v[204:207], v[42:45]
	v_mfma_f32_16x16x32_bf16 v[34:37], v[188:191], v[228:231], v[34:37]
	v_mfma_f32_16x16x32_bf16 v[26:29], v[196:199], v[228:231], v[26:29]
	v_mfma_f32_16x16x32_bf16 v[18:21], v[188:191], v[236:239], v[18:21]
	v_mfma_f32_16x16x32_bf16 v[10:13], v[196:199], v[236:239], v[10:13]
	v_mfma_f32_16x16x32_bf16 v[6:9], v[188:191], v[244:247], v[6:9]
	v_mfma_f32_16x16x32_bf16 v[2:5], v[196:199], v[244:247], v[2:5]
	s_setprio 0
	s_add_u32 s6, s6, 0x100
	s_addc_u32 s7, s7, 0
	s_add_u32 s45, s45, 0x100
	s_addc_u32 s46, s46, 0
	s_cmp_ge_u32 s48, s40
	s_mov_b32 s47, s48
	s_barrier
	s_cbranch_scc0 .LBB0_1228
	s_and_b64 vcc, exec, s[10:11]
	s_cbranch_vccz .LBB0_1231
	s_barrier

; #define PG8_STAGE(bufoff, gbase, voff) do { _Pragma("unroll") for (int _i = 0; _i < 2; ++_i) \
;         __builtin_amdgcn_global_load_lds((const unsigned*)((const char*)(gbase) + (voff)[_i]), (PG8_LAS unsigned*)(lds + (bufoff) + ldsw + _i * 8192), 16, 0, 0); } while (0)
; #define PG8_LDA(dst, b, h) do { _Pragma("unroll") for (int m = 0; m < 4; ++m) _Pragma("unroll") for (int k = 0; k < 2; ++k) dst[m][k] = *(const PG8_LAS bf16x8*)(lds + PG8_SA(b, h) + aoff + m * 2048 + k * 1024); } while (0)
; #define PG8_LDB(dst, b, h) do { _Pragma("unroll") for (int n = 0; n < 2; ++n) _Pragma("unroll") for (int k = 0; k < 2; ++k) dst[n][k] = *(const PG8_LAS bf16x8*)(lds + PG8_SB(b, h) + boff + n * 2048 + k * 1024); } while (0)
; #define PG8_MMA(ai, bj, At, Bt) do { __builtin_amdgcn_s_setprio(1); _Pragma("unroll") for (int m = 0; m < 4; ++m) _Pragma("unroll") for (int n = 0; n < 2; ++n) _Pragma("unroll") for (int k = 0; k < 2; ++k) \
;         acc[ai][bj][m][n] = __builtin_amdgcn_mfma_f32_16x16x32_bf16(Bt[n][k], At[m][k], acc[ai][bj][m][n], 0, 0, 0); __builtin_amdgcn_s_setprio(0); } while (0)
; #define PG8_WAIT_V(n) asm volatile("s_waitcnt vmcnt(" #n ")" ::: "memory")
; #define PG8_BAR __builtin_amdgcn_s_barrier()
; template <class Epi, class Sched, bool ALIGN_EPI = false, bool SP2 = false>
; __device__ __forceinline__ void gemm_phase(PG8_LAS unsigned char* lds, const Gemm g, const Sched& S, const Epi& E) {
;     ...
;         for (int t = 0; t < nt; t += 2) {
;             const bool last = (t == nt - 2);
;             const char* a1 = cA + (size_t)(t + 1) * kstep;
;             const char* a2 = last ? nA : cA + (size_t)(t + 2) * kstep; const char* b2 = last ? nB : cB + (size_t)(t + 2) * kstep;
;             const char* a3 = a2 + kstep; const char* b3 = b2 + kstep;
;             if (last && has_next) S.a_ready(nxt);
;             if constexpr (SP2) {
;             PG8_LDB(B0, 0, 0); PG8_LDB(B1, 0, 1); PG8_SCHED; PG8_LDA(At, 0, 0); PG8_STAGE(PG8_SA(1, 1), a1 + hstep, voffA);
;             PG8_WAIT_V(8); PG8_WAIT_L(0); PG8_BAR; PG8_MMA(0, 0, At, B0); PG8_MMA(0, 1, At, B1); PG8_BAR; PG8_SCHED;
;             PG8_LDA(At, 0, 1); PG8_STAGE(PG8_SB(0, 0), b2, voffB); PG8_STAGE(PG8_SB(0, 1), b2 + hstep, voffB); PG8_STAGE(PG8_SA(0, 0), a2, voffA);
;             PG8_WAIT_V(8); PG8_WAIT_L(0); PG8_BAR; PG8_MMA(1, 0, At, B0); PG8_MMA(1, 1, At, B1); PG8_BAR; PG8_SCHED;
.LBB0_1373:
	ds_read_b128 v[146:149], v143
	ds_read_b128 v[150:153], v143 offset:1024
	ds_read_b128 v[154:157], v143 offset:2048
	ds_read_b128 v[158:161], v143 offset:3072
	ds_read_b128 v[178:181], v144
	ds_read_b128 v[182:185], v144 offset:1024
	ds_read_b128 v[186:189], v144 offset:2048
	ds_read_b128 v[190:193], v144 offset:3072
	s_add_i32 s47, s46, 2
	s_add_u32 s22, s0, 0xfff80080
	s_addc_u32 s23, s1, -1
	s_cmp_eq_u32 s43, s46
	s_cselect_b32 s25, s15, s23
	s_cselect_b32 s24, s41, s22
	s_cselect_b32 s23, s13, s45
	s_cselect_b32 s22, s42, s44
	v_lshl_add_u64 v[138:139], s[0:1], 0, v[130:131]
	s_add_i32 m0, s21, 0xc000
	ds_read_b128 v[194:197], v145
	ds_read_b128 v[198:201], v145 offset:1024
	ds_read_b128 v[202:205], v145 offset:2048
	ds_read_b128 v[206:209], v145 offset:3072
	ds_read_b128 v[210:213], v145 offset:4096
	ds_read_b128 v[218:221], v145 offset:5120
	ds_read_b128 v[228:231], v145 offset:6144
	ds_read_b128 v[232:235], v145 offset:7168
	global_load_lds_dwordx4 v[138:139], off
	v_lshl_add_u64 v[138:139], s[0:1], 0, v[132:133]
	s_add_i32 m0, s21, 0xe000
	s_nop 0
	global_load_lds_dwordx4 v[138:139], off
	s_waitcnt vmcnt(8)
	s_waitcnt lgkmcnt(0)
	s_barrier
	s_setprio 1
	s_waitcnt lgkmcnt(0)
	v_mfma_f32_16x16x32_bf16 v[126:129], v[146:149], v[194:197], v[126:129]
	v_mfma_f32_16x16x32_bf16 v[122:125], v[154:157], v[194:197], v[122:125]
	v_mfma_f32_16x16x32_bf16 v[110:113], v[146:149], v[202:205], v[110:113]
	v_mfma_f32_16x16x32_bf16 v[106:109], v[154:157], v[202:205], v[106:109]
	v_mfma_f32_16x16x32_bf16 v[94:97], v[146:149], v[210:213], v[94:97]
	v_mfma_f32_16x16x32_bf16 v[90:93], v[154:157], v[210:213], v[90:93]
	v_mfma_f32_16x16x32_bf16 v[78:81], v[146:149], v[228:231], v[78:81]
	v_mfma_f32_16x16x32_bf16 v[74:77], v[154:157], v[228:231], v[74:77]
	v_mfma_f32_16x16x32_bf16 v[126:129], v[150:153], v[198:201], v[126:129]
	v_mfma_f32_16x16x32_bf16 v[122:125], v[158:161], v[198:201], v[122:125]
	v_mfma_f32_16x16x32_bf16 v[110:113], v[150:153], v[206:209], v[110:113]
	v_mfma_f32_16x16x32_bf16 v[106:109], v[158:161], v[206:209], v[106:109]
	v_mfma_f32_16x16x32_bf16 v[94:97], v[150:153], v[218:221], v[94:97]
	v_mfma_f32_16x16x32_bf16 v[90:93], v[158:161], v[218:221], v[90:93]
	v_mfma_f32_16x16x32_bf16 v[78:81], v[150:153], v[232:235], v[78:81]
	v_mfma_f32_16x16x32_bf16 v[74:77], v[158:161], v[232:235], v[74:77]
	s_setprio 0
	s_setprio 1
	v_mfma_f32_16x16x32_bf16 v[118:121], v[178:181], v[194:197], v[118:121]
	v_mfma_f32_16x16x32_bf16 v[114:117], v[186:189], v[194:197], v[114:117]
	v_mfma_f32_16x16x32_bf16 v[102:105], v[178:181], v[202:205], v[102:105]
	v_mfma_f32_16x16x32_bf16 v[98:101], v[186:189], v[202:205], v[98:101]
	v_mfma_f32_16x16x32_bf16 v[86:89], v[178:181], v[210:213], v[86:89]
	v_mfma_f32_16x16x32_bf16 v[82:85], v[186:189], v[210:213], v[82:85]
	v_mfma_f32_16x16x32_bf16 v[70:73], v[178:181], v[228:231], v[70:73]
	v_mfma_f32_16x16x32_bf16 v[66:69], v[186:189], v[228:231], v[66:69]
	v_mfma_f32_16x16x32_bf16 v[118:121], v[182:185], v[198:201], v[118:121]
	v_mfma_f32_16x16x32_bf16 v[114:117], v[190:193], v[198:201], v[114:117]
	v_mfma_f32_16x16x32_bf16 v[102:105], v[182:185], v[206:209], v[102:105]
	v_mfma_f32_16x16x32_bf16 v[98:101], v[190:193], v[206:209], v[98:101]
	v_mfma_f32_16x16x32_bf16 v[86:89], v[182:185], v[218:221], v[86:89]
	v_mfma_f32_16x16x32_bf16 v[82:85], v[190:193], v[218:221], v[82:85]
	v_mfma_f32_16x16x32_bf16 v[70:73], v[182:185], v[232:235], v[70:73]
	v_mfma_f32_16x16x32_bf16 v[66:69], v[190:193], v[232:235], v[66:69]
	s_setprio 0
	s_barrier
	s_add_i32 s46, s35, s2
	v_lshl_add_u64 v[138:139], s[22:23], 0, v[168:169]
	s_mov_b32 m0, s46
	ds_read_b128 v[194:197], v145 offset:16384
	ds_read_b128 v[198:201], v145 offset:17408
	ds_read_b128 v[202:205], v145 offset:18432
	ds_read_b128 v[206:209], v145 offset:19456
	ds_read_b128 v[210:213], v145 offset:20480
	ds_read_b128 v[218:221], v145 offset:21504
	ds_read_b128 v[228:231], v145 offset:22528
	ds_read_b128 v[232:235], v145 offset:23552
	global_load_lds_dwordx4 v[138:139], off
	s_add_i32 m0, s46, 0x2000
	s_add_u32 s48, s22, 0x80000
	v_lshl_add_u64 v[222:223], s[22:23], 0, v[172:173]
	s_addc_u32 s49, s23, 0
	s_add_i32 s46, s36, s2
	global_load_lds_dwordx4 v[222:223], off
	v_lshl_add_u64 v[236:237], s[48:49], 0, v[168:169]
	s_mov_b32 m0, s46
	v_lshl_add_u64 v[238:239], s[24:25], 0, v[170:171]
	global_load_lds_dwordx4 v[236:237], off
	v_lshl_add_u64 v[236:237], s[48:49], 0, v[172:173]
	s_add_i32 m0, s46, 0x2000
	s_nop 0
	global_load_lds_dwordx4 v[236:237], off
	v_lshl_add_u64 v[236:237], s[24:25], 0, v[166:167]
	s_mov_b32 m0, s21
	s_nop 0
	global_load_lds_dwordx4 v[236:237], off
	s_mov_b32 m0, s27
	s_nop 0
	global_load_lds_dwordx4 v[238:239], off
	s_waitcnt vmcnt(8)
	s_waitcnt lgkmcnt(0)
	s_barrier
; #define PG8_STAGE(bufoff, gbase, voff) do { _Pragma("unroll") for (int _i = 0; _i < 2; ++_i) \
;         __builtin_amdgcn_global_load_lds((const unsigned*)((const char*)(gbase) + (voff)[_i]), (PG8_LAS unsigned*)(lds + (bufoff) + ldsw + _i * 8192), 16, 0, 0); } while (0)
; #define PG8_LDA(dst, b, h) do { _Pragma("unroll") for (int m = 0; m < 4; ++m) _Pragma("unroll") for (int k = 0; k < 2; ++k) dst[m][k] = *(const PG8_LAS bf16x8*)(lds + PG8_SA(b, h) + aoff + m * 2048 + k * 1024); } while (0)
; #define PG8_LDB(dst, b, h) do { _Pragma("unroll") for (int n = 0; n < 2; ++n) _Pragma("unroll") for (int k = 0; k < 2; ++k) dst[n][k] = *(const PG8_LAS bf16x8*)(lds + PG8_SB(b, h) + boff + n * 2048 + k * 1024); } while (0)
; #define PG8_MMA(ai, bj, At, Bt) do { __builtin_amdgcn_s_setprio(1); _Pragma("unroll") for (int m = 0; m < 4; ++m) _Pragma("unroll") for (int n = 0; n < 2; ++n) _Pragma("unroll") for (int k = 0; k < 2; ++k) \
;         acc[ai][bj][m][n] = __builtin_amdgcn_mfma_f32_16x16x32_bf16(Bt[n][k], At[m][k], acc[ai][bj][m][n], 0, 0, 0); __builtin_amdgcn_s_setprio(0); } while (0)
; #define PG8_WAIT_V(n) asm volatile("s_waitcnt vmcnt(" #n ")" ::: "memory")
; #define PG8_WAIT_L(n) asm volatile("s_waitcnt lgkmcnt(" #n ")" ::: "memory")
; #define PG8_BAR __builtin_amdgcn_s_barrier()
; #define PG8_SCHED __builtin_amdgcn_sched_barrier(0)
; template <class Epi, class Sched, bool ALIGN_EPI = false, bool SP2 = false>
; __device__ __forceinline__ void gemm_phase(PG8_LAS unsigned char* lds, const Gemm g, const Sched& S, const Epi& E) {
;     ...
;             PG8_WAIT_V(8); PG8_WAIT_L(0); PG8_BAR; PG8_MMA(1, 0, At, B0); PG8_MMA(1, 1, At, B1); PG8_BAR; PG8_SCHED;
;             PG8_LDB(B0, 1, 0); PG8_LDB(B1, 1, 1); PG8_SCHED; PG8_LDA(At, 1, 0); PG8_STAGE(PG8_SA(0, 1), a2 + hstep, voffA);
;             PG8_WAIT_V(8); PG8_WAIT_L(0); PG8_BAR; PG8_MMA(0, 0, At, B0); PG8_MMA(0, 1, At, B1); PG8_BAR; PG8_SCHED;
;             PG8_LDA(At, 1, 1); PG8_STAGE(PG8_SB(1, 0), b3, voffB); PG8_STAGE(PG8_SB(1, 1), b3 + hstep, voffB); PG8_STAGE(PG8_SA(1, 0), a3, voffA);
	s_setprio 1
	s_waitcnt lgkmcnt(0)
	v_mfma_f32_16x16x32_bf16 v[62:65], v[146:149], v[194:197], v[62:65]
	v_mfma_f32_16x16x32_bf16 v[58:61], v[154:157], v[194:197], v[58:61]
	v_mfma_f32_16x16x32_bf16 v[46:49], v[146:149], v[202:205], v[46:49]
	v_mfma_f32_16x16x32_bf16 v[42:45], v[154:157], v[202:205], v[42:45]
	v_mfma_f32_16x16x32_bf16 v[30:33], v[146:149], v[210:213], v[30:33]
	v_mfma_f32_16x16x32_bf16 v[26:29], v[154:157], v[210:213], v[26:29]
	v_mfma_f32_16x16x32_bf16 v[14:17], v[146:149], v[228:231], v[14:17]
	v_mfma_f32_16x16x32_bf16 v[10:13], v[154:157], v[228:231], v[10:13]
	v_mfma_f32_16x16x32_bf16 v[62:65], v[150:153], v[198:201], v[62:65]
	v_mfma_f32_16x16x32_bf16 v[58:61], v[158:161], v[198:201], v[58:61]
	v_mfma_f32_16x16x32_bf16 v[46:49], v[150:153], v[206:209], v[46:49]
	v_mfma_f32_16x16x32_bf16 v[42:45], v[158:161], v[206:209], v[42:45]
	v_mfma_f32_16x16x32_bf16 v[30:33], v[150:153], v[218:221], v[30:33]
	v_mfma_f32_16x16x32_bf16 v[26:29], v[158:161], v[218:221], v[26:29]
	v_mfma_f32_16x16x32_bf16 v[14:17], v[150:153], v[232:235], v[14:17]
	v_mfma_f32_16x16x32_bf16 v[10:13], v[158:161], v[232:235], v[10:13]
	s_setprio 0
	s_setprio 1
	v_mfma_f32_16x16x32_bf16 v[54:57], v[178:181], v[194:197], v[54:57]
	v_mfma_f32_16x16x32_bf16 v[50:53], v[186:189], v[194:197], v[50:53]
	v_mfma_f32_16x16x32_bf16 v[38:41], v[178:181], v[202:205], v[38:41]
	v_mfma_f32_16x16x32_bf16 v[34:37], v[186:189], v[202:205], v[34:37]
	v_mfma_f32_16x16x32_bf16 v[22:25], v[178:181], v[210:213], v[22:25]
	v_mfma_f32_16x16x32_bf16 v[18:21], v[186:189], v[210:213], v[18:21]
	v_mfma_f32_16x16x32_bf16 v[6:9], v[178:181], v[228:231], v[6:9]
	v_mfma_f32_16x16x32_bf16 v[2:5], v[186:189], v[228:231], v[2:5]
	v_mfma_f32_16x16x32_bf16 v[54:57], v[182:185], v[198:201], v[54:57]
	v_mfma_f32_16x16x32_bf16 v[50:53], v[190:193], v[198:201], v[50:53]
	v_mfma_f32_16x16x32_bf16 v[38:41], v[182:185], v[206:209], v[38:41]
	v_mfma_f32_16x16x32_bf16 v[34:37], v[190:193], v[206:209], v[34:37]
	v_mfma_f32_16x16x32_bf16 v[22:25], v[182:185], v[218:221], v[22:25]
	v_mfma_f32_16x16x32_bf16 v[18:21], v[190:193], v[218:221], v[18:21]
	v_mfma_f32_16x16x32_bf16 v[6:9], v[182:185], v[232:235], v[6:9]
	v_mfma_f32_16x16x32_bf16 v[2:5], v[190:193], v[232:235], v[2:5]
	s_setprio 0
	s_barrier
	s_add_i32 s46, 0, 0x18000
	s_add_i32 s48, 0, 0x1c000
	v_add_u32_e32 v158, s46, v141
	v_add_u32_e32 v175, s48, v141
	ds_read_b128 v[146:149], v158
	ds_read_b128 v[150:153], v158 offset:1024
	ds_read_b128 v[154:157], v158 offset:2048
	ds_read_b128 v[158:161], v158 offset:3072
	ds_read_b128 v[178:181], v175
	ds_read_b128 v[182:185], v175 offset:1024
	ds_read_b128 v[186:189], v175 offset:2048
	ds_read_b128 v[190:193], v175 offset:3072
	s_add_u32 s24, s24, 0x80000
	s_addc_u32 s25, s25, 0
	s_mov_b32 m0, s28
	v_lshl_add_u64 v[240:241], s[24:25], 0, v[166:167]
	ds_read_b128 v[194:197], v145 offset:32768
	ds_read_b128 v[198:201], v145 offset:33792
	ds_read_b128 v[202:205], v145 offset:34816
	ds_read_b128 v[206:209], v145 offset:35840
	ds_read_b128 v[210:213], v145 offset:36864
	ds_read_b128 v[218:221], v145 offset:37888
	ds_read_b128 v[228:231], v145 offset:38912
	ds_read_b128 v[232:235], v145 offset:39936
	global_load_lds_dwordx4 v[240:241], off
	v_lshl_add_u64 v[240:241], s[24:25], 0, v[170:171]
	s_mov_b32 m0, s29
	s_nop 0
	global_load_lds_dwordx4 v[240:241], off
	s_waitcnt vmcnt(8)
	s_waitcnt lgkmcnt(0)
	s_barrier
	s_setprio 1
	s_waitcnt lgkmcnt(0)
	v_mfma_f32_16x16x32_bf16 v[126:129], v[146:149], v[194:197], v[126:129]
	v_mfma_f32_16x16x32_bf16 v[122:125], v[154:157], v[194:197], v[122:125]
	v_mfma_f32_16x16x32_bf16 v[110:113], v[146:149], v[202:205], v[110:113]
	v_mfma_f32_16x16x32_bf16 v[106:109], v[154:157], v[202:205], v[106:109]
	v_mfma_f32_16x16x32_bf16 v[94:97], v[146:149], v[210:213], v[94:97]
	v_mfma_f32_16x16x32_bf16 v[90:93], v[154:157], v[210:213], v[90:93]
	v_mfma_f32_16x16x32_bf16 v[78:81], v[146:149], v[228:231], v[78:81]
	v_mfma_f32_16x16x32_bf16 v[74:77], v[154:157], v[228:231], v[74:77]
	v_mfma_f32_16x16x32_bf16 v[126:129], v[150:153], v[198:201], v[126:129]
	v_mfma_f32_16x16x32_bf16 v[122:125], v[158:161], v[198:201], v[122:125]
	v_mfma_f32_16x16x32_bf16 v[110:113], v[150:153], v[206:209], v[110:113]
	v_mfma_f32_16x16x32_bf16 v[106:109], v[158:161], v[206:209], v[106:109]
	v_mfma_f32_16x16x32_bf16 v[94:97], v[150:153], v[218:221], v[94:97]
	v_mfma_f32_16x16x32_bf16 v[90:93], v[158:161], v[218:221], v[90:93]
	v_mfma_f32_16x16x32_bf16 v[78:81], v[150:153], v[232:235], v[78:81]
	v_mfma_f32_16x16x32_bf16 v[74:77], v[158:161], v[232:235], v[74:77]
	s_setprio 0
	s_setprio 1
	v_mfma_f32_16x16x32_bf16 v[118:121], v[178:181], v[194:197], v[118:121]
	v_mfma_f32_16x16x32_bf16 v[114:117], v[186:189], v[194:197], v[114:117]
	v_mfma_f32_16x16x32_bf16 v[102:105], v[178:181], v[202:205], v[102:105]
	v_mfma_f32_16x16x32_bf16 v[98:101], v[186:189], v[202:205], v[98:101]
	v_mfma_f32_16x16x32_bf16 v[86:89], v[178:181], v[210:213], v[86:89]
	v_mfma_f32_16x16x32_bf16 v[82:85], v[186:189], v[210:213], v[82:85]
	v_mfma_f32_16x16x32_bf16 v[70:73], v[178:181], v[228:231], v[70:73]
	v_mfma_f32_16x16x32_bf16 v[66:69], v[186:189], v[228:231], v[66:69]
	v_mfma_f32_16x16x32_bf16 v[118:121], v[182:185], v[198:201], v[118:121]
	v_mfma_f32_16x16x32_bf16 v[114:117], v[190:193], v[198:201], v[114:117]
	v_mfma_f32_16x16x32_bf16 v[102:105], v[182:185], v[206:209], v[102:105]
	v_mfma_f32_16x16x32_bf16 v[98:101], v[190:193], v[206:209], v[98:101]
	v_mfma_f32_16x16x32_bf16 v[86:89], v[182:185], v[218:221], v[86:89]
	v_mfma_f32_16x16x32_bf16 v[82:85], v[190:193], v[218:221], v[82:85]
	v_mfma_f32_16x16x32_bf16 v[70:73], v[182:185], v[232:235], v[70:73]
	v_mfma_f32_16x16x32_bf16 v[66:69], v[190:193], v[232:235], v[66:69]
	s_setprio 0
	s_barrier
; #define PG8_STAGE(bufoff, gbase, voff) do { _Pragma("unroll") for (int _i = 0; _i < 2; ++_i) \
;         __builtin_amdgcn_global_load_lds((const unsigned*)((const char*)(gbase) + (voff)[_i]), (PG8_LAS unsigned*)(lds + (bufoff) + ldsw + _i * 8192), 16, 0, 0); } while (0)
; #define PG8_LDA(dst, b, h) do { _Pragma("unroll") for (int m = 0; m < 4; ++m) _Pragma("unroll") for (int k = 0; k < 2; ++k) dst[m][k] = *(const PG8_LAS bf16x8*)(lds + PG8_SA(b, h) + aoff + m * 2048 + k * 1024); } while (0)
; #define PG8_MMA(ai, bj, At, Bt) do { __builtin_amdgcn_s_setprio(1); _Pragma("unroll") for (int m = 0; m < 4; ++m) _Pragma("unroll") for (int n = 0; n < 2; ++n) _Pragma("unroll") for (int k = 0; k < 2; ++k) \
;         acc[ai][bj][m][n] = __builtin_amdgcn_mfma_f32_16x16x32_bf16(Bt[n][k], At[m][k], acc[ai][bj][m][n], 0, 0, 0); __builtin_amdgcn_s_setprio(0); } while (0)
; #define PG8_WAIT_V(n) asm volatile("s_waitcnt vmcnt(" #n ")" ::: "memory")
; #define PG8_WAIT_L(n) asm volatile("s_waitcnt lgkmcnt(" #n ")" ::: "memory")
; #define PG8_BAR __builtin_amdgcn_s_barrier()
; #define PG8_SCHED __builtin_amdgcn_sched_barrier(0)
; template <class Epi, class Sched, bool ALIGN_EPI = false, bool SP2 = false>
; __device__ __forceinline__ void gemm_phase(PG8_LAS unsigned char* lds, const Gemm g, const Sched& S, const Epi& E) {
;     ...
;         for (int t = 0; t < nt; t += 2) {
;             const bool last = (t == nt - 2);
;             const char* a1 = cA + (size_t)(t + 1) * kstep;
;             const char* a2 = last ? nA : cA + (size_t)(t + 2) * kstep; const char* b2 = last ? nB : cB + (size_t)(t + 2) * kstep;
;     ...
;             PG8_LDA(At, 1, 1); PG8_STAGE(PG8_SB(1, 0), b3, voffB); PG8_STAGE(PG8_SB(1, 1), b3 + hstep, voffB); PG8_STAGE(PG8_SA(1, 0), a3, voffA);
;             PG8_WAIT_V(8); PG8_WAIT_L(0); PG8_BAR; PG8_MMA(1, 0, At, B0); PG8_MMA(1, 1, At, B1); PG8_BAR; PG8_SCHED;
	s_add_i32 s24, s46, s2
	v_lshl_add_u64 v[138:139], v[138:139], 0, s[8:9]
	s_mov_b32 m0, s24
	ds_read_b128 v[194:197], v145 offset:49152
	ds_read_b128 v[198:201], v145 offset:50176
	ds_read_b128 v[202:205], v145 offset:51200
	ds_read_b128 v[206:209], v145 offset:52224
	ds_read_b128 v[210:213], v145 offset:53248
	ds_read_b128 v[218:221], v145 offset:54272
	ds_read_b128 v[228:231], v145 offset:55296
	ds_read_b128 v[232:235], v145 offset:56320
	global_load_lds_dwordx4 v[138:139], off
	s_add_i32 m0, s24, 0x2000
	s_add_u32 s22, s22, 0x80080
	v_lshl_add_u64 v[138:139], v[222:223], 0, s[8:9]
	s_addc_u32 s23, s23, 0
	s_add_i32 s24, s48, s2
	global_load_lds_dwordx4 v[138:139], off
	v_lshl_add_u64 v[138:139], s[22:23], 0, v[168:169]
	s_mov_b32 m0, s24
	s_nop 0
	global_load_lds_dwordx4 v[138:139], off
	v_lshl_add_u64 v[138:139], s[22:23], 0, v[172:173]
	s_add_i32 m0, s24, 0x2000
	s_nop 0
	global_load_lds_dwordx4 v[138:139], off
	v_lshl_add_u64 v[138:139], v[236:237], 0, s[8:9]
	s_mov_b32 m0, s31
	s_nop 0
	global_load_lds_dwordx4 v[138:139], off
	v_lshl_add_u64 v[138:139], v[238:239], 0, s[8:9]
	s_mov_b32 m0, s33
	s_nop 0
	global_load_lds_dwordx4 v[138:139], off
	s_waitcnt vmcnt(8)
	s_waitcnt lgkmcnt(0)
	s_barrier
	s_setprio 1
	s_waitcnt lgkmcnt(0)
	v_mfma_f32_16x16x32_bf16 v[62:65], v[146:149], v[194:197], v[62:65]
	v_mfma_f32_16x16x32_bf16 v[58:61], v[154:157], v[194:197], v[58:61]
	v_mfma_f32_16x16x32_bf16 v[46:49], v[146:149], v[202:205], v[46:49]
	v_mfma_f32_16x16x32_bf16 v[42:45], v[154:157], v[202:205], v[42:45]
	v_mfma_f32_16x16x32_bf16 v[30:33], v[146:149], v[210:213], v[30:33]
	v_mfma_f32_16x16x32_bf16 v[26:29], v[154:157], v[210:213], v[26:29]
	v_mfma_f32_16x16x32_bf16 v[14:17], v[146:149], v[228:231], v[14:17]
	v_mfma_f32_16x16x32_bf16 v[10:13], v[154:157], v[228:231], v[10:13]
	v_mfma_f32_16x16x32_bf16 v[62:65], v[150:153], v[198:201], v[62:65]
	v_mfma_f32_16x16x32_bf16 v[58:61], v[158:161], v[198:201], v[58:61]
	v_mfma_f32_16x16x32_bf16 v[46:49], v[150:153], v[206:209], v[46:49]
	v_mfma_f32_16x16x32_bf16 v[42:45], v[158:161], v[206:209], v[42:45]
	v_mfma_f32_16x16x32_bf16 v[30:33], v[150:153], v[218:221], v[30:33]
	v_mfma_f32_16x16x32_bf16 v[26:29], v[158:161], v[218:221], v[26:29]
	v_mfma_f32_16x16x32_bf16 v[14:17], v[150:153], v[232:235], v[14:17]
	v_mfma_f32_16x16x32_bf16 v[10:13], v[158:161], v[232:235], v[10:13]
	s_setprio 0
	s_setprio 1
	v_mfma_f32_16x16x32_bf16 v[54:57], v[178:181], v[194:197], v[54:57]
	v_mfma_f32_16x16x32_bf16 v[50:53], v[186:189], v[194:197], v[50:53]
	v_mfma_f32_16x16x32_bf16 v[38:41], v[178:181], v[202:205], v[38:41]
	v_mfma_f32_16x16x32_bf16 v[34:37], v[186:189], v[202:205], v[34:37]
	v_mfma_f32_16x16x32_bf16 v[22:25], v[178:181], v[210:213], v[22:25]
	v_mfma_f32_16x16x32_bf16 v[18:21], v[186:189], v[210:213], v[18:21]
	v_mfma_f32_16x16x32_bf16 v[6:9], v[178:181], v[228:231], v[6:9]
	v_mfma_f32_16x16x32_bf16 v[2:5], v[186:189], v[228:231], v[2:5]
	v_mfma_f32_16x16x32_bf16 v[54:57], v[182:185], v[198:201], v[54:57]
	v_mfma_f32_16x16x32_bf16 v[50:53], v[190:193], v[198:201], v[50:53]
	v_mfma_f32_16x16x32_bf16 v[38:41], v[182:185], v[206:209], v[38:41]
	v_mfma_f32_16x16x32_bf16 v[34:37], v[190:193], v[206:209], v[34:37]
	v_mfma_f32_16x16x32_bf16 v[22:25], v[182:185], v[218:221], v[22:25]
	v_mfma_f32_16x16x32_bf16 v[18:21], v[190:193], v[218:221], v[18:21]
	v_mfma_f32_16x16x32_bf16 v[6:9], v[182:185], v[232:235], v[6:9]
	v_mfma_f32_16x16x32_bf16 v[2:5], v[190:193], v[232:235], v[2:5]
	s_setprio 0
	s_add_u32 s0, s0, 0x100
	s_addc_u32 s1, s1, 0
	s_add_u32 s44, s44, 0x100
	s_addc_u32 s45, s45, 0
	s_cmp_ge_u32 s47, s40
	s_mov_b32 s46, s47
	s_barrier
	s_cbranch_scc0 .LBB0_1373
	s_and_b64 vcc, exec, s[10:11]
	s_cbranch_vccz .LBB0_1376
	s_barrier

; #define PG8_STAGE(bufoff, gbase, voff) do { _Pragma("unroll") for (int _i = 0; _i < 2; ++_i) \
;         __builtin_amdgcn_global_load_lds((const unsigned*)((const char*)(gbase) + (voff)[_i]), (PG8_LAS unsigned*)(lds + (bufoff) + ldsw + _i * 8192), 16, 0, 0); } while (0)
; #define PG8_LDA(dst, b, h) do { _Pragma("unroll") for (int m = 0; m < 4; ++m) _Pragma("unroll") for (int k = 0; k < 2; ++k) dst[m][k] = *(const PG8_LAS bf16x8*)(lds + PG8_SA(b, h) + aoff + m * 2048 + k * 1024); } while (0)
; #define PG8_LDB(dst, b, h) do { _Pragma("unroll") for (int n = 0; n < 2; ++n) _Pragma("unroll") for (int k = 0; k < 2; ++k) dst[n][k] = *(const PG8_LAS bf16x8*)(lds + PG8_SB(b, h) + boff + n * 2048 + k * 1024); } while (0)
; #define PG8_MMA(ai, bj, At, Bt) do { __builtin_amdgcn_s_setprio(1); _Pragma("unroll") for (int m = 0; m < 4; ++m) _Pragma("unroll") for (int n = 0; n < 2; ++n) _Pragma("unroll") for (int k = 0; k < 2; ++k) \
;         acc[ai][bj][m][n] = __builtin_amdgcn_mfma_f32_16x16x32_bf16(Bt[n][k], At[m][k], acc[ai][bj][m][n], 0, 0, 0); __builtin_amdgcn_s_setprio(0); } while (0)
; #define PG8_WAIT_V(n) asm volatile("s_waitcnt vmcnt(" #n ")" ::: "memory")
; #define PG8_BAR __builtin_amdgcn_s_barrier()
; template <class Epi, class Sched, bool ALIGN_EPI = false, bool SP2 = false>
; __device__ __forceinline__ void gemm_phase(PG8_LAS unsigned char* lds, const Gemm g, const Sched& S, const Epi& E) {
;     ...
;         for (int t = 0; t < nt; t += 2) {
;             const bool last = (t == nt - 2);
;             const char* a1 = cA + (size_t)(t + 1) * kstep;
;             const char* a2 = last ? nA : cA + (size_t)(t + 2) * kstep; const char* b2 = last ? nB : cB + (size_t)(t + 2) * kstep;
;             const char* a3 = a2 + kstep; const char* b3 = b2 + kstep;
;             if (last && has_next) S.a_ready(nxt);
;             if constexpr (SP2) {
;             PG8_LDB(B0, 0, 0); PG8_LDB(B1, 0, 1); PG8_SCHED; PG8_LDA(At, 0, 0); PG8_STAGE(PG8_SA(1, 1), a1 + hstep, voffA);
;             PG8_WAIT_V(8); PG8_WAIT_L(0); PG8_BAR; PG8_MMA(0, 0, At, B0); PG8_MMA(0, 1, At, B1); PG8_BAR; PG8_SCHED;
;             PG8_LDA(At, 0, 1); PG8_STAGE(PG8_SB(0, 0), b2, voffB); PG8_STAGE(PG8_SB(0, 1), b2 + hstep, voffB); PG8_STAGE(PG8_SA(0, 0), a2, voffA);
;             PG8_WAIT_V(8); PG8_WAIT_L(0); PG8_BAR; PG8_MMA(1, 0, At, B0); PG8_MMA(1, 1, At, B1); PG8_BAR; PG8_SCHED;
.LBB0_1532:
	ds_read_b128 v[136:139], v143
	ds_read_b128 v[146:149], v143 offset:1024
	ds_read_b128 v[150:153], v143 offset:2048
	ds_read_b128 v[154:157], v143 offset:3072
	ds_read_b128 v[158:161], v144
	ds_read_b128 v[166:169], v144 offset:1024
	ds_read_b128 v[170:173], v144 offset:2048
	ds_read_b128 v[178:181], v144 offset:3072
	s_add_i32 s67, s34, 2
	s_add_u32 s35, s30, 0xffea0080
	s_addc_u32 s36, s31, -1
	s_cmp_eq_u32 s64, s34
	s_cselect_b32 s34, s28, s65
	s_cselect_b32 s37, s27, s36
	s_cselect_b32 s36, s26, s35
	s_cselect_b32 s35, s29, s66
	v_lshl_add_u64 v[216:217], s[30:31], 0, v[130:131]
	s_add_i32 m0, s3, 0xc000
	ds_read_b128 v[182:185], v145
	ds_read_b128 v[186:189], v145 offset:1024
	ds_read_b128 v[190:193], v145 offset:2048
	ds_read_b128 v[194:197], v145 offset:3072
	ds_read_b128 v[198:201], v145 offset:4096
	ds_read_b128 v[202:205], v145 offset:5120
	ds_read_b128 v[206:209], v145 offset:6144
	ds_read_b128 v[210:213], v145 offset:7168
	global_load_lds_dwordx4 v[216:217], off
	v_lshl_add_u64 v[216:217], s[30:31], 0, v[132:133]
	s_add_i32 m0, s3, 0xe000
	s_nop 0
	global_load_lds_dwordx4 v[216:217], off
	s_waitcnt vmcnt(8)
	s_waitcnt lgkmcnt(0)
	s_barrier
	s_setprio 1
	s_waitcnt lgkmcnt(0)
	v_mfma_f32_16x16x32_bf16 v[126:129], v[136:139], v[182:185], v[126:129]
	v_mfma_f32_16x16x32_bf16 v[122:125], v[150:153], v[182:185], v[122:125]
	v_mfma_f32_16x16x32_bf16 v[118:121], v[136:139], v[190:193], v[118:121]
	v_mfma_f32_16x16x32_bf16 v[114:117], v[150:153], v[190:193], v[114:117]
	v_mfma_f32_16x16x32_bf16 v[102:105], v[136:139], v[198:201], v[102:105]
	v_mfma_f32_16x16x32_bf16 v[98:101], v[150:153], v[198:201], v[98:101]
	v_mfma_f32_16x16x32_bf16 v[90:93], v[136:139], v[206:209], v[90:93]
	v_mfma_f32_16x16x32_bf16 v[82:85], v[150:153], v[206:209], v[82:85]
	v_mfma_f32_16x16x32_bf16 v[126:129], v[146:149], v[186:189], v[126:129]
	v_mfma_f32_16x16x32_bf16 v[122:125], v[154:157], v[186:189], v[122:125]
	v_mfma_f32_16x16x32_bf16 v[118:121], v[146:149], v[194:197], v[118:121]
	v_mfma_f32_16x16x32_bf16 v[114:117], v[154:157], v[194:197], v[114:117]
	v_mfma_f32_16x16x32_bf16 v[102:105], v[146:149], v[202:205], v[102:105]
	v_mfma_f32_16x16x32_bf16 v[98:101], v[154:157], v[202:205], v[98:101]
	v_mfma_f32_16x16x32_bf16 v[90:93], v[146:149], v[210:213], v[90:93]
	v_mfma_f32_16x16x32_bf16 v[82:85], v[154:157], v[210:213], v[82:85]
	s_setprio 0
	s_setprio 1
	v_mfma_f32_16x16x32_bf16 v[110:113], v[158:161], v[182:185], v[110:113]
	v_mfma_f32_16x16x32_bf16 v[106:109], v[170:173], v[182:185], v[106:109]
	v_mfma_f32_16x16x32_bf16 v[94:97], v[158:161], v[190:193], v[94:97]
	v_mfma_f32_16x16x32_bf16 v[86:89], v[170:173], v[190:193], v[86:89]
	v_mfma_f32_16x16x32_bf16 v[78:81], v[158:161], v[198:201], v[78:81]
	v_mfma_f32_16x16x32_bf16 v[74:77], v[170:173], v[198:201], v[74:77]
	v_mfma_f32_16x16x32_bf16 v[70:73], v[158:161], v[206:209], v[70:73]
	v_mfma_f32_16x16x32_bf16 v[66:69], v[170:173], v[206:209], v[66:69]
	v_mfma_f32_16x16x32_bf16 v[110:113], v[166:169], v[186:189], v[110:113]
	v_mfma_f32_16x16x32_bf16 v[106:109], v[178:181], v[186:189], v[106:109]
	v_mfma_f32_16x16x32_bf16 v[94:97], v[166:169], v[194:197], v[94:97]
	v_mfma_f32_16x16x32_bf16 v[86:89], v[178:181], v[194:197], v[86:89]
	v_mfma_f32_16x16x32_bf16 v[78:81], v[166:169], v[202:205], v[78:81]
	v_mfma_f32_16x16x32_bf16 v[74:77], v[178:181], v[202:205], v[74:77]
	v_mfma_f32_16x16x32_bf16 v[70:73], v[166:169], v[210:213], v[70:73]
	v_mfma_f32_16x16x32_bf16 v[66:69], v[178:181], v[210:213], v[66:69]
	s_setprio 0
	s_barrier
	s_add_i32 s68, s48, s2
	v_lshl_add_u64 v[216:217], s[34:35], 0, v[174:175]
	s_mov_b32 m0, s68
	ds_read_b128 v[182:185], v145 offset:16384
	ds_read_b128 v[186:189], v145 offset:17408
	ds_read_b128 v[190:193], v145 offset:18432
	ds_read_b128 v[194:197], v145 offset:19456
	ds_read_b128 v[198:201], v145 offset:20480
	ds_read_b128 v[202:205], v145 offset:21504
	ds_read_b128 v[206:209], v145 offset:22528
	ds_read_b128 v[210:213], v145 offset:23552
	global_load_lds_dwordx4 v[216:217], off
	s_add_i32 m0, s68, 0x2000
	s_add_u32 s68, s34, 0x160000
	v_lshl_add_u64 v[218:219], s[34:35], 0, v[176:177]
	s_addc_u32 s69, s35, 0
	s_add_i32 s70, s49, s2
	global_load_lds_dwordx4 v[218:219], off
	v_lshl_add_u64 v[220:221], s[68:69], 0, v[174:175]
	s_mov_b32 m0, s70
	v_lshl_add_u64 v[222:223], s[36:37], 0, v[176:177]
	global_load_lds_dwordx4 v[220:221], off
	v_lshl_add_u64 v[220:221], s[68:69], 0, v[176:177]
	s_add_i32 m0, s70, 0x2000
	s_nop 0
	global_load_lds_dwordx4 v[220:221], off
	v_lshl_add_u64 v[220:221], s[36:37], 0, v[174:175]
	s_mov_b32 m0, s3
	s_nop 0
	global_load_lds_dwordx4 v[220:221], off
	s_mov_b32 m0, s33
	s_nop 0
	global_load_lds_dwordx4 v[222:223], off
	s_waitcnt vmcnt(8)
	s_waitcnt lgkmcnt(0)
	s_barrier
; #define PG8_STAGE(bufoff, gbase, voff) do { _Pragma("unroll") for (int _i = 0; _i < 2; ++_i) \
;         __builtin_amdgcn_global_load_lds((const unsigned*)((const char*)(gbase) + (voff)[_i]), (PG8_LAS unsigned*)(lds + (bufoff) + ldsw + _i * 8192), 16, 0, 0); } while (0)
; #define PG8_LDA(dst, b, h) do { _Pragma("unroll") for (int m = 0; m < 4; ++m) _Pragma("unroll") for (int k = 0; k < 2; ++k) dst[m][k] = *(const PG8_LAS bf16x8*)(lds + PG8_SA(b, h) + aoff + m * 2048 + k * 1024); } while (0)
; #define PG8_LDB(dst, b, h) do { _Pragma("unroll") for (int n = 0; n < 2; ++n) _Pragma("unroll") for (int k = 0; k < 2; ++k) dst[n][k] = *(const PG8_LAS bf16x8*)(lds + PG8_SB(b, h) + boff + n * 2048 + k * 1024); } while (0)
; #define PG8_MMA(ai, bj, At, Bt) do { __builtin_amdgcn_s_setprio(1); _Pragma("unroll") for (int m = 0; m < 4; ++m) _Pragma("unroll") for (int n = 0; n < 2; ++n) _Pragma("unroll") for (int k = 0; k < 2; ++k) \
;         acc[ai][bj][m][n] = __builtin_amdgcn_mfma_f32_16x16x32_bf16(Bt[n][k], At[m][k], acc[ai][bj][m][n], 0, 0, 0); __builtin_amdgcn_s_setprio(0); } while (0)
; #define PG8_WAIT_V(n) asm volatile("s_waitcnt vmcnt(" #n ")" ::: "memory")
; #define PG8_WAIT_L(n) asm volatile("s_waitcnt lgkmcnt(" #n ")" ::: "memory")
; #define PG8_BAR __builtin_amdgcn_s_barrier()
; #define PG8_SCHED __builtin_amdgcn_sched_barrier(0)
; template <class Epi, class Sched, bool ALIGN_EPI = false, bool SP2 = false>
; __device__ __forceinline__ void gemm_phase(PG8_LAS unsigned char* lds, const Gemm g, const Sched& S, const Epi& E) {
;     ...
;             PG8_WAIT_V(8); PG8_WAIT_L(0); PG8_BAR; PG8_MMA(1, 0, At, B0); PG8_MMA(1, 1, At, B1); PG8_BAR; PG8_SCHED;
;             PG8_LDB(B0, 1, 0); PG8_LDB(B1, 1, 1); PG8_SCHED; PG8_LDA(At, 1, 0); PG8_STAGE(PG8_SA(0, 1), a2 + hstep, voffA);
;             PG8_WAIT_V(8); PG8_WAIT_L(0); PG8_BAR; PG8_MMA(0, 0, At, B0); PG8_MMA(0, 1, At, B1); PG8_BAR; PG8_SCHED;
;             PG8_LDA(At, 1, 1); PG8_STAGE(PG8_SB(1, 0), b3, voffB); PG8_STAGE(PG8_SB(1, 1), b3 + hstep, voffB); PG8_STAGE(PG8_SA(1, 0), a3, voffA);
	s_setprio 1
	s_waitcnt lgkmcnt(0)
	v_mfma_f32_16x16x32_bf16 v[62:65], v[136:139], v[182:185], v[62:65]
	v_mfma_f32_16x16x32_bf16 v[58:61], v[150:153], v[182:185], v[58:61]
	v_mfma_f32_16x16x32_bf16 v[54:57], v[136:139], v[190:193], v[54:57]
	v_mfma_f32_16x16x32_bf16 v[50:53], v[150:153], v[190:193], v[50:53]
	v_mfma_f32_16x16x32_bf16 v[42:45], v[136:139], v[198:201], v[42:45]
	v_mfma_f32_16x16x32_bf16 v[34:37], v[150:153], v[198:201], v[34:37]
	v_mfma_f32_16x16x32_bf16 v[26:29], v[136:139], v[206:209], v[26:29]
	v_mfma_f32_16x16x32_bf16 v[18:21], v[150:153], v[206:209], v[18:21]
	v_mfma_f32_16x16x32_bf16 v[62:65], v[146:149], v[186:189], v[62:65]
	v_mfma_f32_16x16x32_bf16 v[58:61], v[154:157], v[186:189], v[58:61]
	v_mfma_f32_16x16x32_bf16 v[54:57], v[146:149], v[194:197], v[54:57]
	v_mfma_f32_16x16x32_bf16 v[50:53], v[154:157], v[194:197], v[50:53]
	v_mfma_f32_16x16x32_bf16 v[42:45], v[146:149], v[202:205], v[42:45]
	v_mfma_f32_16x16x32_bf16 v[34:37], v[154:157], v[202:205], v[34:37]
	v_mfma_f32_16x16x32_bf16 v[26:29], v[146:149], v[210:213], v[26:29]
	v_mfma_f32_16x16x32_bf16 v[18:21], v[154:157], v[210:213], v[18:21]
	s_setprio 0
	s_setprio 1
	v_mfma_f32_16x16x32_bf16 v[46:49], v[158:161], v[182:185], v[46:49]
	v_mfma_f32_16x16x32_bf16 v[38:41], v[170:173], v[182:185], v[38:41]
	v_mfma_f32_16x16x32_bf16 v[30:33], v[158:161], v[190:193], v[30:33]
	v_mfma_f32_16x16x32_bf16 v[22:25], v[170:173], v[190:193], v[22:25]
	v_mfma_f32_16x16x32_bf16 v[14:17], v[158:161], v[198:201], v[14:17]
	v_mfma_f32_16x16x32_bf16 v[10:13], v[170:173], v[198:201], v[10:13]
	v_mfma_f32_16x16x32_bf16 v[6:9], v[158:161], v[206:209], v[6:9]
	v_mfma_f32_16x16x32_bf16 v[2:5], v[170:173], v[206:209], v[2:5]
	v_mfma_f32_16x16x32_bf16 v[46:49], v[166:169], v[186:189], v[46:49]
	v_mfma_f32_16x16x32_bf16 v[38:41], v[178:181], v[186:189], v[38:41]
	v_mfma_f32_16x16x32_bf16 v[30:33], v[166:169], v[194:197], v[30:33]
	v_mfma_f32_16x16x32_bf16 v[22:25], v[178:181], v[194:197], v[22:25]
	v_mfma_f32_16x16x32_bf16 v[14:17], v[166:169], v[202:205], v[14:17]
	v_mfma_f32_16x16x32_bf16 v[10:13], v[178:181], v[202:205], v[10:13]
	v_mfma_f32_16x16x32_bf16 v[6:9], v[166:169], v[210:213], v[6:9]
	v_mfma_f32_16x16x32_bf16 v[2:5], v[178:181], v[210:213], v[2:5]
	s_setprio 0
	s_barrier
	s_add_i32 s68, 0, 0x18000
	s_add_i32 s69, 0, 0x1c000
	v_add_u32_e32 v154, s68, v141
	v_add_u32_e32 v178, s69, v141
	ds_read_b128 v[136:139], v154
	ds_read_b128 v[146:149], v154 offset:1024
	ds_read_b128 v[150:153], v154 offset:2048
	ds_read_b128 v[154:157], v154 offset:3072
	ds_read_b128 v[158:161], v178
	ds_read_b128 v[166:169], v178 offset:1024
	ds_read_b128 v[170:173], v178 offset:2048
	ds_read_b128 v[178:181], v178 offset:3072
	s_add_u32 s36, s36, 0x160000
	s_addc_u32 s37, s37, 0
	s_mov_b32 m0, s38
	v_lshl_add_u64 v[224:225], s[36:37], 0, v[174:175]
	ds_read_b128 v[182:185], v145 offset:32768
	ds_read_b128 v[186:189], v145 offset:33792
	ds_read_b128 v[190:193], v145 offset:34816
	ds_read_b128 v[194:197], v145 offset:35840
	ds_read_b128 v[198:201], v145 offset:36864
	ds_read_b128 v[202:205], v145 offset:37888
	ds_read_b128 v[206:209], v145 offset:38912
	ds_read_b128 v[210:213], v145 offset:39936
	global_load_lds_dwordx4 v[224:225], off
	v_lshl_add_u64 v[224:225], s[36:37], 0, v[176:177]
	s_mov_b32 m0, s39
	s_nop 0
	global_load_lds_dwordx4 v[224:225], off
	s_waitcnt vmcnt(8)
	s_waitcnt lgkmcnt(0)
	s_barrier
	s_setprio 1
	s_waitcnt lgkmcnt(0)
	v_mfma_f32_16x16x32_bf16 v[126:129], v[136:139], v[182:185], v[126:129]
	v_mfma_f32_16x16x32_bf16 v[122:125], v[150:153], v[182:185], v[122:125]
	v_mfma_f32_16x16x32_bf16 v[118:121], v[136:139], v[190:193], v[118:121]
	v_mfma_f32_16x16x32_bf16 v[114:117], v[150:153], v[190:193], v[114:117]
	v_mfma_f32_16x16x32_bf16 v[102:105], v[136:139], v[198:201], v[102:105]
	v_mfma_f32_16x16x32_bf16 v[98:101], v[150:153], v[198:201], v[98:101]
	v_mfma_f32_16x16x32_bf16 v[90:93], v[136:139], v[206:209], v[90:93]
	v_mfma_f32_16x16x32_bf16 v[82:85], v[150:153], v[206:209], v[82:85]
	v_mfma_f32_16x16x32_bf16 v[126:129], v[146:149], v[186:189], v[126:129]
	v_mfma_f32_16x16x32_bf16 v[122:125], v[154:157], v[186:189], v[122:125]
	v_mfma_f32_16x16x32_bf16 v[118:121], v[146:149], v[194:197], v[118:121]
	v_mfma_f32_16x16x32_bf16 v[114:117], v[154:157], v[194:197], v[114:117]
	v_mfma_f32_16x16x32_bf16 v[102:105], v[146:149], v[202:205], v[102:105]
	v_mfma_f32_16x16x32_bf16 v[98:101], v[154:157], v[202:205], v[98:101]
	v_mfma_f32_16x16x32_bf16 v[90:93], v[146:149], v[210:213], v[90:93]
	v_mfma_f32_16x16x32_bf16 v[82:85], v[154:157], v[210:213], v[82:85]
	s_setprio 0
	s_setprio 1
	v_mfma_f32_16x16x32_bf16 v[110:113], v[158:161], v[182:185], v[110:113]
	v_mfma_f32_16x16x32_bf16 v[106:109], v[170:173], v[182:185], v[106:109]
	v_mfma_f32_16x16x32_bf16 v[94:97], v[158:161], v[190:193], v[94:97]
	v_mfma_f32_16x16x32_bf16 v[86:89], v[170:173], v[190:193], v[86:89]
	v_mfma_f32_16x16x32_bf16 v[78:81], v[158:161], v[198:201], v[78:81]
	v_mfma_f32_16x16x32_bf16 v[74:77], v[170:173], v[198:201], v[74:77]
	v_mfma_f32_16x16x32_bf16 v[70:73], v[158:161], v[206:209], v[70:73]
	v_mfma_f32_16x16x32_bf16 v[66:69], v[170:173], v[206:209], v[66:69]
	v_mfma_f32_16x16x32_bf16 v[110:113], v[166:169], v[186:189], v[110:113]
	v_mfma_f32_16x16x32_bf16 v[106:109], v[178:181], v[186:189], v[106:109]
	v_mfma_f32_16x16x32_bf16 v[94:97], v[166:169], v[194:197], v[94:97]
	v_mfma_f32_16x16x32_bf16 v[86:89], v[178:181], v[194:197], v[86:89]
	v_mfma_f32_16x16x32_bf16 v[78:81], v[166:169], v[202:205], v[78:81]
	v_mfma_f32_16x16x32_bf16 v[74:77], v[178:181], v[202:205], v[74:77]
	v_mfma_f32_16x16x32_bf16 v[70:73], v[166:169], v[210:213], v[70:73]
	v_mfma_f32_16x16x32_bf16 v[66:69], v[178:181], v[210:213], v[66:69]
	s_setprio 0
	s_barrier
; #define PG8_STAGE(bufoff, gbase, voff) do { _Pragma("unroll") for (int _i = 0; _i < 2; ++_i) \
;         __builtin_amdgcn_global_load_lds((const unsigned*)((const char*)(gbase) + (voff)[_i]), (PG8_LAS unsigned*)(lds + (bufoff) + ldsw + _i * 8192), 16, 0, 0); } while (0)
; #define PG8_LDA(dst, b, h) do { _Pragma("unroll") for (int m = 0; m < 4; ++m) _Pragma("unroll") for (int k = 0; k < 2; ++k) dst[m][k] = *(const PG8_LAS bf16x8*)(lds + PG8_SA(b, h) + aoff + m * 2048 + k * 1024); } while (0)
; #define PG8_MMA(ai, bj, At, Bt) do { __builtin_amdgcn_s_setprio(1); _Pragma("unroll") for (int m = 0; m < 4; ++m) _Pragma("unroll") for (int n = 0; n < 2; ++n) _Pragma("unroll") for (int k = 0; k < 2; ++k) \
;         acc[ai][bj][m][n] = __builtin_amdgcn_mfma_f32_16x16x32_bf16(Bt[n][k], At[m][k], acc[ai][bj][m][n], 0, 0, 0); __builtin_amdgcn_s_setprio(0); } while (0)
; #define PG8_WAIT_V(n) asm volatile("s_waitcnt vmcnt(" #n ")" ::: "memory")
; #define PG8_WAIT_L(n) asm volatile("s_waitcnt lgkmcnt(" #n ")" ::: "memory")
; #define PG8_BAR __builtin_amdgcn_s_barrier()
; #define PG8_SCHED __builtin_amdgcn_sched_barrier(0)
; template <class Epi, class Sched, bool ALIGN_EPI = false, bool SP2 = false>
; __device__ __forceinline__ void gemm_phase(PG8_LAS unsigned char* lds, const Gemm g, const Sched& S, const Epi& E) {
;     ...
;         for (int t = 0; t < nt; t += 2) {
;             const bool last = (t == nt - 2);
;             const char* a1 = cA + (size_t)(t + 1) * kstep;
;             const char* a2 = last ? nA : cA + (size_t)(t + 2) * kstep; const char* b2 = last ? nB : cB + (size_t)(t + 2) * kstep;
;     ...
;             PG8_LDA(At, 1, 1); PG8_STAGE(PG8_SB(1, 0), b3, voffB); PG8_STAGE(PG8_SB(1, 1), b3 + hstep, voffB); PG8_STAGE(PG8_SA(1, 0), a3, voffA);
;             PG8_WAIT_V(8); PG8_WAIT_L(0); PG8_BAR; PG8_MMA(1, 0, At, B0); PG8_MMA(1, 1, At, B1); PG8_BAR; PG8_SCHED;
	s_add_i32 s36, s68, s2
	v_lshl_add_u64 v[216:217], v[216:217], 0, s[8:9]
	s_mov_b32 m0, s36
	ds_read_b128 v[182:185], v145 offset:49152
	ds_read_b128 v[186:189], v145 offset:50176
	ds_read_b128 v[190:193], v145 offset:51200
	ds_read_b128 v[194:197], v145 offset:52224
	ds_read_b128 v[198:201], v145 offset:53248
	ds_read_b128 v[202:205], v145 offset:54272
	ds_read_b128 v[206:209], v145 offset:55296
	ds_read_b128 v[210:213], v145 offset:56320
	global_load_lds_dwordx4 v[216:217], off
	s_add_i32 m0, s36, 0x2000
	s_add_u32 s34, s34, 0x160080
	v_lshl_add_u64 v[216:217], v[218:219], 0, s[8:9]
	s_addc_u32 s35, s35, 0
	s_add_i32 s36, s69, s2
	global_load_lds_dwordx4 v[216:217], off
	v_lshl_add_u64 v[216:217], s[34:35], 0, v[174:175]
	s_mov_b32 m0, s36
	s_nop 0
	global_load_lds_dwordx4 v[216:217], off
	v_lshl_add_u64 v[216:217], s[34:35], 0, v[176:177]
	s_add_i32 m0, s36, 0x2000
	s_nop 0
	global_load_lds_dwordx4 v[216:217], off
	v_lshl_add_u64 v[216:217], v[220:221], 0, s[8:9]
	s_mov_b32 m0, s40
	s_nop 0
	global_load_lds_dwordx4 v[216:217], off
	v_lshl_add_u64 v[216:217], v[222:223], 0, s[8:9]
	s_mov_b32 m0, s41
	s_nop 0
	global_load_lds_dwordx4 v[216:217], off
	s_waitcnt vmcnt(8)
	s_waitcnt lgkmcnt(0)
	s_barrier
	s_setprio 1
	s_waitcnt lgkmcnt(0)
	v_mfma_f32_16x16x32_bf16 v[62:65], v[136:139], v[182:185], v[62:65]
	v_mfma_f32_16x16x32_bf16 v[58:61], v[150:153], v[182:185], v[58:61]
	v_mfma_f32_16x16x32_bf16 v[54:57], v[136:139], v[190:193], v[54:57]
	v_mfma_f32_16x16x32_bf16 v[50:53], v[150:153], v[190:193], v[50:53]
	v_mfma_f32_16x16x32_bf16 v[42:45], v[136:139], v[198:201], v[42:45]
	v_mfma_f32_16x16x32_bf16 v[34:37], v[150:153], v[198:201], v[34:37]
	v_mfma_f32_16x16x32_bf16 v[26:29], v[136:139], v[206:209], v[26:29]
	v_mfma_f32_16x16x32_bf16 v[18:21], v[150:153], v[206:209], v[18:21]
	v_mfma_f32_16x16x32_bf16 v[62:65], v[146:149], v[186:189], v[62:65]
	v_mfma_f32_16x16x32_bf16 v[58:61], v[154:157], v[186:189], v[58:61]
	v_mfma_f32_16x16x32_bf16 v[54:57], v[146:149], v[194:197], v[54:57]
	v_mfma_f32_16x16x32_bf16 v[50:53], v[154:157], v[194:197], v[50:53]
	v_mfma_f32_16x16x32_bf16 v[42:45], v[146:149], v[202:205], v[42:45]
	v_mfma_f32_16x16x32_bf16 v[34:37], v[154:157], v[202:205], v[34:37]
	v_mfma_f32_16x16x32_bf16 v[26:29], v[146:149], v[210:213], v[26:29]
	v_mfma_f32_16x16x32_bf16 v[18:21], v[154:157], v[210:213], v[18:21]
	s_setprio 0
	s_setprio 1
	v_mfma_f32_16x16x32_bf16 v[46:49], v[158:161], v[182:185], v[46:49]
	v_mfma_f32_16x16x32_bf16 v[38:41], v[170:173], v[182:185], v[38:41]
	v_mfma_f32_16x16x32_bf16 v[30:33], v[158:161], v[190:193], v[30:33]
	v_mfma_f32_16x16x32_bf16 v[22:25], v[170:173], v[190:193], v[22:25]
	v_mfma_f32_16x16x32_bf16 v[14:17], v[158:161], v[198:201], v[14:17]
	v_mfma_f32_16x16x32_bf16 v[10:13], v[170:173], v[198:201], v[10:13]
	v_mfma_f32_16x16x32_bf16 v[6:9], v[158:161], v[206:209], v[6:9]
	v_mfma_f32_16x16x32_bf16 v[2:5], v[170:173], v[206:209], v[2:5]
	v_mfma_f32_16x16x32_bf16 v[46:49], v[166:169], v[186:189], v[46:49]
	v_mfma_f32_16x16x32_bf16 v[38:41], v[178:181], v[186:189], v[38:41]
	v_mfma_f32_16x16x32_bf16 v[30:33], v[166:169], v[194:197], v[30:33]
	v_mfma_f32_16x16x32_bf16 v[22:25], v[178:181], v[194:197], v[22:25]
	v_mfma_f32_16x16x32_bf16 v[14:17], v[166:169], v[202:205], v[14:17]
	v_mfma_f32_16x16x32_bf16 v[10:13], v[178:181], v[202:205], v[10:13]
	v_mfma_f32_16x16x32_bf16 v[6:9], v[166:169], v[210:213], v[6:9]
	v_mfma_f32_16x16x32_bf16 v[2:5], v[178:181], v[210:213], v[2:5]
	s_setprio 0
	s_add_u32 s30, s30, 0x100
	s_addc_u32 s31, s31, 0
	s_add_u32 s65, s65, 0x100
	s_addc_u32 s66, s66, 0
	s_cmp_ge_u32 s67, s59
	s_mov_b32 s34, s67
	s_barrier
	s_cbranch_scc0 .LBB0_1532
	s_and_b64 vcc, exec, s[10:11]
	s_cbranch_vccz .LBB0_1535
	s_barrier
